# v9 + unit-boundary barriers removed: leading half skips first barrier of each unit, trailing half skips last; no ALIGN/restore/prologue-extra barriers (epilogues overlap other half's MFMA)
# baseline (speedup 1.0000x reference)
; #define PG8_WAIT_V(n) asm volatile("s_waitcnt vmcnt(" #n ")" ::: "memory")
; #define PG8_BAR __builtin_amdgcn_s_barrier()
; template <class Epi, class Sched, bool ALIGN_EPI = false, bool SP2 = false>
; __device__ __forceinline__ void gemm_phase(PG8_LAS unsigned char* lds, const Gemm g, const Sched& S, const Epi& E) {
;     int tid_ = threadIdx.x; asm volatile("" : "+v"(tid_));
;     const int tid = tid_, wid = __builtin_amdgcn_readfirstlane(tid >> 6), lane = tid & 63, wr = wid >> 2, wc = wid & 3, fr = lane & 15, fq = lane >> 4;
;     const int K = g.K, nt = K / BK;
;     unsigned voffA[2], voffB[2];
; #pragma unroll
;     for (int i = 0; i < 2; ++i) { int R, C; stage_rc(tid * 16 + i * 8192, R, C); const int Rb = Epi::PERM ? ((R & ~31) + perm32(R & 31)) : R;
;         voffA[i] = (unsigned)(R * K + C) * 2u; voffB[i] = (unsigned)(Rb * K + C) * 2u; }
;     const size_t kstep = (size_t)(BK * 2);
;     const size_t hstep = (size_t)HALF * K * 2;
;     const size_t tstep = 2 * hstep;
;     const unsigned ldsw = (unsigned)wid * 1024u;
;     const int aoff = lds_byte(wr * 64 + fr, fq * 8), boff = lds_byte(wc * 32 + fr, fq * 8);
;     ...
;     Unit cur, nxt; int ui = 0;
;     if (!S.next(0, cur)) return;
;     f32x4 acc[2][2][4][2];
; #pragma unroll
;     for (int a = 0; a < 2; ++a)
; #pragma unroll
;         for (int b = 0; b < 2; ++b)
; #pragma unroll
;             for (int m = 0; m < 4; ++m)
; #pragma unroll
;                 for (int n = 0; n < 2; ++n) acc[a][b][m][n] = (f32x4){0.f, 0.f, 0.f, 0.f};
;     bf16x8 At[4][2], B0[2][2], B1[2][2];
;     const char* cA = (const char*)g.A + (size_t)cur.pm * tstep; const char* cB = (const char*)g.Bt + (size_t)cur.pn * tstep;
;     S.a_ready(cur);
;     if constexpr (SP2) {
;         PG8_STAGE(PG8_SB(0, 0), cB, voffB); PG8_STAGE(PG8_SB(0, 1), cB + hstep, voffB); PG8_STAGE(PG8_SA(0, 0), cA, voffA); PG8_STAGE(PG8_SA(0, 1), cA + hstep, voffA);
;         if (wr == 1) PG8_BAR;
;         PG8_WAIT_V(2); PG8_BAR;
;         PG8_STAGE(PG8_SB(1, 0), cB + kstep, voffB); PG8_STAGE(PG8_SA(1, 0), cA + kstep, voffA); PG8_STAGE(PG8_SB(1, 1), cB + hstep + kstep, voffB);
;         PG8_WAIT_V(6); PG8_BAR;
;     } else {
;         PG8_STAGE(PG8_SB(0, 0), cB, voffB); PG8_STAGE(PG8_SA(0, 0), cA, voffA); PG8_STAGE(PG8_SB(0, 1), cB + hstep, voffB); PG8_STAGE(PG8_SA(0, 1), cA + hstep, voffA);
;         if (wr == 1) PG8_BAR;
;         PG8_WAIT_V(4); PG8_BAR;
.LBB0_354:
	s_or_b64 exec, exec, s[34:35]
	s_xor_b64 s[34:35], s[44:45], -1
	s_cmp_eq_u32 s55, 5
	v_writelane_b32 v255, s55, 4
	s_cselect_b32 s85, s91, s43
	s_cselect_b32 s84, s90, s42
	s_cmp_eq_u32 s54, 1
	s_mov_b64 s[0:1], -1
	s_waitcnt lgkmcnt(0)
	s_barrier
	s_cbranch_scc1 .LBB0_548
	s_cmp_lg_u32 s54, 0
	s_cselect_b64 s[0:1], -1, 0
	v_cndmask_b32_e64 v0, 0, 1, s[0:1]
	s_and_b64 s[0:1], s[48:49], exec
	s_cselect_b32 s86, 2, 0
	v_readfirstlane_b32 s0, v0
	s_mov_b32 s1, s87
	s_or_b64 s[48:49], s[86:87], s[0:1]
	v_readlane_b32 s0, v253, 23
	v_mov_b32_e32 v2, v182
	v_readlane_b32 s1, v253, 24
	s_andn2_b64 vcc, exec, s[0:1]
	v_readfirstlane_b32 s4, v2
	s_cbranch_vccnz .LBB0_375
	v_lshlrev_b32_e32 v0, 4, v2
	v_add_u32_e32 v4, 0x2000, v0
	v_ashrrev_i32_e32 v3, 31, v4
	v_lshrrev_b32_e32 v3, 22, v3
	v_add_u32_e32 v3, v4, v3
	v_ashrrev_i32_e32 v3, 10, v3
	v_mul_i32_i24_e32 v5, 0x400, v3
	v_sub_u32_e32 v4, v4, v5
	v_lshrrev_b32_e32 v5, 4, v4
	v_bitop3_b32 v5, v5, v4, 32 bitop3:0x6c
	v_ashrrev_i32_e32 v4, 31, v5
	v_lshrrev_b32_e32 v4, 26, v4
	v_add_u32_e32 v6, v5, v4
	v_lshlrev_b32_e32 v7, 3, v3
	s_lshl_b32 s0, s48, 24
	v_readlane_b32 s1, v253, 21
	v_ashrrev_i32_e32 v4, 6, v6
	v_and_b32_e32 v7, -16, v7
	s_add_u32 s22, s1, s0
	v_readlane_b32 s0, v253, 22
	v_add_u32_e32 v7, v4, v7
	s_addc_u32 s23, s0, 0
	v_and_b32_e32 v8, 3, v4
	s_mov_b32 s0, 0x1fffe0
	v_lshrrev_b32_e32 v9, 2, v7
	v_lshlrev_b32_e32 v10, 1, v7
	v_and_b32_e32 v6, 0xc0, v6
	v_and_or_b32 v8, v7, s0, v8
	v_and_b32_e32 v9, 4, v9
	v_and_b32_e32 v10, 24, v10
	v_sub_u32_e32 v5, v5, v6
	v_or3_b32 v8, v8, v9, v10
	v_lshlrev_b32_e32 v9, 5, v3
	v_ashrrev_i16_sdwa v5, v184, sext(v5) dst_sel:DWORD dst_unused:UNUSED_PAD src0_sel:DWORD src1_sel:BYTE_0
	v_and_b32_e32 v9, 32, v9
	v_bfe_i32 v5, v5, 0, 16
	v_add_lshl_u32 v6, v9, v5, 1
	v_lshl_add_u32 v130, v8, 11, v6
	v_lshl_add_u32 v132, v7, 11, v6
	v_bfe_i32 v6, v2, 27, 1
	v_lshrrev_b32_e32 v6, 22, v6
	v_add_u32_e32 v6, v0, v6
	v_and_b32_e32 v6, 0xfffffc00, v6
	v_sub_u32_e32 v0, v0, v6
	v_lshrrev_b32_e32 v6, 4, v0
	v_ashrrev_i32_e32 v7, 31, v2
	v_bitop3_b32 v0, v6, v0, 32 bitop3:0x6c
	v_lshrrev_b32_e32 v7, 26, v7
	v_ashrrev_i32_e32 v6, 31, v0
	v_add_u32_e32 v7, v2, v7
	v_lshrrev_b32_e32 v6, 26, v6
	v_ashrrev_i32_e32 v7, 6, v7
	v_add_u32_e32 v8, v0, v6
	v_lshlrev_b32_e32 v9, 3, v7
	v_ashrrev_i32_e32 v6, 6, v8
	v_and_b32_e32 v9, -16, v9
	v_add_u32_e32 v9, v6, v9
	v_and_b32_e32 v10, 3, v6
	v_lshrrev_b32_e32 v11, 2, v9
	v_lshlrev_b32_e32 v12, 1, v9
	v_and_b32_e32 v8, 0xc0, v8
	s_ashr_i32 s6, s4, 6
	v_and_or_b32 v10, v9, s0, v10
	v_and_b32_e32 v11, 4, v11
	v_and_b32_e32 v12, 24, v12
	v_sub_u32_e32 v0, v0, v8
	s_ashr_i32 s5, s4, 8
	s_lshl_b32 s24, s6, 10
	v_or3_b32 v10, v10, v11, v12
	v_lshlrev_b32_e32 v11, 5, v7
	v_ashrrev_i16_sdwa v0, v184, sext(v0) dst_sel:DWORD dst_unused:UNUSED_PAD src0_sel:DWORD src1_sel:BYTE_0
	v_readlane_b32 s0, v253, 62
	v_and_b32_e32 v11, 32, v11
	v_bfe_i32 v8, v0, 0, 16
	v_readlane_b32 s1, v253, 63
	s_add_u32 s18, s22, s0
	v_add_lshl_u32 v11, v11, v8, 1
	s_addc_u32 s19, s23, s1
	s_add_i32 s25, s24, 0
	v_lshl_add_u32 v0, v10, 11, v11
	s_add_i32 m0, s25, 0x10000
	v_lshl_add_u32 v134, v9, 11, v11
	global_load_lds_dwordx4 v0, s[18:19]
	s_add_i32 m0, s25, 0x12000
	s_add_u32 s0, s18, 0x40000
	global_load_lds_dwordx4 v130, s[18:19]
	s_addc_u32 s1, s19, 0
	s_add_i32 m0, s25, 0x14000
	s_add_i32 s26, s25, 0x2000
	global_load_lds_dwordx4 v0, s[0:1]
	s_add_i32 m0, s25, 0x16000
	s_add_i32 s27, s25, 0x4000
	global_load_lds_dwordx4 v130, s[0:1]
	v_readlane_b32 s0, v254, 2
	s_mov_b32 m0, s25
	v_readlane_b32 s1, v254, 3
	s_add_i32 s28, s25, 0x6000
	s_cmp_eq_u32 s5, 1
	s_nop 2
	global_load_lds_dwordx4 v134, s[0:1]
	s_mov_b32 m0, s26
	s_nop 0
	global_load_lds_dwordx4 v132, s[0:1]
	v_readlane_b32 s0, v254, 4
	s_mov_b32 m0, s27
	v_readlane_b32 s1, v254, 5
	s_nop 4
	global_load_lds_dwordx4 v134, s[0:1]
	s_mov_b32 m0, s28
	s_nop 0
	global_load_lds_dwordx4 v132, s[0:1]
	s_cselect_b64 s[0:1], -1, 0
	s_cmp_lg_u32 s5, 1
	s_cbranch_scc1 .LBB0_358
.LBB0_358:
	v_lshl_add_u64 v[10:11], s[18:19], 0, v[0:1]
	v_mov_b32_e32 v131, v1
	v_readlane_b32 s16, v254, 2
	s_lshl_b32 s6, s6, 5
	v_lshl_add_u64 v[12:13], s[18:19], 0, v[130:131]
	v_mov_b32_e32 v135, v1
	v_readlane_b32 s17, v254, 3
	s_and_b32 s9, s6, 0x60
	s_add_i32 m0, s25, 0x18000
	v_lshl_add_u64 v[10:11], v[10:11], 0, s[38:39]
	v_lshl_add_u64 v[14:15], s[16:17], 0, v[134:135]
	v_mov_b32_e32 v133, v1
	s_lshl_b32 s8, s5, 13
	s_lshl_b32 s10, s9, 7
	s_waitcnt vmcnt(2)
	s_barrier
	global_load_lds_dwordx4 v[10:11], off
	v_lshl_add_u64 v[10:11], v[12:13], 0, s[38:39]
	s_add_i32 m0, s25, 0x1a000
	s_add_i32 s29, s25, 0x8000
	s_add_i32 s30, s25, 0xa000
	v_lshl_add_u64 v[16:17], s[16:17], 0, v[132:133]
	global_load_lds_dwordx4 v[10:11], off
	v_lshl_add_u64 v[10:11], v[14:15], 0, s[38:39]
	s_mov_b32 m0, s29
	s_add_u32 s6, s18, 0x40080
	global_load_lds_dwordx4 v[10:11], off
	v_lshl_add_u64 v[10:11], v[16:17], 0, s[38:39]
	s_mov_b32 m0, s30
	s_addc_u32 s7, s19, 0
	global_load_lds_dwordx4 v[10:11], off
	s_add_i32 m0, s25, 0x1c000
	v_lshl_add_u64 v[10:11], s[6:7], 0, v[0:1]
	global_load_lds_dwordx4 v[10:11], off
	v_lshl_add_u64 v[10:11], s[6:7], 0, v[130:131]
	s_add_i32 m0, s25, 0x1e000
	v_and_b32_e32 v9, 15, v2
	global_load_lds_dwordx4 v[10:11], off
	v_lshrrev_b32_e32 v10, 1, v2
	v_and_b32_e32 v10, 24, v10
	v_lshlrev_b32_e32 v11, 1, v10
	v_lshlrev_b32_e32 v2, 2, v2
	v_lshl_or_b32 v142, s5, 6, v9
	v_lshl_or_b32 v9, v9, 6, v11
	v_and_b32_e32 v2, 32, v2
	v_bitop3_b32 v11, v9, s8, v2 bitop3:0xde
	v_bitop3_b32 v143, v9, s10, v2 bitop3:0xde
	v_lshlrev_b32_e32 v2, 14, v7
	v_and_b32_e32 v2, 0xffff8000, v2
	v_lshl_add_u32 v2, v6, 11, v2
	v_and_b32_e32 v6, 1, v7
	v_lshl_or_b32 v2, v6, 6, v2
	v_lshl_add_u32 v136, v8, 1, v2
	v_lshlrev_b32_e32 v2, 14, v3
	v_and_b32_e32 v2, 0xffff8000, v2
	s_waitcnt vmcnt(6)
	v_lshl_add_u32 v2, v4, 11, v2
	v_and_b32_e32 v3, 1, v3
	s_cmpk_lt_u32 s4, 0x100
	v_lshl_or_b32 v2, v3, 6, v2
	v_readlane_b32 s4, v254, 0
	s_cselect_b64 s[6:7], -1, 0
	v_or_b32_e32 v144, s9, v10
	v_mov_b32_e32 v137, v1
	v_lshl_add_u32 v138, v5, 1, v2
	v_mov_b32_e32 v139, v1
	s_mov_b32 s31, 0
	v_add_u32_e32 v145, 0, v11
	v_readlane_b32 s33, v253, 61
	s_mov_b32 s49, s4
	s_barrier
	v_readlane_b32 s5, v254, 1
	s_waitcnt vmcnt(0)
	s_branch .LBB0_361

; #define PG8_STAGE(bufoff, gbase, voff) do { _Pragma("unroll") for (int _i = 0; _i < 2; ++_i) \
;         __builtin_amdgcn_global_load_lds((const unsigned*)((const char*)(gbase) + (voff)[_i]), (PG8_LAS unsigned*)(lds + (bufoff) + ldsw + _i * 8192), 16, 0, 0); } while (0)
; #define PG8_LDA(dst, b, h) do { _Pragma("unroll") for (int m = 0; m < 4; ++m) _Pragma("unroll") for (int k = 0; k < 2; ++k) dst[m][k] = *(const PG8_LAS bf16x8*)(lds + PG8_SA(b, h) + aoff + m * 2048 + k * 1024); } while (0)
; #define PG8_LDB(dst, b, h) do { _Pragma("unroll") for (int n = 0; n < 2; ++n) _Pragma("unroll") for (int k = 0; k < 2; ++k) dst[n][k] = *(const PG8_LAS bf16x8*)(lds + PG8_SB(b, h) + boff + n * 2048 + k * 1024); } while (0)
; #define PG8_MMA(ai, bj, At, Bt) do { __builtin_amdgcn_s_setprio(1); _Pragma("unroll") for (int m = 0; m < 4; ++m) _Pragma("unroll") for (int n = 0; n < 2; ++n) _Pragma("unroll") for (int k = 0; k < 2; ++k) \
;         acc[ai][bj][m][n] = __builtin_amdgcn_mfma_f32_16x16x32_bf16(Bt[n][k], At[m][k], acc[ai][bj][m][n], 0, 0, 0); __builtin_amdgcn_s_setprio(0); } while (0)
; #define PG8_WAIT_V(n) asm volatile("s_waitcnt vmcnt(" #n ")" ::: "memory")
; #define PG8_WAIT_L(n) asm volatile("s_waitcnt lgkmcnt(" #n ")" ::: "memory")
; #define PG8_BAR __builtin_amdgcn_s_barrier()
; template <class Epi, class Sched, bool ALIGN_EPI = false, bool SP2 = false>
; __device__ __forceinline__ void gemm_phase(PG8_LAS unsigned char* lds, const Gemm g, const Sched& S, const Epi& E) {
;     ...
;         const bool has_next = S.next(ui + 1, nxt);
;         const char* nA = has_next ? (const char*)g.A + (size_t)nxt.pm * tstep : cA; const char* nB = has_next ? (const char*)g.Bt + (size_t)nxt.pn * tstep : cB;
;         for (int t = 0; t < nt; t += 2) {
;             const bool last = (t == nt - 2);
;             const char* a1 = cA + (size_t)(t + 1) * kstep;
;             const char* a2 = last ? nA : cA + (size_t)(t + 2) * kstep; const char* b2 = last ? nB : cB + (size_t)(t + 2) * kstep;
;             const char* a3 = a2 + kstep; const char* b3 = b2 + kstep;
;             if (last && has_next) S.a_ready(nxt);
;             if constexpr (SP2) {
;             PG8_LDB(B0, 0, 0); PG8_LDB(B1, 0, 1); PG8_SCHED; PG8_LDA(At, 0, 0); PG8_STAGE(PG8_SA(1, 1), a1 + hstep, voffA);
;             PG8_WAIT_V(8); PG8_WAIT_L(0); PG8_BAR; PG8_MMA(0, 0, At, B0); PG8_MMA(0, 1, At, B1); PG8_BAR; PG8_SCHED;
.LBB0_367:
	s_ashr_i32 s11, s10, 31
	s_lshl_b64 s[12:13], s[10:11], 19
	s_add_u32 s12, s90, s12
	s_addc_u32 s13, s91, s13
	s_and_b64 s[14:15], s[4:5], exec
	s_cselect_b32 s11, s13, s17
	s_cselect_b32 s50, s12, s16
	s_ashr_i32 s9, s8, 31
	s_lshl_b64 s[14:15], s[8:9], 19
	s_add_u32 s14, s22, s14
	s_addc_u32 s15, s23, s15
	s_and_b64 s[20:21], s[4:5], exec
	s_cselect_b32 s9, s15, s19
	s_cselect_b32 s51, s14, s18
	s_add_u32 s16, s16, 0x40080
	s_addc_u32 s17, s17, 0
	s_add_u32 s52, s18, 0x100
	s_addc_u32 s53, s19, 0
	s_mov_b32 s55, -2
	s_add_u32 s18, s16, 0xfffc0080
	s_addc_u32 s19, s17, -1
	s_add_i32 s56, 0, 0x10000
	s_cmp_eq_u32 s55, 12
	s_cselect_b32 s21, s11, s19
	s_cselect_b32 s20, s50, s18
	v_add_u32_e32 v140, s56, v143
	s_cselect_b32 s19, s9, s53
	s_cselect_b32 s18, s51, s52
	s_add_i32 s58, 0, 0x14000
	ds_read_b128 v[154:157], v140
	ds_read_b128 v[158:161], v140 offset:1024
	ds_read_b128 v[162:165], v140 offset:2048
	ds_read_b128 v[166:169], v140 offset:3072
	v_add_u32_e32 v140, s58, v143
	ds_read_b128 v[170:173], v140
	ds_read_b128 v[174:177], v140 offset:1024
	ds_read_b128 v[178:181], v140 offset:2048
	ds_read_b128 v[200:203], v140 offset:3072
	v_lshl_add_u64 v[140:141], s[16:17], 0, v[136:137]
	s_add_i32 m0, s25, 0xc000
	ds_read_b128 v[204:207], v145
	ds_read_b128 v[208:211], v145 offset:1024
	ds_read_b128 v[212:215], v145 offset:2048
	ds_read_b128 v[216:219], v145 offset:3072
	ds_read_b128 v[220:223], v145 offset:4096
	ds_read_b128 v[224:227], v145 offset:5120
	ds_read_b128 v[228:231], v145 offset:6144
	ds_read_b128 v[232:235], v145 offset:7168
	global_load_lds_dwordx4 v[140:141], off
	v_lshl_add_u64 v[140:141], s[16:17], 0, v[138:139]
	s_add_i32 m0, s25, 0xe000
	s_nop 0
	global_load_lds_dwordx4 v[140:141], off
	s_waitcnt vmcnt(16)
	s_waitcnt lgkmcnt(0)
	s_and_b64 vcc, exec, s[6:7]
	s_cbranch_vccnz .Lpe_368
	s_barrier
.Lpe_368:
	s_setprio 1
	s_waitcnt lgkmcnt(0)
	v_mfma_f32_16x16x32_bf16 v[122:125], v[154:157], v[204:207], 0
	v_mfma_f32_16x16x32_bf16 v[114:117], v[162:165], v[204:207], 0
	v_mfma_f32_16x16x32_bf16 v[106:109], v[154:157], v[212:215], 0
	v_mfma_f32_16x16x32_bf16 v[98:101], v[162:165], v[212:215], 0
	v_mfma_f32_16x16x32_bf16 v[90:93], v[154:157], v[220:223], 0
	v_mfma_f32_16x16x32_bf16 v[82:85], v[162:165], v[220:223], 0
	v_mfma_f32_16x16x32_bf16 v[74:77], v[154:157], v[228:231], 0
	v_mfma_f32_16x16x32_bf16 v[66:69], v[162:165], v[228:231], 0
	v_mfma_f32_16x16x32_bf16 v[122:125], v[158:161], v[208:211], v[122:125]
	v_mfma_f32_16x16x32_bf16 v[114:117], v[166:169], v[208:211], v[114:117]
	v_mfma_f32_16x16x32_bf16 v[106:109], v[158:161], v[216:219], v[106:109]
	v_mfma_f32_16x16x32_bf16 v[98:101], v[166:169], v[216:219], v[98:101]
	v_mfma_f32_16x16x32_bf16 v[90:93], v[158:161], v[224:227], v[90:93]
	v_mfma_f32_16x16x32_bf16 v[82:85], v[166:169], v[224:227], v[82:85]
	v_mfma_f32_16x16x32_bf16 v[74:77], v[158:161], v[232:235], v[74:77]
	v_mfma_f32_16x16x32_bf16 v[66:69], v[166:169], v[232:235], v[66:69]
	s_setprio 0
	s_setprio 1
	v_mfma_f32_16x16x32_bf16 v[126:129], v[170:173], v[204:207], 0
	v_mfma_f32_16x16x32_bf16 v[118:121], v[178:181], v[204:207], 0
	v_mfma_f32_16x16x32_bf16 v[110:113], v[170:173], v[212:215], 0
	v_mfma_f32_16x16x32_bf16 v[102:105], v[178:181], v[212:215], 0
	v_mfma_f32_16x16x32_bf16 v[94:97], v[170:173], v[220:223], 0
	v_mfma_f32_16x16x32_bf16 v[86:89], v[178:181], v[220:223], 0
	v_mfma_f32_16x16x32_bf16 v[78:81], v[170:173], v[228:231], 0
	v_mfma_f32_16x16x32_bf16 v[70:73], v[178:181], v[228:231], 0
	v_mfma_f32_16x16x32_bf16 v[126:129], v[174:177], v[208:211], v[126:129]
	v_mfma_f32_16x16x32_bf16 v[118:121], v[200:203], v[208:211], v[118:121]
	v_mfma_f32_16x16x32_bf16 v[110:113], v[174:177], v[216:219], v[110:113]
	v_mfma_f32_16x16x32_bf16 v[102:105], v[200:203], v[216:219], v[102:105]
	v_mfma_f32_16x16x32_bf16 v[94:97], v[174:177], v[224:227], v[94:97]
	v_mfma_f32_16x16x32_bf16 v[86:89], v[200:203], v[224:227], v[86:89]
	v_mfma_f32_16x16x32_bf16 v[78:81], v[174:177], v[232:235], v[78:81]
	v_mfma_f32_16x16x32_bf16 v[70:73], v[200:203], v[232:235], v[70:73]
	s_setprio 0
	s_barrier
	s_add_i32 s56, s56, s24
	v_lshl_add_u64 v[140:141], s[18:19], 0, v[0:1]
	s_mov_b32 m0, s56
	ds_read_b128 v[204:207], v145 offset:16384
	ds_read_b128 v[208:211], v145 offset:17408
	ds_read_b128 v[212:215], v145 offset:18432
	ds_read_b128 v[216:219], v145 offset:19456
	ds_read_b128 v[220:223], v145 offset:20480
	ds_read_b128 v[224:227], v145 offset:21504
	ds_read_b128 v[228:231], v145 offset:22528
	ds_read_b128 v[232:235], v145 offset:23552
	global_load_lds_dwordx4 v[140:141], off
	s_add_i32 m0, s56, 0x2000
	s_add_u32 s56, s18, 0x40000
	v_lshl_add_u64 v[146:147], s[18:19], 0, v[130:131]
	s_addc_u32 s57, s19, 0
	s_add_i32 s58, s58, s24
	global_load_lds_dwordx4 v[146:147], off
	v_lshl_add_u64 v[148:149], s[56:57], 0, v[0:1]
	s_mov_b32 m0, s58
	v_lshl_add_u64 v[236:237], s[20:21], 0, v[132:133]
	global_load_lds_dwordx4 v[148:149], off
	v_lshl_add_u64 v[148:149], s[56:57], 0, v[130:131]
	s_add_i32 m0, s58, 0x2000
	s_nop 0
	global_load_lds_dwordx4 v[148:149], off
	v_lshl_add_u64 v[148:149], s[20:21], 0, v[134:135]
	s_mov_b32 m0, s25
	s_nop 0
	global_load_lds_dwordx4 v[148:149], off
	s_mov_b32 m0, s26
	s_nop 0
	global_load_lds_dwordx4 v[236:237], off
	s_waitcnt vmcnt(16)
	s_waitcnt lgkmcnt(0)
	s_barrier
; #define PG8_STAGE(bufoff, gbase, voff) do { _Pragma("unroll") for (int _i = 0; _i < 2; ++_i) \
;         __builtin_amdgcn_global_load_lds((const unsigned*)((const char*)(gbase) + (voff)[_i]), (PG8_LAS unsigned*)(lds + (bufoff) + ldsw + _i * 8192), 16, 0, 0); } while (0)
; #define PG8_LDA(dst, b, h) do { _Pragma("unroll") for (int m = 0; m < 4; ++m) _Pragma("unroll") for (int k = 0; k < 2; ++k) dst[m][k] = *(const PG8_LAS bf16x8*)(lds + PG8_SA(b, h) + aoff + m * 2048 + k * 1024); } while (0)
; #define PG8_LDB(dst, b, h) do { _Pragma("unroll") for (int n = 0; n < 2; ++n) _Pragma("unroll") for (int k = 0; k < 2; ++k) dst[n][k] = *(const PG8_LAS bf16x8*)(lds + PG8_SB(b, h) + boff + n * 2048 + k * 1024); } while (0)
; #define PG8_MMA(ai, bj, At, Bt) do { __builtin_amdgcn_s_setprio(1); _Pragma("unroll") for (int m = 0; m < 4; ++m) _Pragma("unroll") for (int n = 0; n < 2; ++n) _Pragma("unroll") for (int k = 0; k < 2; ++k) \
;         acc[ai][bj][m][n] = __builtin_amdgcn_mfma_f32_16x16x32_bf16(Bt[n][k], At[m][k], acc[ai][bj][m][n], 0, 0, 0); __builtin_amdgcn_s_setprio(0); } while (0)
; #define PG8_WAIT_V(n) asm volatile("s_waitcnt vmcnt(" #n ")" ::: "memory")
; #define PG8_WAIT_L(n) asm volatile("s_waitcnt lgkmcnt(" #n ")" ::: "memory")
; #define PG8_BAR __builtin_amdgcn_s_barrier()
; #define PG8_SCHED __builtin_amdgcn_sched_barrier(0)
; template <class Epi, class Sched, bool ALIGN_EPI = false, bool SP2 = false>
; __device__ __forceinline__ void gemm_phase(PG8_LAS unsigned char* lds, const Gemm g, const Sched& S, const Epi& E) {
;     ...
;             PG8_WAIT_V(8); PG8_WAIT_L(0); PG8_BAR; PG8_MMA(1, 0, At, B0); PG8_MMA(1, 1, At, B1); PG8_BAR; PG8_SCHED;
;             PG8_LDB(B0, 1, 0); PG8_LDB(B1, 1, 1); PG8_SCHED; PG8_LDA(At, 1, 0); PG8_STAGE(PG8_SA(0, 1), a2 + hstep, voffA);
;             PG8_WAIT_V(8); PG8_WAIT_L(0); PG8_BAR; PG8_MMA(0, 0, At, B0); PG8_MMA(0, 1, At, B1); PG8_BAR; PG8_SCHED;
	s_setprio 1
	s_waitcnt lgkmcnt(0)
	v_mfma_f32_16x16x32_bf16 v[58:61], v[154:157], v[204:207], 0
	v_mfma_f32_16x16x32_bf16 v[50:53], v[162:165], v[204:207], 0
	v_mfma_f32_16x16x32_bf16 v[42:45], v[154:157], v[212:215], 0
	v_mfma_f32_16x16x32_bf16 v[34:37], v[162:165], v[212:215], 0
	v_mfma_f32_16x16x32_bf16 v[26:29], v[154:157], v[220:223], 0
	v_mfma_f32_16x16x32_bf16 v[18:21], v[162:165], v[220:223], 0
	v_mfma_f32_16x16x32_bf16 v[10:13], v[154:157], v[228:231], 0
	v_mfma_f32_16x16x32_bf16 v[2:5], v[162:165], v[228:231], 0
	v_mfma_f32_16x16x32_bf16 v[58:61], v[158:161], v[208:211], v[58:61]
	v_mfma_f32_16x16x32_bf16 v[50:53], v[166:169], v[208:211], v[50:53]
	v_mfma_f32_16x16x32_bf16 v[42:45], v[158:161], v[216:219], v[42:45]
	v_mfma_f32_16x16x32_bf16 v[34:37], v[166:169], v[216:219], v[34:37]
	v_mfma_f32_16x16x32_bf16 v[26:29], v[158:161], v[224:227], v[26:29]
	v_mfma_f32_16x16x32_bf16 v[18:21], v[166:169], v[224:227], v[18:21]
	v_mfma_f32_16x16x32_bf16 v[10:13], v[158:161], v[232:235], v[10:13]
	v_mfma_f32_16x16x32_bf16 v[2:5], v[166:169], v[232:235], v[2:5]
	s_setprio 0
	s_setprio 1
	v_mfma_f32_16x16x32_bf16 v[62:65], v[170:173], v[204:207], 0
	v_mfma_f32_16x16x32_bf16 v[54:57], v[178:181], v[204:207], 0
	v_mfma_f32_16x16x32_bf16 v[46:49], v[170:173], v[212:215], 0
	v_mfma_f32_16x16x32_bf16 v[38:41], v[178:181], v[212:215], 0
	v_mfma_f32_16x16x32_bf16 v[30:33], v[170:173], v[220:223], 0
	v_mfma_f32_16x16x32_bf16 v[22:25], v[178:181], v[220:223], 0
	v_mfma_f32_16x16x32_bf16 v[14:17], v[170:173], v[228:231], 0
	v_mfma_f32_16x16x32_bf16 v[6:9], v[178:181], v[228:231], 0
	v_mfma_f32_16x16x32_bf16 v[62:65], v[174:177], v[208:211], v[62:65]
	v_mfma_f32_16x16x32_bf16 v[54:57], v[200:203], v[208:211], v[54:57]
	v_mfma_f32_16x16x32_bf16 v[46:49], v[174:177], v[216:219], v[46:49]
	v_mfma_f32_16x16x32_bf16 v[38:41], v[200:203], v[216:219], v[38:41]
	v_mfma_f32_16x16x32_bf16 v[30:33], v[174:177], v[224:227], v[30:33]
	v_mfma_f32_16x16x32_bf16 v[22:25], v[200:203], v[224:227], v[22:25]
	v_mfma_f32_16x16x32_bf16 v[14:17], v[174:177], v[232:235], v[14:17]
	v_mfma_f32_16x16x32_bf16 v[6:9], v[200:203], v[232:235], v[6:9]
	s_setprio 0
	s_barrier
	s_add_i32 s56, 0, 0x18000
	s_add_i32 s57, 0, 0x1c000
	v_add_u32_e32 v166, s56, v143
	v_add_u32_e32 v200, s57, v143
	ds_read_b128 v[154:157], v166
	ds_read_b128 v[158:161], v166 offset:1024
	ds_read_b128 v[162:165], v166 offset:2048
	ds_read_b128 v[166:169], v166 offset:3072
	ds_read_b128 v[170:173], v200
	ds_read_b128 v[174:177], v200 offset:1024
	ds_read_b128 v[178:181], v200 offset:2048
	ds_read_b128 v[200:203], v200 offset:3072
	s_add_u32 s20, s20, 0x40000
	s_addc_u32 s21, s21, 0
	s_mov_b32 m0, s27
	v_lshl_add_u64 v[238:239], s[20:21], 0, v[134:135]
	ds_read_b128 v[204:207], v145 offset:32768
	ds_read_b128 v[208:211], v145 offset:33792
	ds_read_b128 v[212:215], v145 offset:34816
	ds_read_b128 v[216:219], v145 offset:35840
	ds_read_b128 v[220:223], v145 offset:36864
	ds_read_b128 v[224:227], v145 offset:37888
	ds_read_b128 v[228:231], v145 offset:38912
	ds_read_b128 v[232:235], v145 offset:39936
	global_load_lds_dwordx4 v[238:239], off
	v_lshl_add_u64 v[238:239], s[20:21], 0, v[132:133]
	s_mov_b32 m0, s28
	s_nop 0
	global_load_lds_dwordx4 v[238:239], off
	s_waitcnt vmcnt(8)
	s_waitcnt lgkmcnt(0)
	s_barrier
	s_setprio 1
	s_waitcnt lgkmcnt(0)
	v_mfma_f32_16x16x32_bf16 v[122:125], v[154:157], v[204:207], v[122:125]
	v_mfma_f32_16x16x32_bf16 v[114:117], v[162:165], v[204:207], v[114:117]
	v_mfma_f32_16x16x32_bf16 v[106:109], v[154:157], v[212:215], v[106:109]
	v_mfma_f32_16x16x32_bf16 v[98:101], v[162:165], v[212:215], v[98:101]
	v_mfma_f32_16x16x32_bf16 v[90:93], v[154:157], v[220:223], v[90:93]
	v_mfma_f32_16x16x32_bf16 v[82:85], v[162:165], v[220:223], v[82:85]
	v_mfma_f32_16x16x32_bf16 v[74:77], v[154:157], v[228:231], v[74:77]
	v_mfma_f32_16x16x32_bf16 v[66:69], v[162:165], v[228:231], v[66:69]
	v_mfma_f32_16x16x32_bf16 v[122:125], v[158:161], v[208:211], v[122:125]
	v_mfma_f32_16x16x32_bf16 v[114:117], v[166:169], v[208:211], v[114:117]
	v_mfma_f32_16x16x32_bf16 v[106:109], v[158:161], v[216:219], v[106:109]
	v_mfma_f32_16x16x32_bf16 v[98:101], v[166:169], v[216:219], v[98:101]
	v_mfma_f32_16x16x32_bf16 v[90:93], v[158:161], v[224:227], v[90:93]
	v_mfma_f32_16x16x32_bf16 v[82:85], v[166:169], v[224:227], v[82:85]
	v_mfma_f32_16x16x32_bf16 v[74:77], v[158:161], v[232:235], v[74:77]
	v_mfma_f32_16x16x32_bf16 v[66:69], v[166:169], v[232:235], v[66:69]
	s_setprio 0
	s_setprio 1
	v_mfma_f32_16x16x32_bf16 v[126:129], v[170:173], v[204:207], v[126:129]
	v_mfma_f32_16x16x32_bf16 v[118:121], v[178:181], v[204:207], v[118:121]
	v_mfma_f32_16x16x32_bf16 v[110:113], v[170:173], v[212:215], v[110:113]
	v_mfma_f32_16x16x32_bf16 v[102:105], v[178:181], v[212:215], v[102:105]
	v_mfma_f32_16x16x32_bf16 v[94:97], v[170:173], v[220:223], v[94:97]
	v_mfma_f32_16x16x32_bf16 v[86:89], v[178:181], v[220:223], v[86:89]
	v_mfma_f32_16x16x32_bf16 v[78:81], v[170:173], v[228:231], v[78:81]
	v_mfma_f32_16x16x32_bf16 v[70:73], v[178:181], v[228:231], v[70:73]
	v_mfma_f32_16x16x32_bf16 v[126:129], v[174:177], v[208:211], v[126:129]
	v_mfma_f32_16x16x32_bf16 v[118:121], v[200:203], v[208:211], v[118:121]
	v_mfma_f32_16x16x32_bf16 v[110:113], v[174:177], v[216:219], v[110:113]
	v_mfma_f32_16x16x32_bf16 v[102:105], v[200:203], v[216:219], v[102:105]
	v_mfma_f32_16x16x32_bf16 v[94:97], v[174:177], v[224:227], v[94:97]
	v_mfma_f32_16x16x32_bf16 v[86:89], v[200:203], v[224:227], v[86:89]
	v_mfma_f32_16x16x32_bf16 v[78:81], v[174:177], v[232:235], v[78:81]
	v_mfma_f32_16x16x32_bf16 v[70:73], v[200:203], v[232:235], v[70:73]
	s_setprio 0
	s_barrier
; #define PG8_STAGE(bufoff, gbase, voff) do { _Pragma("unroll") for (int _i = 0; _i < 2; ++_i) \
;         __builtin_amdgcn_global_load_lds((const unsigned*)((const char*)(gbase) + (voff)[_i]), (PG8_LAS unsigned*)(lds + (bufoff) + ldsw + _i * 8192), 16, 0, 0); } while (0)
; #define PG8_LDA(dst, b, h) do { _Pragma("unroll") for (int m = 0; m < 4; ++m) _Pragma("unroll") for (int k = 0; k < 2; ++k) dst[m][k] = *(const PG8_LAS bf16x8*)(lds + PG8_SA(b, h) + aoff + m * 2048 + k * 1024); } while (0)
; #define PG8_LDB(dst, b, h) do { _Pragma("unroll") for (int n = 0; n < 2; ++n) _Pragma("unroll") for (int k = 0; k < 2; ++k) dst[n][k] = *(const PG8_LAS bf16x8*)(lds + PG8_SB(b, h) + boff + n * 2048 + k * 1024); } while (0)
; #define PG8_MMA(ai, bj, At, Bt) do { __builtin_amdgcn_s_setprio(1); _Pragma("unroll") for (int m = 0; m < 4; ++m) _Pragma("unroll") for (int n = 0; n < 2; ++n) _Pragma("unroll") for (int k = 0; k < 2; ++k) \
;         acc[ai][bj][m][n] = __builtin_amdgcn_mfma_f32_16x16x32_bf16(Bt[n][k], At[m][k], acc[ai][bj][m][n], 0, 0, 0); __builtin_amdgcn_s_setprio(0); } while (0)
; #define PG8_WAIT_V(n) asm volatile("s_waitcnt vmcnt(" #n ")" ::: "memory")
; template <class Epi, class Sched, bool ALIGN_EPI = false, bool SP2 = false>
; __device__ __forceinline__ void gemm_phase(PG8_LAS unsigned char* lds, const Gemm g, const Sched& S, const Epi& E) {
;     ...
;             PG8_LDB(B0, 0, 0); PG8_LDB(B1, 0, 1); PG8_SCHED; PG8_LDA(At, 0, 0); PG8_STAGE(PG8_SA(1, 1), a1 + hstep, voffA);
;             PG8_WAIT_V(8); PG8_WAIT_L(0); PG8_BAR; PG8_MMA(0, 0, At, B0); PG8_MMA(0, 1, At, B1); PG8_BAR; PG8_SCHED;
;             PG8_LDA(At, 0, 1); PG8_STAGE(PG8_SB(0, 0), b2, voffB); PG8_STAGE(PG8_SB(0, 1), b2 + hstep, voffB); PG8_STAGE(PG8_SA(0, 0), a2, voffA);
;             PG8_WAIT_V(8); PG8_WAIT_L(0); PG8_BAR; PG8_MMA(1, 0, At, B0); PG8_MMA(1, 1, At, B1); PG8_BAR; PG8_SCHED;
;             PG8_LDB(B0, 1, 0); PG8_LDB(B1, 1, 1); PG8_SCHED; PG8_LDA(At, 1, 0); PG8_STAGE(PG8_SA(0, 1), a2 + hstep, voffA);
;             PG8_WAIT_V(8); PG8_WAIT_L(0); PG8_BAR; PG8_MMA(0, 0, At, B0); PG8_MMA(0, 1, At, B1); PG8_BAR; PG8_SCHED;
;             PG8_LDA(At, 1, 1); PG8_STAGE(PG8_SB(1, 0), b3, voffB); PG8_STAGE(PG8_SB(1, 1), b3 + hstep, voffB); PG8_STAGE(PG8_SA(1, 0), a3, voffA);
;             PG8_WAIT_V(8); PG8_WAIT_L(0); PG8_BAR; PG8_MMA(1, 0, At, B0); PG8_MMA(1, 1, At, B1); PG8_BAR; PG8_SCHED;
	s_add_i32 s20, s56, s24
	v_lshl_add_u64 v[140:141], v[140:141], 0, s[38:39]
	s_mov_b32 m0, s20
	ds_read_b128 v[204:207], v145 offset:49152
	ds_read_b128 v[208:211], v145 offset:50176
	ds_read_b128 v[212:215], v145 offset:51200
	ds_read_b128 v[216:219], v145 offset:52224
	ds_read_b128 v[220:223], v145 offset:53248
	ds_read_b128 v[224:227], v145 offset:54272
	ds_read_b128 v[228:231], v145 offset:55296
	ds_read_b128 v[232:235], v145 offset:56320
	global_load_lds_dwordx4 v[140:141], off
	s_add_i32 m0, s20, 0x2000
	s_add_u32 s18, s18, 0x40080
	v_lshl_add_u64 v[140:141], v[146:147], 0, s[38:39]
	s_addc_u32 s19, s19, 0
	s_add_i32 s20, s57, s24
	global_load_lds_dwordx4 v[140:141], off
	v_lshl_add_u64 v[140:141], s[18:19], 0, v[0:1]
	s_mov_b32 m0, s20
	s_nop 0
	global_load_lds_dwordx4 v[140:141], off
	v_lshl_add_u64 v[140:141], s[18:19], 0, v[130:131]
	s_add_i32 m0, s20, 0x2000
	s_nop 0
	global_load_lds_dwordx4 v[140:141], off
	v_lshl_add_u64 v[140:141], v[148:149], 0, s[38:39]
	s_mov_b32 m0, s29
	s_nop 0
	global_load_lds_dwordx4 v[140:141], off
	v_lshl_add_u64 v[140:141], v[236:237], 0, s[38:39]
	s_mov_b32 m0, s30
	s_nop 0
	global_load_lds_dwordx4 v[140:141], off
	s_waitcnt vmcnt(8)
	s_waitcnt lgkmcnt(0)
	s_barrier
	s_setprio 1
	s_waitcnt lgkmcnt(0)
	v_mfma_f32_16x16x32_bf16 v[58:61], v[154:157], v[204:207], v[58:61]
	v_mfma_f32_16x16x32_bf16 v[50:53], v[162:165], v[204:207], v[50:53]
	v_mfma_f32_16x16x32_bf16 v[42:45], v[154:157], v[212:215], v[42:45]
	v_mfma_f32_16x16x32_bf16 v[34:37], v[162:165], v[212:215], v[34:37]
	v_mfma_f32_16x16x32_bf16 v[26:29], v[154:157], v[220:223], v[26:29]
	v_mfma_f32_16x16x32_bf16 v[18:21], v[162:165], v[220:223], v[18:21]
	v_mfma_f32_16x16x32_bf16 v[10:13], v[154:157], v[228:231], v[10:13]
	v_mfma_f32_16x16x32_bf16 v[2:5], v[162:165], v[228:231], v[2:5]
	v_mfma_f32_16x16x32_bf16 v[58:61], v[158:161], v[208:211], v[58:61]
	v_mfma_f32_16x16x32_bf16 v[50:53], v[166:169], v[208:211], v[50:53]
	v_mfma_f32_16x16x32_bf16 v[42:45], v[158:161], v[216:219], v[42:45]
	v_mfma_f32_16x16x32_bf16 v[34:37], v[166:169], v[216:219], v[34:37]
	v_mfma_f32_16x16x32_bf16 v[26:29], v[158:161], v[224:227], v[26:29]
	v_mfma_f32_16x16x32_bf16 v[18:21], v[166:169], v[224:227], v[18:21]
	v_mfma_f32_16x16x32_bf16 v[10:13], v[158:161], v[232:235], v[10:13]
	v_mfma_f32_16x16x32_bf16 v[2:5], v[166:169], v[232:235], v[2:5]
	s_setprio 0
	s_setprio 1
	v_mfma_f32_16x16x32_bf16 v[62:65], v[170:173], v[204:207], v[62:65]
	v_mfma_f32_16x16x32_bf16 v[54:57], v[178:181], v[204:207], v[54:57]
	v_mfma_f32_16x16x32_bf16 v[46:49], v[170:173], v[212:215], v[46:49]
	v_mfma_f32_16x16x32_bf16 v[38:41], v[178:181], v[212:215], v[38:41]
	v_mfma_f32_16x16x32_bf16 v[30:33], v[170:173], v[220:223], v[30:33]
	v_mfma_f32_16x16x32_bf16 v[22:25], v[178:181], v[220:223], v[22:25]
	v_mfma_f32_16x16x32_bf16 v[14:17], v[170:173], v[228:231], v[14:17]
	v_mfma_f32_16x16x32_bf16 v[6:9], v[178:181], v[228:231], v[6:9]
	v_mfma_f32_16x16x32_bf16 v[62:65], v[174:177], v[208:211], v[62:65]
	v_mfma_f32_16x16x32_bf16 v[54:57], v[200:203], v[208:211], v[54:57]
	v_mfma_f32_16x16x32_bf16 v[46:49], v[174:177], v[216:219], v[46:49]
	v_mfma_f32_16x16x32_bf16 v[38:41], v[200:203], v[216:219], v[38:41]
	v_mfma_f32_16x16x32_bf16 v[30:33], v[174:177], v[224:227], v[30:33]
	v_mfma_f32_16x16x32_bf16 v[22:25], v[200:203], v[224:227], v[22:25]
	v_mfma_f32_16x16x32_bf16 v[14:17], v[174:177], v[232:235], v[14:17]
	v_mfma_f32_16x16x32_bf16 v[6:9], v[200:203], v[232:235], v[6:9]
	s_setprio 0
	s_barrier
	s_add_i32 s55, s55, 2
	s_add_u32 s16, s16, 0x100
	s_addc_u32 s17, s17, 0
	s_add_u32 s52, s52, 0x100
	s_addc_u32 s53, s53, 0
.LBB0_368:
	s_add_u32 s18, s16, 0xfffc0080
	s_addc_u32 s19, s17, -1
	s_add_i32 s56, 0, 0x10000
	s_cmp_eq_u32 s55, 12
	s_cselect_b32 s21, s11, s19
	s_cselect_b32 s20, s50, s18
	v_add_u32_e32 v140, s56, v143
	s_cselect_b32 s19, s9, s53
	s_cselect_b32 s18, s51, s52
	s_add_i32 s58, 0, 0x14000
	ds_read_b128 v[154:157], v140
	ds_read_b128 v[158:161], v140 offset:1024
	ds_read_b128 v[162:165], v140 offset:2048
	ds_read_b128 v[166:169], v140 offset:3072
	v_add_u32_e32 v140, s58, v143
	ds_read_b128 v[170:173], v140
	ds_read_b128 v[174:177], v140 offset:1024
	ds_read_b128 v[178:181], v140 offset:2048
	ds_read_b128 v[200:203], v140 offset:3072
	v_lshl_add_u64 v[140:141], s[16:17], 0, v[136:137]
	s_add_i32 m0, s25, 0xc000
	ds_read_b128 v[204:207], v145
	ds_read_b128 v[208:211], v145 offset:1024
	ds_read_b128 v[212:215], v145 offset:2048
	ds_read_b128 v[216:219], v145 offset:3072
	ds_read_b128 v[220:223], v145 offset:4096
	ds_read_b128 v[224:227], v145 offset:5120
	ds_read_b128 v[228:231], v145 offset:6144
	ds_read_b128 v[232:235], v145 offset:7168
	global_load_lds_dwordx4 v[140:141], off
	v_lshl_add_u64 v[140:141], s[16:17], 0, v[138:139]
	s_add_i32 m0, s25, 0xe000
	s_nop 0
	global_load_lds_dwordx4 v[140:141], off
	s_waitcnt vmcnt(8)
	s_waitcnt lgkmcnt(0)
	s_barrier
; #define PG8_STAGE(bufoff, gbase, voff) do { _Pragma("unroll") for (int _i = 0; _i < 2; ++_i) \
;         __builtin_amdgcn_global_load_lds((const unsigned*)((const char*)(gbase) + (voff)[_i]), (PG8_LAS unsigned*)(lds + (bufoff) + ldsw + _i * 8192), 16, 0, 0); } while (0)
; #define PG8_LDA(dst, b, h) do { _Pragma("unroll") for (int m = 0; m < 4; ++m) _Pragma("unroll") for (int k = 0; k < 2; ++k) dst[m][k] = *(const PG8_LAS bf16x8*)(lds + PG8_SA(b, h) + aoff + m * 2048 + k * 1024); } while (0)
; #define PG8_MMA(ai, bj, At, Bt) do { __builtin_amdgcn_s_setprio(1); _Pragma("unroll") for (int m = 0; m < 4; ++m) _Pragma("unroll") for (int n = 0; n < 2; ++n) _Pragma("unroll") for (int k = 0; k < 2; ++k) \
;         acc[ai][bj][m][n] = __builtin_amdgcn_mfma_f32_16x16x32_bf16(Bt[n][k], At[m][k], acc[ai][bj][m][n], 0, 0, 0); __builtin_amdgcn_s_setprio(0); } while (0)
; #define PG8_WAIT_V(n) asm volatile("s_waitcnt vmcnt(" #n ")" ::: "memory")
; #define PG8_WAIT_L(n) asm volatile("s_waitcnt lgkmcnt(" #n ")" ::: "memory")
; #define PG8_BAR __builtin_amdgcn_s_barrier()
; #define PG8_SCHED __builtin_amdgcn_sched_barrier(0)
; template <class Epi, class Sched, bool ALIGN_EPI = false, bool SP2 = false>
; __device__ __forceinline__ void gemm_phase(PG8_LAS unsigned char* lds, const Gemm g, const Sched& S, const Epi& E) {
;     ...
;             PG8_WAIT_V(8); PG8_WAIT_L(0); PG8_BAR; PG8_MMA(0, 0, At, B0); PG8_MMA(0, 1, At, B1); PG8_BAR; PG8_SCHED;
;             PG8_LDA(At, 0, 1); PG8_STAGE(PG8_SB(0, 0), b2, voffB); PG8_STAGE(PG8_SB(0, 1), b2 + hstep, voffB); PG8_STAGE(PG8_SA(0, 0), a2, voffA);
;             PG8_WAIT_V(8); PG8_WAIT_L(0); PG8_BAR; PG8_MMA(1, 0, At, B0); PG8_MMA(1, 1, At, B1); PG8_BAR; PG8_SCHED;
	s_setprio 1
	s_waitcnt lgkmcnt(0)
	v_mfma_f32_16x16x32_bf16 v[122:125], v[154:157], v[204:207], v[122:125]
	v_mfma_f32_16x16x32_bf16 v[114:117], v[162:165], v[204:207], v[114:117]
	v_mfma_f32_16x16x32_bf16 v[106:109], v[154:157], v[212:215], v[106:109]
	v_mfma_f32_16x16x32_bf16 v[98:101], v[162:165], v[212:215], v[98:101]
	v_mfma_f32_16x16x32_bf16 v[90:93], v[154:157], v[220:223], v[90:93]
	v_mfma_f32_16x16x32_bf16 v[82:85], v[162:165], v[220:223], v[82:85]
	v_mfma_f32_16x16x32_bf16 v[74:77], v[154:157], v[228:231], v[74:77]
	v_mfma_f32_16x16x32_bf16 v[66:69], v[162:165], v[228:231], v[66:69]
	v_mfma_f32_16x16x32_bf16 v[122:125], v[158:161], v[208:211], v[122:125]
	v_mfma_f32_16x16x32_bf16 v[114:117], v[166:169], v[208:211], v[114:117]
	v_mfma_f32_16x16x32_bf16 v[106:109], v[158:161], v[216:219], v[106:109]
	v_mfma_f32_16x16x32_bf16 v[98:101], v[166:169], v[216:219], v[98:101]
	v_mfma_f32_16x16x32_bf16 v[90:93], v[158:161], v[224:227], v[90:93]
	v_mfma_f32_16x16x32_bf16 v[82:85], v[166:169], v[224:227], v[82:85]
	v_mfma_f32_16x16x32_bf16 v[74:77], v[158:161], v[232:235], v[74:77]
	v_mfma_f32_16x16x32_bf16 v[66:69], v[166:169], v[232:235], v[66:69]
	s_setprio 0
	s_setprio 1
	v_mfma_f32_16x16x32_bf16 v[126:129], v[170:173], v[204:207], v[126:129]
	v_mfma_f32_16x16x32_bf16 v[118:121], v[178:181], v[204:207], v[118:121]
	v_mfma_f32_16x16x32_bf16 v[110:113], v[170:173], v[212:215], v[110:113]
	v_mfma_f32_16x16x32_bf16 v[102:105], v[178:181], v[212:215], v[102:105]
	v_mfma_f32_16x16x32_bf16 v[94:97], v[170:173], v[220:223], v[94:97]
	v_mfma_f32_16x16x32_bf16 v[86:89], v[178:181], v[220:223], v[86:89]
	v_mfma_f32_16x16x32_bf16 v[78:81], v[170:173], v[228:231], v[78:81]
	v_mfma_f32_16x16x32_bf16 v[70:73], v[178:181], v[228:231], v[70:73]
	v_mfma_f32_16x16x32_bf16 v[126:129], v[174:177], v[208:211], v[126:129]
	v_mfma_f32_16x16x32_bf16 v[118:121], v[200:203], v[208:211], v[118:121]
	v_mfma_f32_16x16x32_bf16 v[110:113], v[174:177], v[216:219], v[110:113]
	v_mfma_f32_16x16x32_bf16 v[102:105], v[200:203], v[216:219], v[102:105]
	v_mfma_f32_16x16x32_bf16 v[94:97], v[174:177], v[224:227], v[94:97]
	v_mfma_f32_16x16x32_bf16 v[86:89], v[200:203], v[224:227], v[86:89]
	v_mfma_f32_16x16x32_bf16 v[78:81], v[174:177], v[232:235], v[78:81]
	v_mfma_f32_16x16x32_bf16 v[70:73], v[200:203], v[232:235], v[70:73]
	s_setprio 0
	s_barrier
	s_add_i32 s56, s56, s24
	v_lshl_add_u64 v[140:141], s[18:19], 0, v[0:1]
	s_mov_b32 m0, s56
	ds_read_b128 v[204:207], v145 offset:16384
	ds_read_b128 v[208:211], v145 offset:17408
	ds_read_b128 v[212:215], v145 offset:18432
	ds_read_b128 v[216:219], v145 offset:19456
	ds_read_b128 v[220:223], v145 offset:20480
	ds_read_b128 v[224:227], v145 offset:21504
	ds_read_b128 v[228:231], v145 offset:22528
	ds_read_b128 v[232:235], v145 offset:23552
	global_load_lds_dwordx4 v[140:141], off
	s_add_i32 m0, s56, 0x2000
	s_add_u32 s56, s18, 0x40000
	v_lshl_add_u64 v[146:147], s[18:19], 0, v[130:131]
	s_addc_u32 s57, s19, 0
	s_add_i32 s58, s58, s24
	global_load_lds_dwordx4 v[146:147], off
	v_lshl_add_u64 v[148:149], s[56:57], 0, v[0:1]
	s_mov_b32 m0, s58
	v_lshl_add_u64 v[236:237], s[20:21], 0, v[132:133]
	global_load_lds_dwordx4 v[148:149], off
	v_lshl_add_u64 v[148:149], s[56:57], 0, v[130:131]
	s_add_i32 m0, s58, 0x2000
	s_nop 0
	global_load_lds_dwordx4 v[148:149], off
	v_lshl_add_u64 v[148:149], s[20:21], 0, v[134:135]
	s_mov_b32 m0, s25
	s_nop 0
	global_load_lds_dwordx4 v[148:149], off
	s_mov_b32 m0, s26
	s_nop 0
	global_load_lds_dwordx4 v[236:237], off
	s_waitcnt vmcnt(8)
	s_waitcnt lgkmcnt(0)
	s_barrier
	s_setprio 1
	s_waitcnt lgkmcnt(0)
	v_mfma_f32_16x16x32_bf16 v[58:61], v[154:157], v[204:207], v[58:61]
	v_mfma_f32_16x16x32_bf16 v[50:53], v[162:165], v[204:207], v[50:53]
	v_mfma_f32_16x16x32_bf16 v[42:45], v[154:157], v[212:215], v[42:45]
	v_mfma_f32_16x16x32_bf16 v[34:37], v[162:165], v[212:215], v[34:37]
	v_mfma_f32_16x16x32_bf16 v[26:29], v[154:157], v[220:223], v[26:29]
	v_mfma_f32_16x16x32_bf16 v[18:21], v[162:165], v[220:223], v[18:21]
	v_mfma_f32_16x16x32_bf16 v[10:13], v[154:157], v[228:231], v[10:13]
	v_mfma_f32_16x16x32_bf16 v[2:5], v[162:165], v[228:231], v[2:5]
	v_mfma_f32_16x16x32_bf16 v[58:61], v[158:161], v[208:211], v[58:61]
	v_mfma_f32_16x16x32_bf16 v[50:53], v[166:169], v[208:211], v[50:53]
	v_mfma_f32_16x16x32_bf16 v[42:45], v[158:161], v[216:219], v[42:45]
	v_mfma_f32_16x16x32_bf16 v[34:37], v[166:169], v[216:219], v[34:37]
	v_mfma_f32_16x16x32_bf16 v[26:29], v[158:161], v[224:227], v[26:29]
	v_mfma_f32_16x16x32_bf16 v[18:21], v[166:169], v[224:227], v[18:21]
	v_mfma_f32_16x16x32_bf16 v[10:13], v[158:161], v[232:235], v[10:13]
	v_mfma_f32_16x16x32_bf16 v[2:5], v[166:169], v[232:235], v[2:5]
	s_setprio 0
	s_setprio 1
	v_mfma_f32_16x16x32_bf16 v[62:65], v[170:173], v[204:207], v[62:65]
	v_mfma_f32_16x16x32_bf16 v[54:57], v[178:181], v[204:207], v[54:57]
	v_mfma_f32_16x16x32_bf16 v[46:49], v[170:173], v[212:215], v[46:49]
	v_mfma_f32_16x16x32_bf16 v[38:41], v[178:181], v[212:215], v[38:41]
	v_mfma_f32_16x16x32_bf16 v[30:33], v[170:173], v[220:223], v[30:33]
	v_mfma_f32_16x16x32_bf16 v[22:25], v[178:181], v[220:223], v[22:25]
	v_mfma_f32_16x16x32_bf16 v[14:17], v[170:173], v[228:231], v[14:17]
	v_mfma_f32_16x16x32_bf16 v[6:9], v[178:181], v[228:231], v[6:9]
	v_mfma_f32_16x16x32_bf16 v[62:65], v[174:177], v[208:211], v[62:65]
	v_mfma_f32_16x16x32_bf16 v[54:57], v[200:203], v[208:211], v[54:57]
	v_mfma_f32_16x16x32_bf16 v[46:49], v[174:177], v[216:219], v[46:49]
	v_mfma_f32_16x16x32_bf16 v[38:41], v[200:203], v[216:219], v[38:41]
	v_mfma_f32_16x16x32_bf16 v[30:33], v[174:177], v[224:227], v[30:33]
	v_mfma_f32_16x16x32_bf16 v[22:25], v[200:203], v[224:227], v[22:25]
	v_mfma_f32_16x16x32_bf16 v[14:17], v[174:177], v[232:235], v[14:17]
	v_mfma_f32_16x16x32_bf16 v[6:9], v[200:203], v[232:235], v[6:9]
	s_setprio 0
	s_barrier
; #define PG8_STAGE(bufoff, gbase, voff) do { _Pragma("unroll") for (int _i = 0; _i < 2; ++_i) \
;         __builtin_amdgcn_global_load_lds((const unsigned*)((const char*)(gbase) + (voff)[_i]), (PG8_LAS unsigned*)(lds + (bufoff) + ldsw + _i * 8192), 16, 0, 0); } while (0)
; #define PG8_LDA(dst, b, h) do { _Pragma("unroll") for (int m = 0; m < 4; ++m) _Pragma("unroll") for (int k = 0; k < 2; ++k) dst[m][k] = *(const PG8_LAS bf16x8*)(lds + PG8_SA(b, h) + aoff + m * 2048 + k * 1024); } while (0)
; #define PG8_LDB(dst, b, h) do { _Pragma("unroll") for (int n = 0; n < 2; ++n) _Pragma("unroll") for (int k = 0; k < 2; ++k) dst[n][k] = *(const PG8_LAS bf16x8*)(lds + PG8_SB(b, h) + boff + n * 2048 + k * 1024); } while (0)
; #define PG8_MMA(ai, bj, At, Bt) do { __builtin_amdgcn_s_setprio(1); _Pragma("unroll") for (int m = 0; m < 4; ++m) _Pragma("unroll") for (int n = 0; n < 2; ++n) _Pragma("unroll") for (int k = 0; k < 2; ++k) \
;         acc[ai][bj][m][n] = __builtin_amdgcn_mfma_f32_16x16x32_bf16(Bt[n][k], At[m][k], acc[ai][bj][m][n], 0, 0, 0); __builtin_amdgcn_s_setprio(0); } while (0)
; #define PG8_WAIT_V(n) asm volatile("s_waitcnt vmcnt(" #n ")" ::: "memory")
; #define PG8_WAIT_L(n) asm volatile("s_waitcnt lgkmcnt(" #n ")" ::: "memory")
; #define PG8_BAR __builtin_amdgcn_s_barrier()
; #define PG8_SCHED __builtin_amdgcn_sched_barrier(0)
; template <class Epi, class Sched, bool ALIGN_EPI = false, bool SP2 = false>
; __device__ __forceinline__ void gemm_phase(PG8_LAS unsigned char* lds, const Gemm g, const Sched& S, const Epi& E) {
;     ...
;             PG8_LDB(B0, 1, 0); PG8_LDB(B1, 1, 1); PG8_SCHED; PG8_LDA(At, 1, 0); PG8_STAGE(PG8_SA(0, 1), a2 + hstep, voffA);
;             PG8_WAIT_V(8); PG8_WAIT_L(0); PG8_BAR; PG8_MMA(0, 0, At, B0); PG8_MMA(0, 1, At, B1); PG8_BAR; PG8_SCHED;
	s_add_i32 s56, 0, 0x18000
	s_add_i32 s57, 0, 0x1c000
	v_add_u32_e32 v166, s56, v143
	v_add_u32_e32 v200, s57, v143
	ds_read_b128 v[154:157], v166
	ds_read_b128 v[158:161], v166 offset:1024
	ds_read_b128 v[162:165], v166 offset:2048
	ds_read_b128 v[166:169], v166 offset:3072
	ds_read_b128 v[170:173], v200
	ds_read_b128 v[174:177], v200 offset:1024
	ds_read_b128 v[178:181], v200 offset:2048
	ds_read_b128 v[200:203], v200 offset:3072
	s_add_u32 s20, s20, 0x40000
	s_addc_u32 s21, s21, 0
	s_mov_b32 m0, s27
	v_lshl_add_u64 v[238:239], s[20:21], 0, v[134:135]
	ds_read_b128 v[204:207], v145 offset:32768
	ds_read_b128 v[208:211], v145 offset:33792
	ds_read_b128 v[212:215], v145 offset:34816
	ds_read_b128 v[216:219], v145 offset:35840
	ds_read_b128 v[220:223], v145 offset:36864
	ds_read_b128 v[224:227], v145 offset:37888
	ds_read_b128 v[228:231], v145 offset:38912
	ds_read_b128 v[232:235], v145 offset:39936
	global_load_lds_dwordx4 v[238:239], off
	v_lshl_add_u64 v[238:239], s[20:21], 0, v[132:133]
	s_mov_b32 m0, s28
	s_nop 0
	global_load_lds_dwordx4 v[238:239], off
	s_waitcnt vmcnt(8)
	s_waitcnt lgkmcnt(0)
	s_barrier
	s_setprio 1
	s_waitcnt lgkmcnt(0)
	v_mfma_f32_16x16x32_bf16 v[122:125], v[154:157], v[204:207], v[122:125]
	v_mfma_f32_16x16x32_bf16 v[114:117], v[162:165], v[204:207], v[114:117]
	v_mfma_f32_16x16x32_bf16 v[106:109], v[154:157], v[212:215], v[106:109]
	v_mfma_f32_16x16x32_bf16 v[98:101], v[162:165], v[212:215], v[98:101]
	v_mfma_f32_16x16x32_bf16 v[90:93], v[154:157], v[220:223], v[90:93]
	v_mfma_f32_16x16x32_bf16 v[82:85], v[162:165], v[220:223], v[82:85]
	v_mfma_f32_16x16x32_bf16 v[74:77], v[154:157], v[228:231], v[74:77]
	v_mfma_f32_16x16x32_bf16 v[66:69], v[162:165], v[228:231], v[66:69]
	v_mfma_f32_16x16x32_bf16 v[122:125], v[158:161], v[208:211], v[122:125]
	v_mfma_f32_16x16x32_bf16 v[114:117], v[166:169], v[208:211], v[114:117]
	v_mfma_f32_16x16x32_bf16 v[106:109], v[158:161], v[216:219], v[106:109]
	v_mfma_f32_16x16x32_bf16 v[98:101], v[166:169], v[216:219], v[98:101]
	v_mfma_f32_16x16x32_bf16 v[90:93], v[158:161], v[224:227], v[90:93]
	v_mfma_f32_16x16x32_bf16 v[82:85], v[166:169], v[224:227], v[82:85]
	v_mfma_f32_16x16x32_bf16 v[74:77], v[158:161], v[232:235], v[74:77]
	v_mfma_f32_16x16x32_bf16 v[66:69], v[166:169], v[232:235], v[66:69]
	s_setprio 0
	s_setprio 1
	v_mfma_f32_16x16x32_bf16 v[126:129], v[170:173], v[204:207], v[126:129]
	v_mfma_f32_16x16x32_bf16 v[118:121], v[178:181], v[204:207], v[118:121]
	v_mfma_f32_16x16x32_bf16 v[110:113], v[170:173], v[212:215], v[110:113]
	v_mfma_f32_16x16x32_bf16 v[102:105], v[178:181], v[212:215], v[102:105]
	v_mfma_f32_16x16x32_bf16 v[94:97], v[170:173], v[220:223], v[94:97]
	v_mfma_f32_16x16x32_bf16 v[86:89], v[178:181], v[220:223], v[86:89]
	v_mfma_f32_16x16x32_bf16 v[78:81], v[170:173], v[228:231], v[78:81]
	v_mfma_f32_16x16x32_bf16 v[70:73], v[178:181], v[228:231], v[70:73]
	v_mfma_f32_16x16x32_bf16 v[126:129], v[174:177], v[208:211], v[126:129]
	v_mfma_f32_16x16x32_bf16 v[118:121], v[200:203], v[208:211], v[118:121]
	v_mfma_f32_16x16x32_bf16 v[110:113], v[174:177], v[216:219], v[110:113]
	v_mfma_f32_16x16x32_bf16 v[102:105], v[200:203], v[216:219], v[102:105]
	v_mfma_f32_16x16x32_bf16 v[94:97], v[174:177], v[224:227], v[94:97]
	v_mfma_f32_16x16x32_bf16 v[86:89], v[200:203], v[224:227], v[86:89]
	v_mfma_f32_16x16x32_bf16 v[78:81], v[174:177], v[232:235], v[78:81]
	v_mfma_f32_16x16x32_bf16 v[70:73], v[200:203], v[232:235], v[70:73]
	s_setprio 0
	s_barrier
; #define PG8_STAGE(bufoff, gbase, voff) do { _Pragma("unroll") for (int _i = 0; _i < 2; ++_i) \
;         __builtin_amdgcn_global_load_lds((const unsigned*)((const char*)(gbase) + (voff)[_i]), (PG8_LAS unsigned*)(lds + (bufoff) + ldsw + _i * 8192), 16, 0, 0); } while (0)
; #define PG8_LDA(dst, b, h) do { _Pragma("unroll") for (int m = 0; m < 4; ++m) _Pragma("unroll") for (int k = 0; k < 2; ++k) dst[m][k] = *(const PG8_LAS bf16x8*)(lds + PG8_SA(b, h) + aoff + m * 2048 + k * 1024); } while (0)
; #define PG8_MMA(ai, bj, At, Bt) do { __builtin_amdgcn_s_setprio(1); _Pragma("unroll") for (int m = 0; m < 4; ++m) _Pragma("unroll") for (int n = 0; n < 2; ++n) _Pragma("unroll") for (int k = 0; k < 2; ++k) \
;         acc[ai][bj][m][n] = __builtin_amdgcn_mfma_f32_16x16x32_bf16(Bt[n][k], At[m][k], acc[ai][bj][m][n], 0, 0, 0); __builtin_amdgcn_s_setprio(0); } while (0)
; #define PG8_WAIT_V(n) asm volatile("s_waitcnt vmcnt(" #n ")" ::: "memory")
; #define PG8_WAIT_L(n) asm volatile("s_waitcnt lgkmcnt(" #n ")" ::: "memory")
; #define PG8_BAR __builtin_amdgcn_s_barrier()
; #define PG8_SCHED __builtin_amdgcn_sched_barrier(0)
; template <class Epi, class Sched, bool ALIGN_EPI = false, bool SP2 = false>
; __device__ __forceinline__ void gemm_phase(PG8_LAS unsigned char* lds, const Gemm g, const Sched& S, const Epi& E) {
;     ...
;             PG8_LDA(At, 1, 1); PG8_STAGE(PG8_SB(1, 0), b3, voffB); PG8_STAGE(PG8_SB(1, 1), b3 + hstep, voffB); PG8_STAGE(PG8_SA(1, 0), a3, voffA);
;             PG8_WAIT_V(8); PG8_WAIT_L(0); PG8_BAR; PG8_MMA(1, 0, At, B0); PG8_MMA(1, 1, At, B1); PG8_BAR; PG8_SCHED;
	s_add_i32 s20, s56, s24
	v_lshl_add_u64 v[140:141], v[140:141], 0, s[38:39]
	s_mov_b32 m0, s20
	ds_read_b128 v[204:207], v145 offset:49152
	ds_read_b128 v[208:211], v145 offset:50176
	ds_read_b128 v[212:215], v145 offset:51200
	ds_read_b128 v[216:219], v145 offset:52224
	ds_read_b128 v[220:223], v145 offset:53248
	ds_read_b128 v[224:227], v145 offset:54272
	ds_read_b128 v[228:231], v145 offset:55296
	ds_read_b128 v[232:235], v145 offset:56320
	global_load_lds_dwordx4 v[140:141], off
	s_add_i32 m0, s20, 0x2000
	s_add_u32 s18, s18, 0x40080
	v_lshl_add_u64 v[140:141], v[146:147], 0, s[38:39]
	s_addc_u32 s19, s19, 0
	s_add_i32 s20, s57, s24
	global_load_lds_dwordx4 v[140:141], off
	v_lshl_add_u64 v[140:141], s[18:19], 0, v[0:1]
	s_mov_b32 m0, s20
	s_nop 0
	global_load_lds_dwordx4 v[140:141], off
	v_lshl_add_u64 v[140:141], s[18:19], 0, v[130:131]
	s_add_i32 m0, s20, 0x2000
	s_nop 0
	global_load_lds_dwordx4 v[140:141], off
	v_lshl_add_u64 v[140:141], v[148:149], 0, s[38:39]
	s_mov_b32 m0, s29
	s_nop 0
	global_load_lds_dwordx4 v[140:141], off
	v_lshl_add_u64 v[140:141], v[236:237], 0, s[38:39]
	s_mov_b32 m0, s30
	s_nop 0
	global_load_lds_dwordx4 v[140:141], off
	s_waitcnt vmcnt(8)
	s_waitcnt lgkmcnt(0)
	s_barrier
	s_setprio 1
	s_waitcnt lgkmcnt(0)
	v_mfma_f32_16x16x32_bf16 v[58:61], v[154:157], v[204:207], v[58:61]
	v_mfma_f32_16x16x32_bf16 v[50:53], v[162:165], v[204:207], v[50:53]
	v_mfma_f32_16x16x32_bf16 v[42:45], v[154:157], v[212:215], v[42:45]
	v_mfma_f32_16x16x32_bf16 v[34:37], v[162:165], v[212:215], v[34:37]
	v_mfma_f32_16x16x32_bf16 v[26:29], v[154:157], v[220:223], v[26:29]
	v_mfma_f32_16x16x32_bf16 v[18:21], v[162:165], v[220:223], v[18:21]
	v_mfma_f32_16x16x32_bf16 v[10:13], v[154:157], v[228:231], v[10:13]
	v_mfma_f32_16x16x32_bf16 v[2:5], v[162:165], v[228:231], v[2:5]
	v_mfma_f32_16x16x32_bf16 v[58:61], v[158:161], v[208:211], v[58:61]
	v_mfma_f32_16x16x32_bf16 v[50:53], v[166:169], v[208:211], v[50:53]
	v_mfma_f32_16x16x32_bf16 v[42:45], v[158:161], v[216:219], v[42:45]
	v_mfma_f32_16x16x32_bf16 v[34:37], v[166:169], v[216:219], v[34:37]
	v_mfma_f32_16x16x32_bf16 v[26:29], v[158:161], v[224:227], v[26:29]
	v_mfma_f32_16x16x32_bf16 v[18:21], v[166:169], v[224:227], v[18:21]
	v_mfma_f32_16x16x32_bf16 v[10:13], v[158:161], v[232:235], v[10:13]
	v_mfma_f32_16x16x32_bf16 v[2:5], v[166:169], v[232:235], v[2:5]
	s_setprio 0
	s_setprio 1
	v_mfma_f32_16x16x32_bf16 v[62:65], v[170:173], v[204:207], v[62:65]
	v_mfma_f32_16x16x32_bf16 v[54:57], v[178:181], v[204:207], v[54:57]
	v_mfma_f32_16x16x32_bf16 v[46:49], v[170:173], v[212:215], v[46:49]
	v_mfma_f32_16x16x32_bf16 v[38:41], v[178:181], v[212:215], v[38:41]
	v_mfma_f32_16x16x32_bf16 v[30:33], v[170:173], v[220:223], v[30:33]
	v_mfma_f32_16x16x32_bf16 v[22:25], v[178:181], v[220:223], v[22:25]
	v_mfma_f32_16x16x32_bf16 v[14:17], v[170:173], v[228:231], v[14:17]
	v_mfma_f32_16x16x32_bf16 v[6:9], v[178:181], v[228:231], v[6:9]
	v_mfma_f32_16x16x32_bf16 v[62:65], v[174:177], v[208:211], v[62:65]
	v_mfma_f32_16x16x32_bf16 v[54:57], v[200:203], v[208:211], v[54:57]
	v_mfma_f32_16x16x32_bf16 v[46:49], v[174:177], v[216:219], v[46:49]
	v_mfma_f32_16x16x32_bf16 v[38:41], v[200:203], v[216:219], v[38:41]
	v_mfma_f32_16x16x32_bf16 v[30:33], v[174:177], v[224:227], v[30:33]
	v_mfma_f32_16x16x32_bf16 v[22:25], v[200:203], v[224:227], v[22:25]
	v_mfma_f32_16x16x32_bf16 v[14:17], v[174:177], v[232:235], v[14:17]
	v_mfma_f32_16x16x32_bf16 v[6:9], v[200:203], v[232:235], v[6:9]
	s_setprio 0
	s_cmp_lg_u32 s55, 12
	s_cbranch_scc1 .Llb_368
	s_and_b64 vcc, exec, s[6:7]
	s_cbranch_vccz .Lnb_368

; __device__ __forceinline__ unsigned cvt_pk_bf16(float lo, float hi) { f32x2cv v = {lo, hi}; bf16x2cv b = __builtin_convertvector(v, bf16x2cv); return __builtin_bit_cast(unsigned, b); }
; #define PG8_BAR __builtin_amdgcn_s_barrier()
;     __device__ __forceinline__ void operator()(const f32x4 (&acc)[2][2][4][2], const Unit& u, int wr, int wc, int fr, int fq) const {
;         const int row0 = u.pm * BM + wr * 64 + fr; const int col0 = u.pn * HALF + wc * 32 + 8 * fq;
; #pragma unroll
;         for (int ai = 0; ai < 2; ++ai)
; #pragma unroll
;             for (int m = 0; m < 4; ++m) { bf16_t* rowp = O + (size_t)(row0 + ai * HALF + m * 16) * ldc + col0;
;                 float hv[8];
; #pragma unroll
;                 for (int n = 0; n < 2; ++n)
; #pragma unroll
;                     for (int e = 0; e < 4; ++e) { const float ag = acc[ai][0][m][n][e], au = acc[ai][1][m][n][e];
;                         hv[n * 4 + e] = ag * au * __builtin_amdgcn_rcpf(1.0f + __builtin_amdgcn_exp2f(ag)); }
;                 u32x4 w; w.x = cvt_pk_bf16(hv[0], hv[1]); w.y = cvt_pk_bf16(hv[2], hv[3]); w.z = cvt_pk_bf16(hv[4], hv[5]); w.w = cvt_pk_bf16(hv[6], hv[7]);
;                 __builtin_nontemporal_store(w, (u32x4*)rowp); }
; template <class Epi, class Sched, bool ALIGN_EPI = false, bool SP2 = false>
; __device__ __forceinline__ void gemm_phase(PG8_LAS unsigned char* lds, const Gemm g, const Sched& S, const Epi& E) {
;     ...
;         if constexpr (ALIGN_EPI) { if (wr == 0) PG8_BAR; }
;         if constexpr (!Epi::AFTER_DRAIN) { E(acc, cur, wr, wc, fr, fq); S.done(cur); }
.Lnb_368:
	s_add_i32 s55, s55, 2
	s_add_u32 s16, s16, 0x100
	s_addc_u32 s17, s17, 0
	s_add_u32 s52, s52, 0x100
	s_addc_u32 s53, s53, 0
	s_cmp_gt_u32 s55, 13
	s_cbranch_scc0 .LBB0_368
	s_and_b64 vcc, exec, s[6:7]
	s_cbranch_vccz .LBB0_371
.LBB0_371:
	v_lshl_add_u32 v140, s49, 8, v142
	v_ashrrev_i32_e32 v141, 31, v140
	v_lshlrev_b64 v[148:149], 13, v[140:141]
	v_exp_f32_e32 v141, v122
	v_pk_mul_f32 v[128:129], v[124:125], v[128:129]
	v_exp_f32_e32 v124, v124
	v_exp_f32_e32 v125, v125
	v_add_f32_e32 v141, 1.0, v141
	v_rcp_f32_e32 v154, v141
	v_exp_f32_e32 v141, v123
	v_pk_mul_f32 v[122:123], v[122:123], v[126:127]
	v_exp_f32_e32 v126, v114
	v_exp_f32_e32 v127, v115
	v_pk_mul_f32 v[114:115], v[114:115], v[118:119]
	v_add_f32_e32 v141, 1.0, v141
	v_add_f32_e32 v126, 1.0, v126
	v_add_f32_e32 v127, 1.0, v127
	v_rcp_f32_e32 v126, v126
	v_rcp_f32_e32 v127, v127
	v_add_f32_e32 v124, 1.0, v124
	v_add_f32_e32 v125, 1.0, v125
	v_rcp_f32_e32 v155, v141
	v_pk_mul_f32 v[126:127], v[126:127], v[114:115]
	v_exp_f32_e32 v114, v116
	v_exp_f32_e32 v115, v117
	v_rcp_f32_e32 v124, v124
	v_rcp_f32_e32 v125, v125
	v_add_f32_e32 v114, 1.0, v114
	v_add_f32_e32 v115, 1.0, v115
	v_rcp_f32_e32 v114, v114
	v_rcp_f32_e32 v115, v115
	v_lshl_or_b32 v146, s33, 7, v144
	v_ashrrev_i32_e32 v147, 31, v146
	v_pk_mul_f32 v[120:121], v[116:117], v[120:121]
	v_lshl_add_u64 v[148:149], s[92:93], 0, v[148:149]
	v_pk_mul_f32 v[122:123], v[154:155], v[122:123]
	v_pk_mul_f32 v[124:125], v[124:125], v[128:129]
	v_pk_mul_f32 v[128:129], v[114:115], v[120:121]
	v_lshlrev_b64 v[116:117], 1, v[146:147]
	v_lshl_add_u64 v[114:115], v[148:149], 0, v[116:117]
	v_cvt_pk_bf16_f32 v118, v122, v123
	v_cvt_pk_bf16_f32 v119, v124, v125
	v_cvt_pk_bf16_f32 v120, v126, v127
	v_cvt_pk_bf16_f32 v121, v128, v129
	global_store_dwordx4 v[114:115], v[118:121], off nt
	v_pk_mul_f32 v[112:113], v[108:109], v[112:113]
	v_exp_f32_e32 v108, v108
	v_exp_f32_e32 v120, v106
	v_exp_f32_e32 v121, v107
	v_pk_mul_f32 v[106:107], v[106:107], v[110:111]
	v_exp_f32_e32 v110, v98
	v_exp_f32_e32 v111, v99
	v_pk_mul_f32 v[98:99], v[98:99], v[102:103]
	v_exp_f32_e32 v109, v109
	v_add_f32_e32 v110, 1.0, v110
	v_add_f32_e32 v111, 1.0, v111
	v_rcp_f32_e32 v110, v110
	v_rcp_f32_e32 v111, v111
	v_add_f32_e32 v120, 1.0, v120
	v_add_f32_e32 v121, 1.0, v121
	v_add_f32_e32 v108, 1.0, v108
	v_pk_mul_f32 v[102:103], v[110:111], v[98:99]
	v_exp_f32_e32 v98, v100
	v_exp_f32_e32 v99, v101
	v_add_f32_e32 v109, 1.0, v109
	v_rcp_f32_e32 v120, v120
	v_add_f32_e32 v98, 1.0, v98
	v_add_f32_e32 v99, 1.0, v99
	v_rcp_f32_e32 v121, v121
	v_rcp_f32_e32 v108, v108
	v_rcp_f32_e32 v109, v109
	v_rcp_f32_e32 v98, v98
	v_rcp_f32_e32 v99, v99
	v_or_b32_e32 v118, 16, v140
	v_ashrrev_i32_e32 v119, 31, v118
	v_lshlrev_b64 v[118:119], 13, v[118:119]
	v_pk_mul_f32 v[104:105], v[100:101], v[104:105]
	v_lshl_add_u64 v[118:119], s[92:93], 0, v[118:119]
	v_pk_mul_f32 v[106:107], v[120:121], v[106:107]
	v_pk_mul_f32 v[108:109], v[108:109], v[112:113]
	v_pk_mul_f32 v[104:105], v[98:99], v[104:105]
	v_lshl_add_u64 v[110:111], v[118:119], 0, v[116:117]
	v_cvt_pk_bf16_f32 v98, v106, v107
	v_cvt_pk_bf16_f32 v99, v108, v109
	v_cvt_pk_bf16_f32 v100, v102, v103
	v_cvt_pk_bf16_f32 v101, v104, v105
	global_store_dwordx4 v[110:111], v[98:101], off nt
	v_pk_mul_f32 v[96:97], v[92:93], v[96:97]
	v_exp_f32_e32 v92, v92
	v_exp_f32_e32 v100, v90
	v_exp_f32_e32 v101, v91
	v_pk_mul_f32 v[90:91], v[90:91], v[94:95]
	v_exp_f32_e32 v94, v82
	v_exp_f32_e32 v95, v83
	v_pk_mul_f32 v[82:83], v[82:83], v[86:87]
	v_exp_f32_e32 v93, v93
	v_add_f32_e32 v94, 1.0, v94
	v_add_f32_e32 v95, 1.0, v95
	v_rcp_f32_e32 v94, v94
	v_rcp_f32_e32 v95, v95
	v_add_f32_e32 v100, 1.0, v100
	v_add_f32_e32 v101, 1.0, v101
	v_add_f32_e32 v92, 1.0, v92
	v_pk_mul_f32 v[86:87], v[94:95], v[82:83]
	v_exp_f32_e32 v82, v84
	v_exp_f32_e32 v83, v85
	v_add_f32_e32 v93, 1.0, v93
	v_rcp_f32_e32 v100, v100
	v_add_f32_e32 v82, 1.0, v82
	v_add_f32_e32 v83, 1.0, v83
	v_rcp_f32_e32 v101, v101
	v_rcp_f32_e32 v92, v92
	v_rcp_f32_e32 v93, v93
	v_rcp_f32_e32 v82, v82
	v_rcp_f32_e32 v83, v83
	v_or_b32_e32 v98, 32, v140
	v_ashrrev_i32_e32 v99, 31, v98
	v_lshlrev_b64 v[98:99], 13, v[98:99]
	v_pk_mul_f32 v[88:89], v[84:85], v[88:89]
	v_lshl_add_u64 v[98:99], s[92:93], 0, v[98:99]
	v_pk_mul_f32 v[90:91], v[100:101], v[90:91]
	v_pk_mul_f32 v[92:93], v[92:93], v[96:97]
	v_pk_mul_f32 v[88:89], v[82:83], v[88:89]
	v_lshl_add_u64 v[94:95], v[98:99], 0, v[116:117]
	v_cvt_pk_bf16_f32 v82, v90, v91
	v_cvt_pk_bf16_f32 v83, v92, v93
	v_cvt_pk_bf16_f32 v84, v86, v87
	v_cvt_pk_bf16_f32 v85, v88, v89
	global_store_dwordx4 v[94:95], v[82:85], off nt
	v_pk_mul_f32 v[80:81], v[76:77], v[80:81]
	v_exp_f32_e32 v76, v76
	v_exp_f32_e32 v84, v74
	v_exp_f32_e32 v85, v75
	v_pk_mul_f32 v[74:75], v[74:75], v[78:79]
	v_exp_f32_e32 v78, v66
	v_exp_f32_e32 v79, v67
	v_pk_mul_f32 v[66:67], v[66:67], v[70:71]
	v_exp_f32_e32 v77, v77
	v_add_f32_e32 v78, 1.0, v78
	v_add_f32_e32 v79, 1.0, v79
	v_rcp_f32_e32 v78, v78
	v_rcp_f32_e32 v79, v79
	v_add_f32_e32 v84, 1.0, v84
	v_add_f32_e32 v85, 1.0, v85
	v_add_f32_e32 v76, 1.0, v76
	v_pk_mul_f32 v[70:71], v[78:79], v[66:67]
	v_exp_f32_e32 v66, v68
	v_exp_f32_e32 v67, v69
	v_add_f32_e32 v77, 1.0, v77
	v_rcp_f32_e32 v84, v84
	v_add_f32_e32 v66, 1.0, v66
	v_add_f32_e32 v67, 1.0, v67
	v_rcp_f32_e32 v85, v85
	v_rcp_f32_e32 v76, v76
	v_rcp_f32_e32 v77, v77
	v_rcp_f32_e32 v66, v66
	v_rcp_f32_e32 v67, v67
	v_or_b32_e32 v82, 48, v140
	v_ashrrev_i32_e32 v83, 31, v82
	v_lshlrev_b64 v[82:83], 13, v[82:83]
; __device__ __forceinline__ unsigned cvt_pk_bf16(float lo, float hi) { f32x2cv v = {lo, hi}; bf16x2cv b = __builtin_convertvector(v, bf16x2cv); return __builtin_bit_cast(unsigned, b); }
; #define PG8_BAR __builtin_amdgcn_s_barrier()
;     __device__ __forceinline__ void operator()(const f32x4 (&acc)[2][2][4][2], const Unit& u, int wr, int wc, int fr, int fq) const {
;     ...
;             for (int m = 0; m < 4; ++m) { bf16_t* rowp = O + (size_t)(row0 + ai * HALF + m * 16) * ldc + col0;
;                 float hv[8];
; #pragma unroll
;                 for (int n = 0; n < 2; ++n)
; #pragma unroll
;                     for (int e = 0; e < 4; ++e) { const float ag = acc[ai][0][m][n][e], au = acc[ai][1][m][n][e];
;                         hv[n * 4 + e] = ag * au * __builtin_amdgcn_rcpf(1.0f + __builtin_amdgcn_exp2f(ag)); }
;                 u32x4 w; w.x = cvt_pk_bf16(hv[0], hv[1]); w.y = cvt_pk_bf16(hv[2], hv[3]); w.z = cvt_pk_bf16(hv[4], hv[5]); w.w = cvt_pk_bf16(hv[6], hv[7]);
;                 __builtin_nontemporal_store(w, (u32x4*)rowp); }
; template <class Epi, class Sched, bool ALIGN_EPI = false, bool SP2 = false>
; __device__ __forceinline__ void gemm_phase(PG8_LAS unsigned char* lds, const Gemm g, const Sched& S, const Epi& E) {
;     ...
;         if (!has_next) break;
; #pragma unroll
;         for (int a = 0; a < 2; ++a)
; #pragma unroll
;             for (int b = 0; b < 2; ++b)
; #pragma unroll
;                 for (int m = 0; m < 4; ++m)
; #pragma unroll
;                     for (int n = 0; n < 2; ++n) acc[a][b][m][n] = (f32x4){0.f, 0.f, 0.f, 0.f};
;         cur = nxt; cA = nA; cB = nB; ++ui;
;         if constexpr (ALIGN_EPI) { if (wr == 1) PG8_BAR; }
	v_pk_mul_f32 v[72:73], v[68:69], v[72:73]
	v_lshl_add_u64 v[82:83], s[92:93], 0, v[82:83]
	v_pk_mul_f32 v[74:75], v[84:85], v[74:75]
	v_pk_mul_f32 v[76:77], v[76:77], v[80:81]
	v_pk_mul_f32 v[72:73], v[66:67], v[72:73]
	v_lshl_add_u64 v[78:79], v[82:83], 0, v[116:117]
	v_cvt_pk_bf16_f32 v66, v74, v75
	v_cvt_pk_bf16_f32 v67, v76, v77
	v_cvt_pk_bf16_f32 v68, v70, v71
	v_cvt_pk_bf16_f32 v69, v72, v73
	global_store_dwordx4 v[78:79], v[66:69], off nt
	v_pk_mul_f32 v[64:65], v[60:61], v[64:65]
	v_exp_f32_e32 v60, v60
	v_exp_f32_e32 v66, v58
	v_exp_f32_e32 v67, v59
	v_pk_mul_f32 v[58:59], v[58:59], v[62:63]
	v_exp_f32_e32 v62, v50
	v_exp_f32_e32 v63, v51
	v_pk_mul_f32 v[50:51], v[50:51], v[54:55]
	v_exp_f32_e32 v61, v61
	v_add_f32_e32 v62, 1.0, v62
	v_add_f32_e32 v63, 1.0, v63
	v_rcp_f32_e32 v62, v62
	v_rcp_f32_e32 v63, v63
	v_add_f32_e32 v66, 1.0, v66
	v_add_f32_e32 v67, 1.0, v67
	v_add_f32_e32 v60, 1.0, v60
	v_pk_mul_f32 v[54:55], v[62:63], v[50:51]
	v_exp_f32_e32 v50, v52
	v_exp_f32_e32 v51, v53
	v_add_f32_e32 v61, 1.0, v61
	v_rcp_f32_e32 v66, v66
	v_add_f32_e32 v50, 1.0, v50
	v_add_f32_e32 v51, 1.0, v51
	v_rcp_f32_e32 v67, v67
	v_rcp_f32_e32 v60, v60
	v_rcp_f32_e32 v61, v61
	v_rcp_f32_e32 v50, v50
	v_rcp_f32_e32 v51, v51
	v_pk_mul_f32 v[56:57], v[52:53], v[56:57]
	s_mov_b32 s9, 0x100000
	v_pk_mul_f32 v[58:59], v[66:67], v[58:59]
	v_pk_mul_f32 v[60:61], v[60:61], v[64:65]
	v_pk_mul_f32 v[56:57], v[50:51], v[56:57]
	v_cvt_pk_bf16_f32 v52, v54, v55
	v_add_co_u32_e32 v54, vcc, s9, v114
	v_cvt_pk_bf16_f32 v50, v58, v59
	v_cvt_pk_bf16_f32 v51, v60, v61
	v_cvt_pk_bf16_f32 v53, v56, v57
	v_addc_co_u32_e32 v55, vcc, 0, v115, vcc
	global_store_dwordx4 v[54:55], v[50:53], off nt
	v_pk_mul_f32 v[48:49], v[44:45], v[48:49]
	v_exp_f32_e32 v44, v44
	v_exp_f32_e32 v50, v42
	v_exp_f32_e32 v51, v43
	v_pk_mul_f32 v[42:43], v[42:43], v[46:47]
	v_exp_f32_e32 v46, v34
	v_exp_f32_e32 v47, v35
	v_pk_mul_f32 v[34:35], v[34:35], v[38:39]
	v_exp_f32_e32 v45, v45
	v_add_f32_e32 v46, 1.0, v46
	v_add_f32_e32 v47, 1.0, v47
	v_rcp_f32_e32 v46, v46
	v_rcp_f32_e32 v47, v47
	v_add_f32_e32 v50, 1.0, v50
	v_add_f32_e32 v51, 1.0, v51
	v_add_f32_e32 v44, 1.0, v44
	v_pk_mul_f32 v[38:39], v[46:47], v[34:35]
	v_exp_f32_e32 v34, v36
	v_exp_f32_e32 v35, v37
	v_add_f32_e32 v45, 1.0, v45
	v_rcp_f32_e32 v50, v50
	v_add_f32_e32 v34, 1.0, v34
	v_add_f32_e32 v35, 1.0, v35
	v_rcp_f32_e32 v51, v51
	v_rcp_f32_e32 v44, v44
	v_rcp_f32_e32 v45, v45
	v_rcp_f32_e32 v34, v34
	v_rcp_f32_e32 v35, v35
	v_pk_mul_f32 v[40:41], v[36:37], v[40:41]
	s_mov_b32 s9, 0x120000
	v_pk_mul_f32 v[42:43], v[50:51], v[42:43]
	v_pk_mul_f32 v[44:45], v[44:45], v[48:49]
	v_pk_mul_f32 v[40:41], v[34:35], v[40:41]
	v_cvt_pk_bf16_f32 v36, v38, v39
	v_add_co_u32_e32 v38, vcc, s9, v114
	v_cvt_pk_bf16_f32 v34, v42, v43
	v_cvt_pk_bf16_f32 v35, v44, v45
	v_cvt_pk_bf16_f32 v37, v40, v41
	v_addc_co_u32_e32 v39, vcc, 0, v115, vcc
	global_store_dwordx4 v[38:39], v[34:37], off nt
	v_pk_mul_f32 v[32:33], v[28:29], v[32:33]
	v_exp_f32_e32 v28, v28
	v_exp_f32_e32 v34, v26
	v_exp_f32_e32 v35, v27
	v_pk_mul_f32 v[26:27], v[26:27], v[30:31]
	v_exp_f32_e32 v30, v18
	v_exp_f32_e32 v31, v19
	v_pk_mul_f32 v[18:19], v[18:19], v[22:23]
	v_exp_f32_e32 v29, v29
	v_add_f32_e32 v30, 1.0, v30
	v_add_f32_e32 v31, 1.0, v31
	v_rcp_f32_e32 v30, v30
	v_rcp_f32_e32 v31, v31
	v_add_f32_e32 v34, 1.0, v34
	v_add_f32_e32 v35, 1.0, v35
	v_add_f32_e32 v28, 1.0, v28
	v_pk_mul_f32 v[22:23], v[30:31], v[18:19]
	v_exp_f32_e32 v18, v20
	v_exp_f32_e32 v19, v21
	v_add_f32_e32 v29, 1.0, v29
	v_rcp_f32_e32 v34, v34
	v_add_f32_e32 v18, 1.0, v18
	v_add_f32_e32 v19, 1.0, v19
	v_rcp_f32_e32 v35, v35
	v_rcp_f32_e32 v28, v28
	v_rcp_f32_e32 v29, v29
	v_rcp_f32_e32 v18, v18
	v_rcp_f32_e32 v19, v19
	v_pk_mul_f32 v[24:25], v[20:21], v[24:25]
	s_mov_b32 s9, 0x140000
	v_pk_mul_f32 v[26:27], v[34:35], v[26:27]
	v_pk_mul_f32 v[28:29], v[28:29], v[32:33]
	v_pk_mul_f32 v[24:25], v[18:19], v[24:25]
	v_cvt_pk_bf16_f32 v20, v22, v23
	v_add_co_u32_e32 v22, vcc, s9, v114
	v_cvt_pk_bf16_f32 v18, v26, v27
	v_cvt_pk_bf16_f32 v19, v28, v29
	v_cvt_pk_bf16_f32 v21, v24, v25
	v_addc_co_u32_e32 v23, vcc, 0, v115, vcc
	global_store_dwordx4 v[22:23], v[18:21], off nt
	v_pk_mul_f32 v[16:17], v[12:13], v[16:17]
	v_exp_f32_e32 v12, v12
	v_exp_f32_e32 v18, v10
	v_exp_f32_e32 v19, v11
	v_pk_mul_f32 v[10:11], v[10:11], v[14:15]
	v_exp_f32_e32 v14, v2
	v_exp_f32_e32 v15, v3
	v_pk_mul_f32 v[2:3], v[2:3], v[6:7]
	v_exp_f32_e32 v13, v13
	v_add_f32_e32 v14, 1.0, v14
	v_add_f32_e32 v15, 1.0, v15
	v_rcp_f32_e32 v14, v14
	v_rcp_f32_e32 v15, v15
	v_add_f32_e32 v18, 1.0, v18
	v_add_f32_e32 v19, 1.0, v19
	v_add_f32_e32 v12, 1.0, v12
	v_pk_mul_f32 v[6:7], v[14:15], v[2:3]
	v_exp_f32_e32 v2, v4
	v_exp_f32_e32 v3, v5
	v_add_f32_e32 v13, 1.0, v13
	v_rcp_f32_e32 v18, v18
	v_add_f32_e32 v2, 1.0, v2
	v_add_f32_e32 v3, 1.0, v3
	v_rcp_f32_e32 v19, v19
	v_rcp_f32_e32 v12, v12
	v_rcp_f32_e32 v13, v13
	v_rcp_f32_e32 v2, v2
	v_rcp_f32_e32 v3, v3
	v_pk_mul_f32 v[8:9], v[4:5], v[8:9]
	v_cvt_pk_bf16_f32 v4, v6, v7
	v_add_co_u32_e32 v6, vcc, 0x160000, v114
	v_pk_mul_f32 v[10:11], v[18:19], v[10:11]
	v_pk_mul_f32 v[12:13], v[12:13], v[16:17]
	v_pk_mul_f32 v[8:9], v[2:3], v[8:9]
	v_addc_co_u32_e32 v7, vcc, 0, v115, vcc
	v_cvt_pk_bf16_f32 v2, v10, v11
	v_cvt_pk_bf16_f32 v3, v12, v13
	v_cvt_pk_bf16_f32 v5, v8, v9
	s_mov_b64 s[16:17], -1
	s_andn2_b64 vcc, exec, s[4:5]
	global_store_dwordx4 v[6:7], v[2:5], off nt
	s_cbranch_vccnz .LBB0_360
	s_andn2_b64 vcc, exec, s[0:1]
	s_cbranch_vccnz .LBB0_359
	s_branch .LBB0_359

; #define PG8_STAGE(bufoff, gbase, voff) do { _Pragma("unroll") for (int _i = 0; _i < 2; ++_i) \
;         __builtin_amdgcn_global_load_lds((const unsigned*)((const char*)(gbase) + (voff)[_i]), (PG8_LAS unsigned*)(lds + (bufoff) + ldsw + _i * 8192), 16, 0, 0); } while (0)
; #define PG8_WAIT_V(n) asm volatile("s_waitcnt vmcnt(" #n ")" ::: "memory")
; #define PG8_BAR __builtin_amdgcn_s_barrier()
; template <class Epi, class Sched, bool ALIGN_EPI = false, bool SP2 = false>
; __device__ __forceinline__ void gemm_phase(PG8_LAS unsigned char* lds, const Gemm g, const Sched& S, const Epi& E) {
;     ...
;     const int tid = tid_, wid = __builtin_amdgcn_readfirstlane(tid >> 6), lane = tid & 63, wr = wid >> 2, wc = wid & 3, fr = lane & 15, fq = lane >> 4;
;     const int K = g.K, nt = K / BK;
;     unsigned voffA[2], voffB[2];
; #pragma unroll
;     for (int i = 0; i < 2; ++i) { int R, C; stage_rc(tid * 16 + i * 8192, R, C); const int Rb = Epi::PERM ? ((R & ~31) + perm32(R & 31)) : R;
;         voffA[i] = (unsigned)(R * K + C) * 2u; voffB[i] = (unsigned)(Rb * K + C) * 2u; }
;     const size_t kstep = (size_t)(BK * 2);
;     const size_t hstep = (size_t)HALF * K * 2;
;     const size_t tstep = 2 * hstep;
;     const unsigned ldsw = (unsigned)wid * 1024u;
;     const int aoff = lds_byte(wr * 64 + fr, fq * 8), boff = lds_byte(wc * 32 + fr, fq * 8);
;     ...
;     Unit cur, nxt; int ui = 0;
;     if (!S.next(0, cur)) return;
;     f32x4 acc[2][2][4][2];
; #pragma unroll
;     for (int a = 0; a < 2; ++a)
; #pragma unroll
;         for (int b = 0; b < 2; ++b)
; #pragma unroll
;             for (int m = 0; m < 4; ++m)
; #pragma unroll
;                 for (int n = 0; n < 2; ++n) acc[a][b][m][n] = (f32x4){0.f, 0.f, 0.f, 0.f};
;     bf16x8 At[4][2], B0[2][2], B1[2][2];
;     const char* cA = (const char*)g.A + (size_t)cur.pm * tstep; const char* cB = (const char*)g.Bt + (size_t)cur.pn * tstep;
;     S.a_ready(cur);
;     if constexpr (SP2) {
;         PG8_STAGE(PG8_SB(0, 0), cB, voffB); PG8_STAGE(PG8_SB(0, 1), cB + hstep, voffB); PG8_STAGE(PG8_SA(0, 0), cA, voffA); PG8_STAGE(PG8_SA(0, 1), cA + hstep, voffA);
;         if (wr == 1) PG8_BAR;
;         PG8_WAIT_V(2); PG8_BAR;
;         PG8_STAGE(PG8_SB(1, 0), cB + kstep, voffB); PG8_STAGE(PG8_SA(1, 0), cA + kstep, voffA); PG8_STAGE(PG8_SB(1, 1), cB + hstep + kstep, voffB);
;         PG8_WAIT_V(6); PG8_BAR;
.LBB0_419:
	s_or_b64 exec, exec, s[50:51]
	v_readlane_b32 s0, v253, 27
	v_mov_b32_e32 v12, v182
	v_readlane_b32 s1, v253, 28
	s_waitcnt lgkmcnt(0)
	s_barrier
	s_andn2_b64 vcc, exec, s[0:1]
	v_readfirstlane_b32 s4, v12
	s_cbranch_vccnz .LBB0_503
	v_lshlrev_b32_e32 v0, 4, v12
	v_add_u32_e32 v2, 0x2000, v0
	v_ashrrev_i32_e32 v3, 31, v2
	v_lshrrev_b32_e32 v3, 22, v3
	v_add_u32_e32 v3, v2, v3
	v_ashrrev_i32_e32 v6, 10, v3
	v_mul_i32_i24_e32 v3, 0x400, v6
	v_sub_u32_e32 v2, v2, v3
	v_lshrrev_b32_e32 v3, 4, v2
	v_bitop3_b32 v2, v3, v2, 32 bitop3:0x6c
	v_ashrrev_i32_e32 v3, 31, v2
	v_lshrrev_b32_e32 v3, 26, v3
	v_add_u32_e32 v3, v2, v3
	v_lshlrev_b32_e32 v4, 3, v6
	s_lshl_b32 s0, s48, 23
	v_readlane_b32 s1, v253, 25
	v_ashrrev_i32_e32 v7, 6, v3
	v_and_b32_e32 v4, -16, v4
	s_add_u32 s22, s1, s0
	v_readlane_b32 s0, v253, 26
	v_add_u32_e32 v4, v7, v4
	s_addc_u32 s23, s0, 0
	v_and_b32_e32 v5, 3, v7
	s_mov_b32 s0, 0x7ffe0
	v_lshrrev_b32_e32 v8, 2, v4
	v_lshlrev_b32_e32 v9, 1, v4
	v_and_b32_e32 v3, 0xc0, v3
	v_and_or_b32 v5, v4, s0, v5
	v_and_b32_e32 v8, 4, v8
	v_and_b32_e32 v9, 24, v9
	v_sub_u32_e32 v2, v2, v3
	v_or3_b32 v5, v5, v8, v9
	v_lshlrev_b32_e32 v8, 5, v6
	v_ashrrev_i16_sdwa v2, v184, sext(v2) dst_sel:DWORD dst_unused:UNUSED_PAD src0_sel:DWORD src1_sel:BYTE_0
	v_and_b32_e32 v9, 32, v8
	v_bfe_i32 v8, v2, 0, 16
	v_add_lshl_u32 v2, v9, v8, 1
	v_lshl_add_u32 v154, v5, 13, v2
	v_lshl_add_u32 v156, v4, 13, v2
	v_bfe_i32 v2, v12, 27, 1
	v_lshrrev_b32_e32 v2, 22, v2
	v_add_u32_e32 v2, v0, v2
	v_and_b32_e32 v2, 0xfffffc00, v2
	v_sub_u32_e32 v0, v0, v2
	v_lshrrev_b32_e32 v2, 4, v0
	v_ashrrev_i32_e32 v3, 31, v12
	v_bitop3_b32 v0, v2, v0, 32 bitop3:0x6c
	v_lshrrev_b32_e32 v3, 26, v3
	v_ashrrev_i32_e32 v2, 31, v0
	v_add_u32_e32 v3, v12, v3
	v_lshrrev_b32_e32 v2, 26, v2
	v_ashrrev_i32_e32 v10, 6, v3
	v_add_u32_e32 v2, v0, v2
	v_lshlrev_b32_e32 v3, 3, v10
	v_ashrrev_i32_e32 v9, 6, v2
	v_and_b32_e32 v3, -16, v3
	v_add_u32_e32 v3, v9, v3
	v_and_b32_e32 v4, 3, v9
	v_lshrrev_b32_e32 v5, 2, v3
	v_lshlrev_b32_e32 v11, 1, v3
	v_and_b32_e32 v2, 0xc0, v2
	s_ashr_i32 s5, s4, 6
	v_and_or_b32 v4, v3, s0, v4
	v_and_b32_e32 v5, 4, v5
	v_and_b32_e32 v11, 24, v11
	v_sub_u32_e32 v0, v0, v2
	s_ashr_i32 s6, s4, 8
	s_lshl_b32 s24, s5, 10
	v_or3_b32 v4, v4, v5, v11
	v_lshlrev_b32_e32 v5, 5, v10
	v_ashrrev_i16_sdwa v0, v184, sext(v0) dst_sel:DWORD dst_unused:UNUSED_PAD src0_sel:DWORD src1_sel:BYTE_0
	v_readlane_b32 s0, v254, 14
	v_and_b32_e32 v5, 32, v5
	v_bfe_i32 v11, v0, 0, 16
	v_readlane_b32 s1, v254, 15
	s_add_u32 s18, s22, s0
	v_add_lshl_u32 v2, v5, v11, 1
	s_addc_u32 s19, s23, s1
	s_add_i32 s25, s24, 0
	v_lshl_add_u32 v0, v4, 13, v2
	s_add_i32 m0, s25, 0x10000
	v_lshl_add_u32 v158, v3, 13, v2
	global_load_lds_dwordx4 v0, s[18:19]
	s_add_i32 m0, s25, 0x12000
	s_add_u32 s0, s18, 0x100000
	global_load_lds_dwordx4 v154, s[18:19]
	s_addc_u32 s1, s19, 0
	s_add_i32 m0, s25, 0x14000
	s_add_i32 s26, s25, 0x2000
	global_load_lds_dwordx4 v0, s[0:1]
	s_add_i32 m0, s25, 0x16000
	s_add_i32 s27, s25, 0x4000
	global_load_lds_dwordx4 v154, s[0:1]
	v_readlane_b32 s0, v254, 19
	s_mov_b32 m0, s25
	v_readlane_b32 s1, v254, 20
	s_add_i32 s28, s25, 0x6000
	v_mov_b32_e32 v155, v1
	s_cmp_eq_u32 s6, 1
	v_lshl_add_u64 v[2:3], s[18:19], 0, v[0:1]
	v_lshl_add_u64 v[4:5], s[18:19], 0, v[154:155]
	global_load_lds_dwordx4 v158, s[0:1]
	s_mov_b32 m0, s26
	v_readlane_b32 s7, v255, 2
	global_load_lds_dwordx4 v156, s[0:1]
	v_readlane_b32 s0, v254, 21
	s_mov_b32 m0, s27
	v_readlane_b32 s1, v254, 22
	v_readlane_b32 s10, v255, 3
	s_nop 3
	global_load_lds_dwordx4 v158, s[0:1]
	s_mov_b32 m0, s28
	s_nop 0
	global_load_lds_dwordx4 v156, s[0:1]
	s_cselect_b64 s[0:1], -1, 0
	s_cmp_lg_u32 s6, 1
	s_cbranch_scc1 .LBB0_422
.LBB0_422:
	s_mul_i32 s86, s54, 0xc00
	s_lshl_b64 s[8:9], s[86:87], 2
	s_add_u32 s7, s7, s8
	s_addc_u32 s8, s10, s9
	v_lshrrev_b32_e32 v18, 1, v12
	s_add_u32 s29, s7, 0x2000
	v_and_b32_e32 v18, 24, v18
	v_readlane_b32 s16, v254, 19
	s_addc_u32 s30, s8, 0
	v_and_b32_e32 v13, 15, v12
	v_lshlrev_b32_e32 v19, 1, v18
	v_lshlrev_b32_e32 v12, 2, v12
	s_lshl_b32 s5, s5, 5
	v_mov_b32_e32 v159, v1
	v_readlane_b32 s17, v254, 20
	v_lshl_or_b32 v200, s6, 6, v13
	v_lshl_or_b32 v13, v13, 6, v19
	s_lshl_b32 s6, s6, 13
	v_and_b32_e32 v12, 32, v12
	s_and_b32 s5, s5, 0x60
	s_add_i32 m0, s25, 0x18000
	v_lshl_add_u64 v[2:3], v[2:3], 0, s[38:39]
	v_lshl_add_u64 v[14:15], s[16:17], 0, v[158:159]
	v_mov_b32_e32 v157, v1
	v_bitop3_b32 v19, v13, s6, v12 bitop3:0xde
	s_lshl_b32 s6, s5, 7
	s_waitcnt vmcnt(2)
	s_barrier
	global_load_lds_dwordx4 v[2:3], off
	v_lshl_add_u64 v[2:3], v[4:5], 0, s[38:39]
	s_add_i32 m0, s25, 0x1a000
	s_add_i32 s31, s25, 0x8000
	s_add_i32 s33, s25, 0xa000
	v_lshl_add_u64 v[16:17], s[16:17], 0, v[156:157]
	v_bitop3_b32 v201, v13, s6, v12 bitop3:0xde
	global_load_lds_dwordx4 v[2:3], off
	v_lshl_add_u64 v[2:3], v[14:15], 0, s[38:39]
	s_mov_b32 m0, s31
	s_add_u32 s6, s18, 0x100080
	global_load_lds_dwordx4 v[2:3], off
	v_lshl_add_u64 v[2:3], v[16:17], 0, s[38:39]
	s_mov_b32 m0, s33
	s_addc_u32 s7, s19, 0
	global_load_lds_dwordx4 v[2:3], off
	s_add_i32 m0, s25, 0x1c000
	v_lshl_add_u64 v[2:3], s[6:7], 0, v[0:1]
	global_load_lds_dwordx4 v[2:3], off
	v_lshl_add_u64 v[2:3], s[6:7], 0, v[154:155]
	s_add_i32 m0, s25, 0x1e000
	s_cmpk_lt_u32 s4, 0x100
	global_load_lds_dwordx4 v[2:3], off
	v_lshlrev_b32_e32 v2, 16, v10
	v_and_b32_e32 v2, 0xfffe0000, v2
	v_lshl_add_u32 v2, v9, 13, v2
	v_and_b32_e32 v3, 1, v10
	v_lshl_or_b32 v2, v3, 6, v2
	v_lshl_add_u32 v160, v11, 1, v2
	v_lshlrev_b32_e32 v2, 16, v6
	v_and_b32_e32 v2, 0xfffe0000, v2
	s_waitcnt vmcnt(6)
	v_lshl_add_u32 v2, v7, 13, v2
	v_and_b32_e32 v3, 1, v6
	v_or_b32_e32 v202, s5, v18
	v_lshl_or_b32 v2, v3, 6, v2
	v_readlane_b32 s4, v254, 16
	s_cselect_b64 s[6:7], -1, 0
	v_mov_b32_e32 v161, v1
	v_lshl_add_u32 v162, v8, 1, v2
	v_mov_b32_e32 v163, v1
	s_mov_b32 s48, 0
	v_add_u32_e32 v203, 0, v19
	v_readlane_b32 s50, v254, 7
	s_mov_b32 s49, s4
	s_barrier
	v_readlane_b32 s5, v254, 17
	s_waitcnt vmcnt(0)
	s_branch .LBB0_425

; #define PG8_STAGE(bufoff, gbase, voff) do { _Pragma("unroll") for (int _i = 0; _i < 2; ++_i) \
;         __builtin_amdgcn_global_load_lds((const unsigned*)((const char*)(gbase) + (voff)[_i]), (PG8_LAS unsigned*)(lds + (bufoff) + ldsw + _i * 8192), 16, 0, 0); } while (0)
; #define PG8_LDA(dst, b, h) do { _Pragma("unroll") for (int m = 0; m < 4; ++m) _Pragma("unroll") for (int k = 0; k < 2; ++k) dst[m][k] = *(const PG8_LAS bf16x8*)(lds + PG8_SA(b, h) + aoff + m * 2048 + k * 1024); } while (0)
; #define PG8_LDB(dst, b, h) do { _Pragma("unroll") for (int n = 0; n < 2; ++n) _Pragma("unroll") for (int k = 0; k < 2; ++k) dst[n][k] = *(const PG8_LAS bf16x8*)(lds + PG8_SB(b, h) + boff + n * 2048 + k * 1024); } while (0)
; #define PG8_WAIT_V(n) asm volatile("s_waitcnt vmcnt(" #n ")" ::: "memory")
; #define PG8_WAIT_L(n) asm volatile("s_waitcnt lgkmcnt(" #n ")" ::: "memory")
; #define PG8_BAR __builtin_amdgcn_s_barrier()
; #define PG8_SCHED __builtin_amdgcn_sched_barrier(0)
; template <class Epi, class Sched, bool ALIGN_EPI = false, bool SP2 = false>
; __device__ __forceinline__ void gemm_phase(PG8_LAS unsigned char* lds, const Gemm g, const Sched& S, const Epi& E) {
;     ...
;         const bool has_next = S.next(ui + 1, nxt);
;         const char* nA = has_next ? (const char*)g.A + (size_t)nxt.pm * tstep : cA; const char* nB = has_next ? (const char*)g.Bt + (size_t)nxt.pn * tstep : cB;
;         for (int t = 0; t < nt; t += 2) {
;             const bool last = (t == nt - 2);
;             const char* a1 = cA + (size_t)(t + 1) * kstep;
;             const char* a2 = last ? nA : cA + (size_t)(t + 2) * kstep; const char* b2 = last ? nB : cB + (size_t)(t + 2) * kstep;
;             const char* a3 = a2 + kstep; const char* b3 = b2 + kstep;
;             if (last && has_next) S.a_ready(nxt);
;             if constexpr (SP2) {
;             PG8_LDB(B0, 0, 0); PG8_LDB(B1, 0, 1); PG8_SCHED; PG8_LDA(At, 0, 0); PG8_STAGE(PG8_SA(1, 1), a1 + hstep, voffA);
;             PG8_WAIT_V(8); PG8_WAIT_L(0); PG8_BAR; PG8_MMA(0, 0, At, B0); PG8_MMA(0, 1, At, B1); PG8_BAR; PG8_SCHED;
;             PG8_LDA(At, 0, 1); PG8_STAGE(PG8_SB(0, 0), b2, voffB); PG8_STAGE(PG8_SB(0, 1), b2 + hstep, voffB); PG8_STAGE(PG8_SA(0, 0), a2, voffA);
;             PG8_WAIT_V(8); PG8_WAIT_L(0); PG8_BAR; PG8_MMA(1, 0, At, B0); PG8_MMA(1, 1, At, B1); PG8_BAR; PG8_SCHED;
.LBB0_431:
	s_ashr_i32 s11, s10, 31
	s_lshl_b64 s[12:13], s[10:11], 21
	s_add_u32 s12, s92, s12
	s_addc_u32 s13, s93, s13
	s_and_b64 s[14:15], s[4:5], exec
	s_cselect_b32 s11, s13, s17
	s_cselect_b32 s51, s12, s16
	s_ashr_i32 s9, s8, 31
	s_lshl_b64 s[14:15], s[8:9], 21
	s_add_u32 s14, s22, s14
	s_addc_u32 s15, s23, s15
	s_and_b64 s[20:21], s[4:5], exec
	s_cselect_b32 s9, s15, s19
	s_cselect_b32 s52, s14, s18
	s_add_u32 s16, s16, 0x100080
	s_addc_u32 s17, s17, 0
	s_add_u32 s53, s18, 0x100
	s_addc_u32 s54, s19, 0
	s_mov_b32 s55, -2
	s_add_u32 s18, s16, 0xfff00080
	s_addc_u32 s19, s17, -1
	s_add_i32 s56, 0, 0x10000
	s_cmp_eq_u32 s55, 60
	s_cselect_b32 s21, s11, s19
	s_cselect_b32 s20, s51, s18
	s_cselect_b32 s19, s9, s54
	s_cselect_b32 s18, s52, s53
	s_add_i32 s58, 0, 0x14000
	v_add_u32_e32 v142, s56, v201
	v_add_u32_e32 v146, s58, v201
	ds_read_b128 v[130:133], v142
	ds_read_b128 v[134:137], v142 offset:1024
	ds_read_b128 v[138:141], v142 offset:2048
	ds_read_b128 v[142:145], v142 offset:3072
	ds_read_b128 v[164:167], v146
	ds_read_b128 v[168:171], v146 offset:1024
	ds_read_b128 v[172:175], v146 offset:2048
	ds_read_b128 v[176:179], v146 offset:3072
	v_lshl_add_u64 v[146:147], s[16:17], 0, v[160:161]
	s_add_i32 m0, s25, 0xc000
	ds_read_b128 v[204:207], v203
	ds_read_b128 v[208:211], v203 offset:1024
	ds_read_b128 v[212:215], v203 offset:2048
	ds_read_b128 v[216:219], v203 offset:3072
	ds_read_b128 v[220:223], v203 offset:4096
	ds_read_b128 v[224:227], v203 offset:5120
	ds_read_b128 v[228:231], v203 offset:6144
	ds_read_b128 v[232:235], v203 offset:7168
	global_load_lds_dwordx4 v[146:147], off
	v_lshl_add_u64 v[146:147], s[16:17], 0, v[162:163]
	s_add_i32 m0, s25, 0xe000
	s_nop 0
	global_load_lds_dwordx4 v[146:147], off
	s_waitcnt vmcnt(20)
	s_waitcnt lgkmcnt(0)
	s_and_b64 vcc, exec, s[6:7]
	s_cbranch_vccnz .Lpe_432
	s_barrier
.Lpe_432:
	s_setprio 1
	s_waitcnt lgkmcnt(0)
	v_mfma_f32_16x16x32_bf16 v[126:129], v[130:133], v[204:207], 0
	v_mfma_f32_16x16x32_bf16 v[122:125], v[138:141], v[204:207], 0
	v_mfma_f32_16x16x32_bf16 v[118:121], v[130:133], v[212:215], 0
	v_mfma_f32_16x16x32_bf16 v[114:117], v[138:141], v[212:215], 0
	v_mfma_f32_16x16x32_bf16 v[110:113], v[130:133], v[220:223], 0
	v_mfma_f32_16x16x32_bf16 v[106:109], v[138:141], v[220:223], 0
	v_mfma_f32_16x16x32_bf16 v[102:105], v[130:133], v[228:231], 0
	v_mfma_f32_16x16x32_bf16 v[98:101], v[138:141], v[228:231], 0
	v_mfma_f32_16x16x32_bf16 v[126:129], v[134:137], v[208:211], v[126:129]
	v_mfma_f32_16x16x32_bf16 v[122:125], v[142:145], v[208:211], v[122:125]
	v_mfma_f32_16x16x32_bf16 v[118:121], v[134:137], v[216:219], v[118:121]
	v_mfma_f32_16x16x32_bf16 v[114:117], v[142:145], v[216:219], v[114:117]
	v_mfma_f32_16x16x32_bf16 v[110:113], v[134:137], v[224:227], v[110:113]
	v_mfma_f32_16x16x32_bf16 v[106:109], v[142:145], v[224:227], v[106:109]
	v_mfma_f32_16x16x32_bf16 v[102:105], v[134:137], v[232:235], v[102:105]
	v_mfma_f32_16x16x32_bf16 v[98:101], v[142:145], v[232:235], v[98:101]
	s_setprio 0
	s_setprio 1
	v_mfma_f32_16x16x32_bf16 v[62:65], v[164:167], v[204:207], 0
	v_mfma_f32_16x16x32_bf16 v[58:61], v[172:175], v[204:207], 0
	v_mfma_f32_16x16x32_bf16 v[54:57], v[164:167], v[212:215], 0
	v_mfma_f32_16x16x32_bf16 v[50:53], v[172:175], v[212:215], 0
	v_mfma_f32_16x16x32_bf16 v[46:49], v[164:167], v[220:223], 0
	v_mfma_f32_16x16x32_bf16 v[42:45], v[172:175], v[220:223], 0
	v_mfma_f32_16x16x32_bf16 v[38:41], v[164:167], v[228:231], 0
	v_mfma_f32_16x16x32_bf16 v[34:37], v[172:175], v[228:231], 0
	v_mfma_f32_16x16x32_bf16 v[62:65], v[168:171], v[208:211], v[62:65]
	v_mfma_f32_16x16x32_bf16 v[58:61], v[176:179], v[208:211], v[58:61]
	v_mfma_f32_16x16x32_bf16 v[54:57], v[168:171], v[216:219], v[54:57]
	v_mfma_f32_16x16x32_bf16 v[50:53], v[176:179], v[216:219], v[50:53]
	v_mfma_f32_16x16x32_bf16 v[46:49], v[168:171], v[224:227], v[46:49]
	v_mfma_f32_16x16x32_bf16 v[42:45], v[176:179], v[224:227], v[42:45]
	v_mfma_f32_16x16x32_bf16 v[38:41], v[168:171], v[232:235], v[38:41]
	v_mfma_f32_16x16x32_bf16 v[34:37], v[176:179], v[232:235], v[34:37]
	s_setprio 0
	s_barrier
	s_add_i32 s56, s56, s24
	v_lshl_add_u64 v[146:147], s[18:19], 0, v[0:1]
	s_mov_b32 m0, s56
	ds_read_b128 v[204:207], v203 offset:16384
	ds_read_b128 v[208:211], v203 offset:17408
	ds_read_b128 v[212:215], v203 offset:18432
	ds_read_b128 v[216:219], v203 offset:19456
	ds_read_b128 v[220:223], v203 offset:20480
	ds_read_b128 v[224:227], v203 offset:21504
	ds_read_b128 v[228:231], v203 offset:22528
	ds_read_b128 v[232:235], v203 offset:23552
	global_load_lds_dwordx4 v[146:147], off
	s_add_i32 m0, s56, 0x2000
	s_add_u32 s56, s18, 0x100000
	v_lshl_add_u64 v[148:149], s[18:19], 0, v[154:155]
	s_addc_u32 s57, s19, 0
	s_add_i32 s58, s58, s24
	global_load_lds_dwordx4 v[148:149], off
	v_lshl_add_u64 v[180:181], s[56:57], 0, v[0:1]
	s_mov_b32 m0, s58
	v_lshl_add_u64 v[236:237], s[20:21], 0, v[156:157]
	global_load_lds_dwordx4 v[180:181], off
	v_lshl_add_u64 v[180:181], s[56:57], 0, v[154:155]
	s_add_i32 m0, s58, 0x2000
	s_nop 0
	global_load_lds_dwordx4 v[180:181], off
	v_lshl_add_u64 v[180:181], s[20:21], 0, v[158:159]
	s_mov_b32 m0, s25
	s_nop 0
	global_load_lds_dwordx4 v[180:181], off
	s_mov_b32 m0, s26
	s_nop 0
	global_load_lds_dwordx4 v[236:237], off
	s_waitcnt vmcnt(20)
	s_waitcnt lgkmcnt(0)
	s_barrier
; #define PG8_STAGE(bufoff, gbase, voff) do { _Pragma("unroll") for (int _i = 0; _i < 2; ++_i) \
;         __builtin_amdgcn_global_load_lds((const unsigned*)((const char*)(gbase) + (voff)[_i]), (PG8_LAS unsigned*)(lds + (bufoff) + ldsw + _i * 8192), 16, 0, 0); } while (0)
; #define PG8_LDA(dst, b, h) do { _Pragma("unroll") for (int m = 0; m < 4; ++m) _Pragma("unroll") for (int k = 0; k < 2; ++k) dst[m][k] = *(const PG8_LAS bf16x8*)(lds + PG8_SA(b, h) + aoff + m * 2048 + k * 1024); } while (0)
; #define PG8_LDB(dst, b, h) do { _Pragma("unroll") for (int n = 0; n < 2; ++n) _Pragma("unroll") for (int k = 0; k < 2; ++k) dst[n][k] = *(const PG8_LAS bf16x8*)(lds + PG8_SB(b, h) + boff + n * 2048 + k * 1024); } while (0)
; #define PG8_MMA(ai, bj, At, Bt) do { __builtin_amdgcn_s_setprio(1); _Pragma("unroll") for (int m = 0; m < 4; ++m) _Pragma("unroll") for (int n = 0; n < 2; ++n) _Pragma("unroll") for (int k = 0; k < 2; ++k) \
;         acc[ai][bj][m][n] = __builtin_amdgcn_mfma_f32_16x16x32_bf16(Bt[n][k], At[m][k], acc[ai][bj][m][n], 0, 0, 0); __builtin_amdgcn_s_setprio(0); } while (0)
; #define PG8_WAIT_V(n) asm volatile("s_waitcnt vmcnt(" #n ")" ::: "memory")
; #define PG8_WAIT_L(n) asm volatile("s_waitcnt lgkmcnt(" #n ")" ::: "memory")
; #define PG8_BAR __builtin_amdgcn_s_barrier()
; #define PG8_SCHED __builtin_amdgcn_sched_barrier(0)
; template <class Epi, class Sched, bool ALIGN_EPI = false, bool SP2 = false>
; __device__ __forceinline__ void gemm_phase(PG8_LAS unsigned char* lds, const Gemm g, const Sched& S, const Epi& E) {
;     ...
;             PG8_WAIT_V(8); PG8_WAIT_L(0); PG8_BAR; PG8_MMA(1, 0, At, B0); PG8_MMA(1, 1, At, B1); PG8_BAR; PG8_SCHED;
;             PG8_LDB(B0, 1, 0); PG8_LDB(B1, 1, 1); PG8_SCHED; PG8_LDA(At, 1, 0); PG8_STAGE(PG8_SA(0, 1), a2 + hstep, voffA);
;             PG8_WAIT_V(8); PG8_WAIT_L(0); PG8_BAR; PG8_MMA(0, 0, At, B0); PG8_MMA(0, 1, At, B1); PG8_BAR; PG8_SCHED;
	s_setprio 1
	s_waitcnt lgkmcnt(0)
	v_mfma_f32_16x16x32_bf16 v[94:97], v[130:133], v[204:207], 0
	v_mfma_f32_16x16x32_bf16 v[90:93], v[138:141], v[204:207], 0
	v_mfma_f32_16x16x32_bf16 v[86:89], v[130:133], v[212:215], 0
	v_mfma_f32_16x16x32_bf16 v[82:85], v[138:141], v[212:215], 0
	v_mfma_f32_16x16x32_bf16 v[78:81], v[130:133], v[220:223], 0
	v_mfma_f32_16x16x32_bf16 v[74:77], v[138:141], v[220:223], 0
	v_mfma_f32_16x16x32_bf16 v[70:73], v[130:133], v[228:231], 0
	v_mfma_f32_16x16x32_bf16 v[66:69], v[138:141], v[228:231], 0
	v_mfma_f32_16x16x32_bf16 v[94:97], v[134:137], v[208:211], v[94:97]
	v_mfma_f32_16x16x32_bf16 v[90:93], v[142:145], v[208:211], v[90:93]
	v_mfma_f32_16x16x32_bf16 v[86:89], v[134:137], v[216:219], v[86:89]
	v_mfma_f32_16x16x32_bf16 v[82:85], v[142:145], v[216:219], v[82:85]
	v_mfma_f32_16x16x32_bf16 v[78:81], v[134:137], v[224:227], v[78:81]
	v_mfma_f32_16x16x32_bf16 v[74:77], v[142:145], v[224:227], v[74:77]
	v_mfma_f32_16x16x32_bf16 v[70:73], v[134:137], v[232:235], v[70:73]
	v_mfma_f32_16x16x32_bf16 v[66:69], v[142:145], v[232:235], v[66:69]
	s_setprio 0
	s_setprio 1
	v_mfma_f32_16x16x32_bf16 v[30:33], v[164:167], v[204:207], 0
	v_mfma_f32_16x16x32_bf16 v[26:29], v[172:175], v[204:207], 0
	v_mfma_f32_16x16x32_bf16 v[22:25], v[164:167], v[212:215], 0
	v_mfma_f32_16x16x32_bf16 v[18:21], v[172:175], v[212:215], 0
	v_mfma_f32_16x16x32_bf16 v[14:17], v[164:167], v[220:223], 0
	v_mfma_f32_16x16x32_bf16 v[10:13], v[172:175], v[220:223], 0
	v_mfma_f32_16x16x32_bf16 v[6:9], v[164:167], v[228:231], 0
	v_mfma_f32_16x16x32_bf16 v[2:5], v[172:175], v[228:231], 0
	v_mfma_f32_16x16x32_bf16 v[30:33], v[168:171], v[208:211], v[30:33]
	v_mfma_f32_16x16x32_bf16 v[26:29], v[176:179], v[208:211], v[26:29]
	v_mfma_f32_16x16x32_bf16 v[22:25], v[168:171], v[216:219], v[22:25]
	v_mfma_f32_16x16x32_bf16 v[18:21], v[176:179], v[216:219], v[18:21]
	v_mfma_f32_16x16x32_bf16 v[14:17], v[168:171], v[224:227], v[14:17]
	v_mfma_f32_16x16x32_bf16 v[10:13], v[176:179], v[224:227], v[10:13]
	v_mfma_f32_16x16x32_bf16 v[6:9], v[168:171], v[232:235], v[6:9]
	v_mfma_f32_16x16x32_bf16 v[2:5], v[176:179], v[232:235], v[2:5]
	s_setprio 0
	s_barrier
	s_add_i32 s56, 0, 0x18000
	s_add_i32 s57, 0, 0x1c000
	v_add_u32_e32 v142, s56, v201
	v_add_u32_e32 v176, s57, v201
	ds_read_b128 v[130:133], v142
	ds_read_b128 v[134:137], v142 offset:1024
	ds_read_b128 v[138:141], v142 offset:2048
	ds_read_b128 v[142:145], v142 offset:3072
	ds_read_b128 v[164:167], v176
	ds_read_b128 v[168:171], v176 offset:1024
	ds_read_b128 v[172:175], v176 offset:2048
	ds_read_b128 v[176:179], v176 offset:3072
	s_add_u32 s20, s20, 0x100000
	s_addc_u32 s21, s21, 0
	s_mov_b32 m0, s27
	v_lshl_add_u64 v[238:239], s[20:21], 0, v[158:159]
	ds_read_b128 v[204:207], v203 offset:32768
	ds_read_b128 v[208:211], v203 offset:33792
	ds_read_b128 v[212:215], v203 offset:34816
	ds_read_b128 v[216:219], v203 offset:35840
	ds_read_b128 v[220:223], v203 offset:36864
	ds_read_b128 v[224:227], v203 offset:37888
	ds_read_b128 v[228:231], v203 offset:38912
	ds_read_b128 v[232:235], v203 offset:39936
	global_load_lds_dwordx4 v[238:239], off
	v_lshl_add_u64 v[238:239], s[20:21], 0, v[156:157]
	s_mov_b32 m0, s28
	s_nop 0
	global_load_lds_dwordx4 v[238:239], off
	s_waitcnt vmcnt(8)
	s_waitcnt lgkmcnt(0)
	s_barrier
	s_setprio 1
	s_waitcnt lgkmcnt(0)
	v_mfma_f32_16x16x32_bf16 v[126:129], v[130:133], v[204:207], v[126:129]
	v_mfma_f32_16x16x32_bf16 v[122:125], v[138:141], v[204:207], v[122:125]
	v_mfma_f32_16x16x32_bf16 v[118:121], v[130:133], v[212:215], v[118:121]
	v_mfma_f32_16x16x32_bf16 v[114:117], v[138:141], v[212:215], v[114:117]
	v_mfma_f32_16x16x32_bf16 v[110:113], v[130:133], v[220:223], v[110:113]
	v_mfma_f32_16x16x32_bf16 v[106:109], v[138:141], v[220:223], v[106:109]
	v_mfma_f32_16x16x32_bf16 v[102:105], v[130:133], v[228:231], v[102:105]
	v_mfma_f32_16x16x32_bf16 v[98:101], v[138:141], v[228:231], v[98:101]
	v_mfma_f32_16x16x32_bf16 v[126:129], v[134:137], v[208:211], v[126:129]
	v_mfma_f32_16x16x32_bf16 v[122:125], v[142:145], v[208:211], v[122:125]
	v_mfma_f32_16x16x32_bf16 v[118:121], v[134:137], v[216:219], v[118:121]
	v_mfma_f32_16x16x32_bf16 v[114:117], v[142:145], v[216:219], v[114:117]
	v_mfma_f32_16x16x32_bf16 v[110:113], v[134:137], v[224:227], v[110:113]
	v_mfma_f32_16x16x32_bf16 v[106:109], v[142:145], v[224:227], v[106:109]
	v_mfma_f32_16x16x32_bf16 v[102:105], v[134:137], v[232:235], v[102:105]
	v_mfma_f32_16x16x32_bf16 v[98:101], v[142:145], v[232:235], v[98:101]
	s_setprio 0
	s_setprio 1
	v_mfma_f32_16x16x32_bf16 v[62:65], v[164:167], v[204:207], v[62:65]
	v_mfma_f32_16x16x32_bf16 v[58:61], v[172:175], v[204:207], v[58:61]
	v_mfma_f32_16x16x32_bf16 v[54:57], v[164:167], v[212:215], v[54:57]
	v_mfma_f32_16x16x32_bf16 v[50:53], v[172:175], v[212:215], v[50:53]
	v_mfma_f32_16x16x32_bf16 v[46:49], v[164:167], v[220:223], v[46:49]
	v_mfma_f32_16x16x32_bf16 v[42:45], v[172:175], v[220:223], v[42:45]
	v_mfma_f32_16x16x32_bf16 v[38:41], v[164:167], v[228:231], v[38:41]
	v_mfma_f32_16x16x32_bf16 v[34:37], v[172:175], v[228:231], v[34:37]
	v_mfma_f32_16x16x32_bf16 v[62:65], v[168:171], v[208:211], v[62:65]
	v_mfma_f32_16x16x32_bf16 v[58:61], v[176:179], v[208:211], v[58:61]
	v_mfma_f32_16x16x32_bf16 v[54:57], v[168:171], v[216:219], v[54:57]
	v_mfma_f32_16x16x32_bf16 v[50:53], v[176:179], v[216:219], v[50:53]
	v_mfma_f32_16x16x32_bf16 v[46:49], v[168:171], v[224:227], v[46:49]
	v_mfma_f32_16x16x32_bf16 v[42:45], v[176:179], v[224:227], v[42:45]
	v_mfma_f32_16x16x32_bf16 v[38:41], v[168:171], v[232:235], v[38:41]
	v_mfma_f32_16x16x32_bf16 v[34:37], v[176:179], v[232:235], v[34:37]
	s_setprio 0
	s_barrier
; #define PG8_STAGE(bufoff, gbase, voff) do { _Pragma("unroll") for (int _i = 0; _i < 2; ++_i) \
;         __builtin_amdgcn_global_load_lds((const unsigned*)((const char*)(gbase) + (voff)[_i]), (PG8_LAS unsigned*)(lds + (bufoff) + ldsw + _i * 8192), 16, 0, 0); } while (0)
; #define PG8_LDA(dst, b, h) do { _Pragma("unroll") for (int m = 0; m < 4; ++m) _Pragma("unroll") for (int k = 0; k < 2; ++k) dst[m][k] = *(const PG8_LAS bf16x8*)(lds + PG8_SA(b, h) + aoff + m * 2048 + k * 1024); } while (0)
; #define PG8_LDB(dst, b, h) do { _Pragma("unroll") for (int n = 0; n < 2; ++n) _Pragma("unroll") for (int k = 0; k < 2; ++k) dst[n][k] = *(const PG8_LAS bf16x8*)(lds + PG8_SB(b, h) + boff + n * 2048 + k * 1024); } while (0)
; #define PG8_MMA(ai, bj, At, Bt) do { __builtin_amdgcn_s_setprio(1); _Pragma("unroll") for (int m = 0; m < 4; ++m) _Pragma("unroll") for (int n = 0; n < 2; ++n) _Pragma("unroll") for (int k = 0; k < 2; ++k) \
;         acc[ai][bj][m][n] = __builtin_amdgcn_mfma_f32_16x16x32_bf16(Bt[n][k], At[m][k], acc[ai][bj][m][n], 0, 0, 0); __builtin_amdgcn_s_setprio(0); } while (0)
; #define PG8_WAIT_V(n) asm volatile("s_waitcnt vmcnt(" #n ")" ::: "memory")
; template <class Epi, class Sched, bool ALIGN_EPI = false, bool SP2 = false>
; __device__ __forceinline__ void gemm_phase(PG8_LAS unsigned char* lds, const Gemm g, const Sched& S, const Epi& E) {
;     ...
;             PG8_LDB(B0, 0, 0); PG8_LDB(B1, 0, 1); PG8_SCHED; PG8_LDA(At, 0, 0); PG8_STAGE(PG8_SA(1, 1), a1 + hstep, voffA);
;             PG8_WAIT_V(8); PG8_WAIT_L(0); PG8_BAR; PG8_MMA(0, 0, At, B0); PG8_MMA(0, 1, At, B1); PG8_BAR; PG8_SCHED;
;             PG8_LDA(At, 0, 1); PG8_STAGE(PG8_SB(0, 0), b2, voffB); PG8_STAGE(PG8_SB(0, 1), b2 + hstep, voffB); PG8_STAGE(PG8_SA(0, 0), a2, voffA);
;             PG8_WAIT_V(8); PG8_WAIT_L(0); PG8_BAR; PG8_MMA(1, 0, At, B0); PG8_MMA(1, 1, At, B1); PG8_BAR; PG8_SCHED;
;             PG8_LDB(B0, 1, 0); PG8_LDB(B1, 1, 1); PG8_SCHED; PG8_LDA(At, 1, 0); PG8_STAGE(PG8_SA(0, 1), a2 + hstep, voffA);
;             PG8_WAIT_V(8); PG8_WAIT_L(0); PG8_BAR; PG8_MMA(0, 0, At, B0); PG8_MMA(0, 1, At, B1); PG8_BAR; PG8_SCHED;
;             PG8_LDA(At, 1, 1); PG8_STAGE(PG8_SB(1, 0), b3, voffB); PG8_STAGE(PG8_SB(1, 1), b3 + hstep, voffB); PG8_STAGE(PG8_SA(1, 0), a3, voffA);
;             PG8_WAIT_V(8); PG8_WAIT_L(0); PG8_BAR; PG8_MMA(1, 0, At, B0); PG8_MMA(1, 1, At, B1); PG8_BAR; PG8_SCHED;
	s_add_i32 s20, s56, s24
	v_lshl_add_u64 v[146:147], v[146:147], 0, s[38:39]
	s_mov_b32 m0, s20
	ds_read_b128 v[204:207], v203 offset:49152
	ds_read_b128 v[208:211], v203 offset:50176
	ds_read_b128 v[212:215], v203 offset:51200
	ds_read_b128 v[216:219], v203 offset:52224
	ds_read_b128 v[220:223], v203 offset:53248
	ds_read_b128 v[224:227], v203 offset:54272
	ds_read_b128 v[228:231], v203 offset:55296
	ds_read_b128 v[232:235], v203 offset:56320
	global_load_lds_dwordx4 v[146:147], off
	s_add_i32 m0, s20, 0x2000
	s_add_u32 s18, s18, 0x100080
	v_lshl_add_u64 v[146:147], v[148:149], 0, s[38:39]
	s_addc_u32 s19, s19, 0
	s_add_i32 s20, s57, s24
	global_load_lds_dwordx4 v[146:147], off
	v_lshl_add_u64 v[146:147], s[18:19], 0, v[0:1]
	s_mov_b32 m0, s20
	s_nop 0
	global_load_lds_dwordx4 v[146:147], off
	v_lshl_add_u64 v[146:147], s[18:19], 0, v[154:155]
	s_add_i32 m0, s20, 0x2000
	s_nop 0
	global_load_lds_dwordx4 v[146:147], off
	v_lshl_add_u64 v[146:147], v[180:181], 0, s[38:39]
	s_mov_b32 m0, s31
	s_nop 0
	global_load_lds_dwordx4 v[146:147], off
	v_lshl_add_u64 v[146:147], v[236:237], 0, s[38:39]
	s_mov_b32 m0, s33
	s_nop 0
	global_load_lds_dwordx4 v[146:147], off
	s_waitcnt vmcnt(8)
	s_waitcnt lgkmcnt(0)
	s_barrier
	s_setprio 1
	s_waitcnt lgkmcnt(0)
	v_mfma_f32_16x16x32_bf16 v[94:97], v[130:133], v[204:207], v[94:97]
	v_mfma_f32_16x16x32_bf16 v[90:93], v[138:141], v[204:207], v[90:93]
	v_mfma_f32_16x16x32_bf16 v[86:89], v[130:133], v[212:215], v[86:89]
	v_mfma_f32_16x16x32_bf16 v[82:85], v[138:141], v[212:215], v[82:85]
	v_mfma_f32_16x16x32_bf16 v[78:81], v[130:133], v[220:223], v[78:81]
	v_mfma_f32_16x16x32_bf16 v[74:77], v[138:141], v[220:223], v[74:77]
	v_mfma_f32_16x16x32_bf16 v[70:73], v[130:133], v[228:231], v[70:73]
	v_mfma_f32_16x16x32_bf16 v[66:69], v[138:141], v[228:231], v[66:69]
	v_mfma_f32_16x16x32_bf16 v[94:97], v[134:137], v[208:211], v[94:97]
	v_mfma_f32_16x16x32_bf16 v[90:93], v[142:145], v[208:211], v[90:93]
	v_mfma_f32_16x16x32_bf16 v[86:89], v[134:137], v[216:219], v[86:89]
	v_mfma_f32_16x16x32_bf16 v[82:85], v[142:145], v[216:219], v[82:85]
	v_mfma_f32_16x16x32_bf16 v[78:81], v[134:137], v[224:227], v[78:81]
	v_mfma_f32_16x16x32_bf16 v[74:77], v[142:145], v[224:227], v[74:77]
	v_mfma_f32_16x16x32_bf16 v[70:73], v[134:137], v[232:235], v[70:73]
	v_mfma_f32_16x16x32_bf16 v[66:69], v[142:145], v[232:235], v[66:69]
	s_setprio 0
	s_setprio 1
	v_mfma_f32_16x16x32_bf16 v[30:33], v[164:167], v[204:207], v[30:33]
	v_mfma_f32_16x16x32_bf16 v[26:29], v[172:175], v[204:207], v[26:29]
	v_mfma_f32_16x16x32_bf16 v[22:25], v[164:167], v[212:215], v[22:25]
	v_mfma_f32_16x16x32_bf16 v[18:21], v[172:175], v[212:215], v[18:21]
	v_mfma_f32_16x16x32_bf16 v[14:17], v[164:167], v[220:223], v[14:17]
	v_mfma_f32_16x16x32_bf16 v[10:13], v[172:175], v[220:223], v[10:13]
	v_mfma_f32_16x16x32_bf16 v[6:9], v[164:167], v[228:231], v[6:9]
	v_mfma_f32_16x16x32_bf16 v[2:5], v[172:175], v[228:231], v[2:5]
	v_mfma_f32_16x16x32_bf16 v[30:33], v[168:171], v[208:211], v[30:33]
	v_mfma_f32_16x16x32_bf16 v[26:29], v[176:179], v[208:211], v[26:29]
	v_mfma_f32_16x16x32_bf16 v[22:25], v[168:171], v[216:219], v[22:25]
	v_mfma_f32_16x16x32_bf16 v[18:21], v[176:179], v[216:219], v[18:21]
	v_mfma_f32_16x16x32_bf16 v[14:17], v[168:171], v[224:227], v[14:17]
	v_mfma_f32_16x16x32_bf16 v[10:13], v[176:179], v[224:227], v[10:13]
	v_mfma_f32_16x16x32_bf16 v[6:9], v[168:171], v[232:235], v[6:9]
	v_mfma_f32_16x16x32_bf16 v[2:5], v[176:179], v[232:235], v[2:5]
	s_setprio 0
	s_barrier
	s_add_i32 s55, s55, 2
	s_add_u32 s16, s16, 0x100
	s_addc_u32 s17, s17, 0
	s_add_u32 s53, s53, 0x100
	s_addc_u32 s54, s54, 0
.LBB0_432:
	s_add_u32 s18, s16, 0xfff00080
	s_addc_u32 s19, s17, -1
	s_add_i32 s56, 0, 0x10000
	s_cmp_eq_u32 s55, 60
	s_cselect_b32 s21, s11, s19
	s_cselect_b32 s20, s51, s18
	s_cselect_b32 s19, s9, s54
	s_cselect_b32 s18, s52, s53
	s_add_i32 s58, 0, 0x14000
	v_add_u32_e32 v142, s56, v201
	v_add_u32_e32 v146, s58, v201
	ds_read_b128 v[130:133], v142
	ds_read_b128 v[134:137], v142 offset:1024
	ds_read_b128 v[138:141], v142 offset:2048
	ds_read_b128 v[142:145], v142 offset:3072
	ds_read_b128 v[164:167], v146
	ds_read_b128 v[168:171], v146 offset:1024
	ds_read_b128 v[172:175], v146 offset:2048
	ds_read_b128 v[176:179], v146 offset:3072
	v_lshl_add_u64 v[146:147], s[16:17], 0, v[160:161]
	s_add_i32 m0, s25, 0xc000
	ds_read_b128 v[204:207], v203
	ds_read_b128 v[208:211], v203 offset:1024
	ds_read_b128 v[212:215], v203 offset:2048
	ds_read_b128 v[216:219], v203 offset:3072
	ds_read_b128 v[220:223], v203 offset:4096
	ds_read_b128 v[224:227], v203 offset:5120
	ds_read_b128 v[228:231], v203 offset:6144
	ds_read_b128 v[232:235], v203 offset:7168
	global_load_lds_dwordx4 v[146:147], off
	v_lshl_add_u64 v[146:147], s[16:17], 0, v[162:163]
	s_add_i32 m0, s25, 0xe000
	s_nop 0
	global_load_lds_dwordx4 v[146:147], off
	s_waitcnt vmcnt(8)
	s_waitcnt lgkmcnt(0)
	s_barrier
; #define PG8_STAGE(bufoff, gbase, voff) do { _Pragma("unroll") for (int _i = 0; _i < 2; ++_i) \
;         __builtin_amdgcn_global_load_lds((const unsigned*)((const char*)(gbase) + (voff)[_i]), (PG8_LAS unsigned*)(lds + (bufoff) + ldsw + _i * 8192), 16, 0, 0); } while (0)
; #define PG8_LDA(dst, b, h) do { _Pragma("unroll") for (int m = 0; m < 4; ++m) _Pragma("unroll") for (int k = 0; k < 2; ++k) dst[m][k] = *(const PG8_LAS bf16x8*)(lds + PG8_SA(b, h) + aoff + m * 2048 + k * 1024); } while (0)
; #define PG8_MMA(ai, bj, At, Bt) do { __builtin_amdgcn_s_setprio(1); _Pragma("unroll") for (int m = 0; m < 4; ++m) _Pragma("unroll") for (int n = 0; n < 2; ++n) _Pragma("unroll") for (int k = 0; k < 2; ++k) \
;         acc[ai][bj][m][n] = __builtin_amdgcn_mfma_f32_16x16x32_bf16(Bt[n][k], At[m][k], acc[ai][bj][m][n], 0, 0, 0); __builtin_amdgcn_s_setprio(0); } while (0)
; #define PG8_WAIT_V(n) asm volatile("s_waitcnt vmcnt(" #n ")" ::: "memory")
; #define PG8_WAIT_L(n) asm volatile("s_waitcnt lgkmcnt(" #n ")" ::: "memory")
; #define PG8_BAR __builtin_amdgcn_s_barrier()
; #define PG8_SCHED __builtin_amdgcn_sched_barrier(0)
; template <class Epi, class Sched, bool ALIGN_EPI = false, bool SP2 = false>
; __device__ __forceinline__ void gemm_phase(PG8_LAS unsigned char* lds, const Gemm g, const Sched& S, const Epi& E) {
;     ...
;             PG8_WAIT_V(8); PG8_WAIT_L(0); PG8_BAR; PG8_MMA(0, 0, At, B0); PG8_MMA(0, 1, At, B1); PG8_BAR; PG8_SCHED;
;             PG8_LDA(At, 0, 1); PG8_STAGE(PG8_SB(0, 0), b2, voffB); PG8_STAGE(PG8_SB(0, 1), b2 + hstep, voffB); PG8_STAGE(PG8_SA(0, 0), a2, voffA);
;             PG8_WAIT_V(8); PG8_WAIT_L(0); PG8_BAR; PG8_MMA(1, 0, At, B0); PG8_MMA(1, 1, At, B1); PG8_BAR; PG8_SCHED;
	s_setprio 1
	s_waitcnt lgkmcnt(0)
	v_mfma_f32_16x16x32_bf16 v[126:129], v[130:133], v[204:207], v[126:129]
	v_mfma_f32_16x16x32_bf16 v[122:125], v[138:141], v[204:207], v[122:125]
	v_mfma_f32_16x16x32_bf16 v[118:121], v[130:133], v[212:215], v[118:121]
	v_mfma_f32_16x16x32_bf16 v[114:117], v[138:141], v[212:215], v[114:117]
	v_mfma_f32_16x16x32_bf16 v[110:113], v[130:133], v[220:223], v[110:113]
	v_mfma_f32_16x16x32_bf16 v[106:109], v[138:141], v[220:223], v[106:109]
	v_mfma_f32_16x16x32_bf16 v[102:105], v[130:133], v[228:231], v[102:105]
	v_mfma_f32_16x16x32_bf16 v[98:101], v[138:141], v[228:231], v[98:101]
	v_mfma_f32_16x16x32_bf16 v[126:129], v[134:137], v[208:211], v[126:129]
	v_mfma_f32_16x16x32_bf16 v[122:125], v[142:145], v[208:211], v[122:125]
	v_mfma_f32_16x16x32_bf16 v[118:121], v[134:137], v[216:219], v[118:121]
	v_mfma_f32_16x16x32_bf16 v[114:117], v[142:145], v[216:219], v[114:117]
	v_mfma_f32_16x16x32_bf16 v[110:113], v[134:137], v[224:227], v[110:113]
	v_mfma_f32_16x16x32_bf16 v[106:109], v[142:145], v[224:227], v[106:109]
	v_mfma_f32_16x16x32_bf16 v[102:105], v[134:137], v[232:235], v[102:105]
	v_mfma_f32_16x16x32_bf16 v[98:101], v[142:145], v[232:235], v[98:101]
	s_setprio 0
	s_setprio 1
	v_mfma_f32_16x16x32_bf16 v[62:65], v[164:167], v[204:207], v[62:65]
	v_mfma_f32_16x16x32_bf16 v[58:61], v[172:175], v[204:207], v[58:61]
	v_mfma_f32_16x16x32_bf16 v[54:57], v[164:167], v[212:215], v[54:57]
	v_mfma_f32_16x16x32_bf16 v[50:53], v[172:175], v[212:215], v[50:53]
	v_mfma_f32_16x16x32_bf16 v[46:49], v[164:167], v[220:223], v[46:49]
	v_mfma_f32_16x16x32_bf16 v[42:45], v[172:175], v[220:223], v[42:45]
	v_mfma_f32_16x16x32_bf16 v[38:41], v[164:167], v[228:231], v[38:41]
	v_mfma_f32_16x16x32_bf16 v[34:37], v[172:175], v[228:231], v[34:37]
	v_mfma_f32_16x16x32_bf16 v[62:65], v[168:171], v[208:211], v[62:65]
	v_mfma_f32_16x16x32_bf16 v[58:61], v[176:179], v[208:211], v[58:61]
	v_mfma_f32_16x16x32_bf16 v[54:57], v[168:171], v[216:219], v[54:57]
	v_mfma_f32_16x16x32_bf16 v[50:53], v[176:179], v[216:219], v[50:53]
	v_mfma_f32_16x16x32_bf16 v[46:49], v[168:171], v[224:227], v[46:49]
	v_mfma_f32_16x16x32_bf16 v[42:45], v[176:179], v[224:227], v[42:45]
	v_mfma_f32_16x16x32_bf16 v[38:41], v[168:171], v[232:235], v[38:41]
	v_mfma_f32_16x16x32_bf16 v[34:37], v[176:179], v[232:235], v[34:37]
	s_setprio 0
	s_barrier
	s_add_i32 s56, s56, s24
	v_lshl_add_u64 v[146:147], s[18:19], 0, v[0:1]
	s_mov_b32 m0, s56
	ds_read_b128 v[204:207], v203 offset:16384
	ds_read_b128 v[208:211], v203 offset:17408
	ds_read_b128 v[212:215], v203 offset:18432
	ds_read_b128 v[216:219], v203 offset:19456
	ds_read_b128 v[220:223], v203 offset:20480
	ds_read_b128 v[224:227], v203 offset:21504
	ds_read_b128 v[228:231], v203 offset:22528
	ds_read_b128 v[232:235], v203 offset:23552
	global_load_lds_dwordx4 v[146:147], off
	s_add_i32 m0, s56, 0x2000
	s_add_u32 s56, s18, 0x100000
	v_lshl_add_u64 v[148:149], s[18:19], 0, v[154:155]
	s_addc_u32 s57, s19, 0
	s_add_i32 s58, s58, s24
	global_load_lds_dwordx4 v[148:149], off
	v_lshl_add_u64 v[180:181], s[56:57], 0, v[0:1]
	s_mov_b32 m0, s58
	v_lshl_add_u64 v[236:237], s[20:21], 0, v[156:157]
	global_load_lds_dwordx4 v[180:181], off
	v_lshl_add_u64 v[180:181], s[56:57], 0, v[154:155]
	s_add_i32 m0, s58, 0x2000
	s_nop 0
	global_load_lds_dwordx4 v[180:181], off
	v_lshl_add_u64 v[180:181], s[20:21], 0, v[158:159]
	s_mov_b32 m0, s25
	s_nop 0
	global_load_lds_dwordx4 v[180:181], off
	s_mov_b32 m0, s26
	s_nop 0
	global_load_lds_dwordx4 v[236:237], off
	s_waitcnt vmcnt(8)
	s_waitcnt lgkmcnt(0)
	s_barrier
	s_setprio 1
	s_waitcnt lgkmcnt(0)
	v_mfma_f32_16x16x32_bf16 v[94:97], v[130:133], v[204:207], v[94:97]
	v_mfma_f32_16x16x32_bf16 v[90:93], v[138:141], v[204:207], v[90:93]
	v_mfma_f32_16x16x32_bf16 v[86:89], v[130:133], v[212:215], v[86:89]
	v_mfma_f32_16x16x32_bf16 v[82:85], v[138:141], v[212:215], v[82:85]
	v_mfma_f32_16x16x32_bf16 v[78:81], v[130:133], v[220:223], v[78:81]
	v_mfma_f32_16x16x32_bf16 v[74:77], v[138:141], v[220:223], v[74:77]
	v_mfma_f32_16x16x32_bf16 v[70:73], v[130:133], v[228:231], v[70:73]
	v_mfma_f32_16x16x32_bf16 v[66:69], v[138:141], v[228:231], v[66:69]
	v_mfma_f32_16x16x32_bf16 v[94:97], v[134:137], v[208:211], v[94:97]
	v_mfma_f32_16x16x32_bf16 v[90:93], v[142:145], v[208:211], v[90:93]
	v_mfma_f32_16x16x32_bf16 v[86:89], v[134:137], v[216:219], v[86:89]
	v_mfma_f32_16x16x32_bf16 v[82:85], v[142:145], v[216:219], v[82:85]
	v_mfma_f32_16x16x32_bf16 v[78:81], v[134:137], v[224:227], v[78:81]
	v_mfma_f32_16x16x32_bf16 v[74:77], v[142:145], v[224:227], v[74:77]
	v_mfma_f32_16x16x32_bf16 v[70:73], v[134:137], v[232:235], v[70:73]
	v_mfma_f32_16x16x32_bf16 v[66:69], v[142:145], v[232:235], v[66:69]
	s_setprio 0
	s_setprio 1
	v_mfma_f32_16x16x32_bf16 v[30:33], v[164:167], v[204:207], v[30:33]
	v_mfma_f32_16x16x32_bf16 v[26:29], v[172:175], v[204:207], v[26:29]
	v_mfma_f32_16x16x32_bf16 v[22:25], v[164:167], v[212:215], v[22:25]
	v_mfma_f32_16x16x32_bf16 v[18:21], v[172:175], v[212:215], v[18:21]
	v_mfma_f32_16x16x32_bf16 v[14:17], v[164:167], v[220:223], v[14:17]
	v_mfma_f32_16x16x32_bf16 v[10:13], v[172:175], v[220:223], v[10:13]
	v_mfma_f32_16x16x32_bf16 v[6:9], v[164:167], v[228:231], v[6:9]
	v_mfma_f32_16x16x32_bf16 v[2:5], v[172:175], v[228:231], v[2:5]
	v_mfma_f32_16x16x32_bf16 v[30:33], v[168:171], v[208:211], v[30:33]
	v_mfma_f32_16x16x32_bf16 v[26:29], v[176:179], v[208:211], v[26:29]
	v_mfma_f32_16x16x32_bf16 v[22:25], v[168:171], v[216:219], v[22:25]
	v_mfma_f32_16x16x32_bf16 v[18:21], v[176:179], v[216:219], v[18:21]
	v_mfma_f32_16x16x32_bf16 v[14:17], v[168:171], v[224:227], v[14:17]
	v_mfma_f32_16x16x32_bf16 v[10:13], v[176:179], v[224:227], v[10:13]
	v_mfma_f32_16x16x32_bf16 v[6:9], v[168:171], v[232:235], v[6:9]
	v_mfma_f32_16x16x32_bf16 v[2:5], v[176:179], v[232:235], v[2:5]
	s_setprio 0
	s_barrier
; #define PG8_STAGE(bufoff, gbase, voff) do { _Pragma("unroll") for (int _i = 0; _i < 2; ++_i) \
;         __builtin_amdgcn_global_load_lds((const unsigned*)((const char*)(gbase) + (voff)[_i]), (PG8_LAS unsigned*)(lds + (bufoff) + ldsw + _i * 8192), 16, 0, 0); } while (0)
; #define PG8_LDA(dst, b, h) do { _Pragma("unroll") for (int m = 0; m < 4; ++m) _Pragma("unroll") for (int k = 0; k < 2; ++k) dst[m][k] = *(const PG8_LAS bf16x8*)(lds + PG8_SA(b, h) + aoff + m * 2048 + k * 1024); } while (0)
; #define PG8_LDB(dst, b, h) do { _Pragma("unroll") for (int n = 0; n < 2; ++n) _Pragma("unroll") for (int k = 0; k < 2; ++k) dst[n][k] = *(const PG8_LAS bf16x8*)(lds + PG8_SB(b, h) + boff + n * 2048 + k * 1024); } while (0)
; #define PG8_MMA(ai, bj, At, Bt) do { __builtin_amdgcn_s_setprio(1); _Pragma("unroll") for (int m = 0; m < 4; ++m) _Pragma("unroll") for (int n = 0; n < 2; ++n) _Pragma("unroll") for (int k = 0; k < 2; ++k) \
;         acc[ai][bj][m][n] = __builtin_amdgcn_mfma_f32_16x16x32_bf16(Bt[n][k], At[m][k], acc[ai][bj][m][n], 0, 0, 0); __builtin_amdgcn_s_setprio(0); } while (0)
; #define PG8_WAIT_V(n) asm volatile("s_waitcnt vmcnt(" #n ")" ::: "memory")
; #define PG8_WAIT_L(n) asm volatile("s_waitcnt lgkmcnt(" #n ")" ::: "memory")
; #define PG8_BAR __builtin_amdgcn_s_barrier()
; #define PG8_SCHED __builtin_amdgcn_sched_barrier(0)
; template <class Epi, class Sched, bool ALIGN_EPI = false, bool SP2 = false>
; __device__ __forceinline__ void gemm_phase(PG8_LAS unsigned char* lds, const Gemm g, const Sched& S, const Epi& E) {
;     ...
;             PG8_LDB(B0, 1, 0); PG8_LDB(B1, 1, 1); PG8_SCHED; PG8_LDA(At, 1, 0); PG8_STAGE(PG8_SA(0, 1), a2 + hstep, voffA);
;             PG8_WAIT_V(8); PG8_WAIT_L(0); PG8_BAR; PG8_MMA(0, 0, At, B0); PG8_MMA(0, 1, At, B1); PG8_BAR; PG8_SCHED;
	s_add_i32 s56, 0, 0x18000
	s_add_i32 s57, 0, 0x1c000
	v_add_u32_e32 v142, s56, v201
	v_add_u32_e32 v176, s57, v201
	ds_read_b128 v[130:133], v142
	ds_read_b128 v[134:137], v142 offset:1024
	ds_read_b128 v[138:141], v142 offset:2048
	ds_read_b128 v[142:145], v142 offset:3072
	ds_read_b128 v[164:167], v176
	ds_read_b128 v[168:171], v176 offset:1024
	ds_read_b128 v[172:175], v176 offset:2048
	ds_read_b128 v[176:179], v176 offset:3072
	s_add_u32 s20, s20, 0x100000
	s_addc_u32 s21, s21, 0
	s_mov_b32 m0, s27
	v_lshl_add_u64 v[238:239], s[20:21], 0, v[158:159]
	ds_read_b128 v[204:207], v203 offset:32768
	ds_read_b128 v[208:211], v203 offset:33792
	ds_read_b128 v[212:215], v203 offset:34816
	ds_read_b128 v[216:219], v203 offset:35840
	ds_read_b128 v[220:223], v203 offset:36864
	ds_read_b128 v[224:227], v203 offset:37888
	ds_read_b128 v[228:231], v203 offset:38912
	ds_read_b128 v[232:235], v203 offset:39936
	global_load_lds_dwordx4 v[238:239], off
	v_lshl_add_u64 v[238:239], s[20:21], 0, v[156:157]
	s_mov_b32 m0, s28
	s_nop 0
	global_load_lds_dwordx4 v[238:239], off
	s_waitcnt vmcnt(8)
	s_waitcnt lgkmcnt(0)
	s_barrier
	s_setprio 1
	s_waitcnt lgkmcnt(0)
	v_mfma_f32_16x16x32_bf16 v[126:129], v[130:133], v[204:207], v[126:129]
	v_mfma_f32_16x16x32_bf16 v[122:125], v[138:141], v[204:207], v[122:125]
	v_mfma_f32_16x16x32_bf16 v[118:121], v[130:133], v[212:215], v[118:121]
	v_mfma_f32_16x16x32_bf16 v[114:117], v[138:141], v[212:215], v[114:117]
	v_mfma_f32_16x16x32_bf16 v[110:113], v[130:133], v[220:223], v[110:113]
	v_mfma_f32_16x16x32_bf16 v[106:109], v[138:141], v[220:223], v[106:109]
	v_mfma_f32_16x16x32_bf16 v[102:105], v[130:133], v[228:231], v[102:105]
	v_mfma_f32_16x16x32_bf16 v[98:101], v[138:141], v[228:231], v[98:101]
	v_mfma_f32_16x16x32_bf16 v[126:129], v[134:137], v[208:211], v[126:129]
	v_mfma_f32_16x16x32_bf16 v[122:125], v[142:145], v[208:211], v[122:125]
	v_mfma_f32_16x16x32_bf16 v[118:121], v[134:137], v[216:219], v[118:121]
	v_mfma_f32_16x16x32_bf16 v[114:117], v[142:145], v[216:219], v[114:117]
	v_mfma_f32_16x16x32_bf16 v[110:113], v[134:137], v[224:227], v[110:113]
	v_mfma_f32_16x16x32_bf16 v[106:109], v[142:145], v[224:227], v[106:109]
	v_mfma_f32_16x16x32_bf16 v[102:105], v[134:137], v[232:235], v[102:105]
	v_mfma_f32_16x16x32_bf16 v[98:101], v[142:145], v[232:235], v[98:101]
	s_setprio 0
	s_setprio 1
	v_mfma_f32_16x16x32_bf16 v[62:65], v[164:167], v[204:207], v[62:65]
	v_mfma_f32_16x16x32_bf16 v[58:61], v[172:175], v[204:207], v[58:61]
	v_mfma_f32_16x16x32_bf16 v[54:57], v[164:167], v[212:215], v[54:57]
	v_mfma_f32_16x16x32_bf16 v[50:53], v[172:175], v[212:215], v[50:53]
	v_mfma_f32_16x16x32_bf16 v[46:49], v[164:167], v[220:223], v[46:49]
	v_mfma_f32_16x16x32_bf16 v[42:45], v[172:175], v[220:223], v[42:45]
	v_mfma_f32_16x16x32_bf16 v[38:41], v[164:167], v[228:231], v[38:41]
	v_mfma_f32_16x16x32_bf16 v[34:37], v[172:175], v[228:231], v[34:37]
	v_mfma_f32_16x16x32_bf16 v[62:65], v[168:171], v[208:211], v[62:65]
	v_mfma_f32_16x16x32_bf16 v[58:61], v[176:179], v[208:211], v[58:61]
	v_mfma_f32_16x16x32_bf16 v[54:57], v[168:171], v[216:219], v[54:57]
	v_mfma_f32_16x16x32_bf16 v[50:53], v[176:179], v[216:219], v[50:53]
	v_mfma_f32_16x16x32_bf16 v[46:49], v[168:171], v[224:227], v[46:49]
	v_mfma_f32_16x16x32_bf16 v[42:45], v[176:179], v[224:227], v[42:45]
	v_mfma_f32_16x16x32_bf16 v[38:41], v[168:171], v[232:235], v[38:41]
	v_mfma_f32_16x16x32_bf16 v[34:37], v[176:179], v[232:235], v[34:37]
	s_setprio 0
	s_barrier
; #define PG8_STAGE(bufoff, gbase, voff) do { _Pragma("unroll") for (int _i = 0; _i < 2; ++_i) \
;         __builtin_amdgcn_global_load_lds((const unsigned*)((const char*)(gbase) + (voff)[_i]), (PG8_LAS unsigned*)(lds + (bufoff) + ldsw + _i * 8192), 16, 0, 0); } while (0)
; #define PG8_LDA(dst, b, h) do { _Pragma("unroll") for (int m = 0; m < 4; ++m) _Pragma("unroll") for (int k = 0; k < 2; ++k) dst[m][k] = *(const PG8_LAS bf16x8*)(lds + PG8_SA(b, h) + aoff + m * 2048 + k * 1024); } while (0)
; #define PG8_MMA(ai, bj, At, Bt) do { __builtin_amdgcn_s_setprio(1); _Pragma("unroll") for (int m = 0; m < 4; ++m) _Pragma("unroll") for (int n = 0; n < 2; ++n) _Pragma("unroll") for (int k = 0; k < 2; ++k) \
;         acc[ai][bj][m][n] = __builtin_amdgcn_mfma_f32_16x16x32_bf16(Bt[n][k], At[m][k], acc[ai][bj][m][n], 0, 0, 0); __builtin_amdgcn_s_setprio(0); } while (0)
; #define PG8_WAIT_V(n) asm volatile("s_waitcnt vmcnt(" #n ")" ::: "memory")
; #define PG8_WAIT_L(n) asm volatile("s_waitcnt lgkmcnt(" #n ")" ::: "memory")
; #define PG8_BAR __builtin_amdgcn_s_barrier()
; #define PG8_SCHED __builtin_amdgcn_sched_barrier(0)
; template <class Epi, class Sched, bool ALIGN_EPI = false, bool SP2 = false>
; __device__ __forceinline__ void gemm_phase(PG8_LAS unsigned char* lds, const Gemm g, const Sched& S, const Epi& E) {
;     ...
;             PG8_LDA(At, 1, 1); PG8_STAGE(PG8_SB(1, 0), b3, voffB); PG8_STAGE(PG8_SB(1, 1), b3 + hstep, voffB); PG8_STAGE(PG8_SA(1, 0), a3, voffA);
;             PG8_WAIT_V(8); PG8_WAIT_L(0); PG8_BAR; PG8_MMA(1, 0, At, B0); PG8_MMA(1, 1, At, B1); PG8_BAR; PG8_SCHED;
	s_add_i32 s20, s56, s24
	v_lshl_add_u64 v[146:147], v[146:147], 0, s[38:39]
	s_mov_b32 m0, s20
	ds_read_b128 v[204:207], v203 offset:49152
	ds_read_b128 v[208:211], v203 offset:50176
	ds_read_b128 v[212:215], v203 offset:51200
	ds_read_b128 v[216:219], v203 offset:52224
	ds_read_b128 v[220:223], v203 offset:53248
	ds_read_b128 v[224:227], v203 offset:54272
	ds_read_b128 v[228:231], v203 offset:55296
	ds_read_b128 v[232:235], v203 offset:56320
	global_load_lds_dwordx4 v[146:147], off
	s_add_i32 m0, s20, 0x2000
	s_add_u32 s18, s18, 0x100080
	v_lshl_add_u64 v[146:147], v[148:149], 0, s[38:39]
	s_addc_u32 s19, s19, 0
	s_add_i32 s20, s57, s24
	global_load_lds_dwordx4 v[146:147], off
	v_lshl_add_u64 v[146:147], s[18:19], 0, v[0:1]
	s_mov_b32 m0, s20
	s_nop 0
	global_load_lds_dwordx4 v[146:147], off
	v_lshl_add_u64 v[146:147], s[18:19], 0, v[154:155]
	s_add_i32 m0, s20, 0x2000
	s_nop 0
	global_load_lds_dwordx4 v[146:147], off
	v_lshl_add_u64 v[146:147], v[180:181], 0, s[38:39]
	s_mov_b32 m0, s31
	s_nop 0
	global_load_lds_dwordx4 v[146:147], off
	v_lshl_add_u64 v[146:147], v[236:237], 0, s[38:39]
	s_mov_b32 m0, s33
	s_nop 0
	global_load_lds_dwordx4 v[146:147], off
	s_waitcnt vmcnt(8)
	s_waitcnt lgkmcnt(0)
	s_barrier
	s_setprio 1
	s_waitcnt lgkmcnt(0)
	v_mfma_f32_16x16x32_bf16 v[94:97], v[130:133], v[204:207], v[94:97]
	v_mfma_f32_16x16x32_bf16 v[90:93], v[138:141], v[204:207], v[90:93]
	v_mfma_f32_16x16x32_bf16 v[86:89], v[130:133], v[212:215], v[86:89]
	v_mfma_f32_16x16x32_bf16 v[82:85], v[138:141], v[212:215], v[82:85]
	v_mfma_f32_16x16x32_bf16 v[78:81], v[130:133], v[220:223], v[78:81]
	v_mfma_f32_16x16x32_bf16 v[74:77], v[138:141], v[220:223], v[74:77]
	v_mfma_f32_16x16x32_bf16 v[70:73], v[130:133], v[228:231], v[70:73]
	v_mfma_f32_16x16x32_bf16 v[66:69], v[138:141], v[228:231], v[66:69]
	v_mfma_f32_16x16x32_bf16 v[94:97], v[134:137], v[208:211], v[94:97]
	v_mfma_f32_16x16x32_bf16 v[90:93], v[142:145], v[208:211], v[90:93]
	v_mfma_f32_16x16x32_bf16 v[86:89], v[134:137], v[216:219], v[86:89]
	v_mfma_f32_16x16x32_bf16 v[82:85], v[142:145], v[216:219], v[82:85]
	v_mfma_f32_16x16x32_bf16 v[78:81], v[134:137], v[224:227], v[78:81]
	v_mfma_f32_16x16x32_bf16 v[74:77], v[142:145], v[224:227], v[74:77]
	v_mfma_f32_16x16x32_bf16 v[70:73], v[134:137], v[232:235], v[70:73]
	v_mfma_f32_16x16x32_bf16 v[66:69], v[142:145], v[232:235], v[66:69]
	s_setprio 0
	s_setprio 1
	v_mfma_f32_16x16x32_bf16 v[30:33], v[164:167], v[204:207], v[30:33]
	v_mfma_f32_16x16x32_bf16 v[26:29], v[172:175], v[204:207], v[26:29]
	v_mfma_f32_16x16x32_bf16 v[22:25], v[164:167], v[212:215], v[22:25]
	v_mfma_f32_16x16x32_bf16 v[18:21], v[172:175], v[212:215], v[18:21]
	v_mfma_f32_16x16x32_bf16 v[14:17], v[164:167], v[220:223], v[14:17]
	v_mfma_f32_16x16x32_bf16 v[10:13], v[172:175], v[220:223], v[10:13]
	v_mfma_f32_16x16x32_bf16 v[6:9], v[164:167], v[228:231], v[6:9]
	v_mfma_f32_16x16x32_bf16 v[2:5], v[172:175], v[228:231], v[2:5]
	v_mfma_f32_16x16x32_bf16 v[30:33], v[168:171], v[208:211], v[30:33]
	v_mfma_f32_16x16x32_bf16 v[26:29], v[176:179], v[208:211], v[26:29]
	v_mfma_f32_16x16x32_bf16 v[22:25], v[168:171], v[216:219], v[22:25]
	v_mfma_f32_16x16x32_bf16 v[18:21], v[176:179], v[216:219], v[18:21]
	v_mfma_f32_16x16x32_bf16 v[14:17], v[168:171], v[224:227], v[14:17]
	v_mfma_f32_16x16x32_bf16 v[10:13], v[176:179], v[224:227], v[10:13]
	v_mfma_f32_16x16x32_bf16 v[6:9], v[168:171], v[232:235], v[6:9]
	v_mfma_f32_16x16x32_bf16 v[2:5], v[176:179], v[232:235], v[2:5]
	s_setprio 0
	s_cmp_lg_u32 s55, 60
	s_cbranch_scc1 .Llb_432
	s_and_b64 vcc, exec, s[6:7]
	s_cbranch_vccz .Lnb_432

; #define PG8_BAR __builtin_amdgcn_s_barrier()
; template <class Epi, class Sched, bool ALIGN_EPI = false, bool SP2 = false>
; __device__ __forceinline__ void gemm_phase(PG8_LAS unsigned char* lds, const Gemm g, const Sched& S, const Epi& E) {
;     ...
;         for (int t = 0; t < nt; t += 2) {
;     ...
;         if constexpr (ALIGN_EPI) { if (wr == 0) PG8_BAR; }
;         if constexpr (!Epi::AFTER_DRAIN) { E(acc, cur, wr, wc, fr, fq); S.done(cur); }
.Lnb_432:
	s_add_i32 s55, s55, 2
	s_add_u32 s16, s16, 0x100
	s_addc_u32 s17, s17, 0
	s_add_u32 s53, s53, 0x100
	s_addc_u32 s54, s54, 0
	s_cmp_gt_u32 s55, 61
	s_cbranch_scc0 .LBB0_432
	s_and_b64 vcc, exec, s[6:7]
	s_cbranch_vccz .LBB0_435

; #define PG8_BAR __builtin_amdgcn_s_barrier()
; template <class Epi, class Sched, bool ALIGN_EPI = false, bool SP2 = false>
; __device__ __forceinline__ void gemm_phase(PG8_LAS unsigned char* lds, const Gemm g, const Sched& S, const Epi& E) {
;     ...
;         if (!has_next) break;
; #pragma unroll
;         for (int a = 0; a < 2; ++a)
; #pragma unroll
;             for (int b = 0; b < 2; ++b)
; #pragma unroll
;                 for (int m = 0; m < 4; ++m)
; #pragma unroll
;                     for (int n = 0; n < 2; ++n) acc[a][b][m][n] = (f32x4){0.f, 0.f, 0.f, 0.f};
;         cur = nxt; cA = nA; cB = nB; ++ui;
;         if constexpr (ALIGN_EPI) { if (wr == 1) PG8_BAR; }
.Lres_a_tail:
	s_andn2_b64 vcc, exec, s[4:5]
	s_mov_b64 s[4:5], -1
	s_cbranch_vccnz .LBB0_424
	s_andn2_b64 vcc, exec, s[0:1]
	s_cbranch_vccnz .LBB0_423
	s_branch .LBB0_423

;     __host__ __device__ bool next(int i, Unit& u) const {
;         const long L = (long)i * G + c; if (L >= nwg) return false;
;         int wgid = (int)L; { const int q = nwg / NXCD, r = nwg % NXCD, xcd = wgid % NXCD, off = wgid / NXCD; wgid = (xcd < r ? xcd * (q + 1) : r * (q + 1) + (xcd - r) * q) + off; }
;         const int nig = WGM * nN, gid = wgid / nig, fm = gid * WGM, gsz = (nM - fm) < WGM ? (nM - fm) : WGM;
;         u.pm = fm + ((wgid % nig) % gsz); u.pn = (wgid % nig) / gsz; return true;
; template <class Epi, class Sched, bool ALIGN_EPI = false, bool SP2 = false>
; __device__ __forceinline__ void gemm_phase(PG8_LAS unsigned char* lds, const Gemm g, const Sched& S, const Epi& E) {
;     ...
;     const int tid = tid_, wid = __builtin_amdgcn_readfirstlane(tid >> 6), lane = tid & 63, wr = wid >> 2, wc = wid & 3, fr = lane & 15, fq = lane >> 4;
;     const int K = g.K, nt = K / BK;
;     unsigned voffA[2], voffB[2];
; #pragma unroll
;     for (int i = 0; i < 2; ++i) { int R, C; stage_rc(tid * 16 + i * 8192, R, C); const int Rb = Epi::PERM ? ((R & ~31) + perm32(R & 31)) : R;
;         voffA[i] = (unsigned)(R * K + C) * 2u; voffB[i] = (unsigned)(Rb * K + C) * 2u; }
;     const size_t kstep = (size_t)(BK * 2);
;     const size_t hstep = (size_t)HALF * K * 2;
;     const size_t tstep = 2 * hstep;
;     const unsigned ldsw = (unsigned)wid * 1024u;
;     const int aoff = lds_byte(wr * 64 + fr, fq * 8), boff = lds_byte(wc * 32 + fr, fq * 8);
;     ...
;     Unit cur, nxt; int ui = 0;
;     if (!S.next(0, cur)) return;
;     f32x4 acc[2][2][4][2];
; #pragma unroll
;     for (int a = 0; a < 2; ++a)
; #pragma unroll
;         for (int b = 0; b < 2; ++b)
; #pragma unroll
;             for (int m = 0; m < 4; ++m)
; #pragma unroll
;                 for (int n = 0; n < 2; ++n) acc[a][b][m][n] = (f32x4){0.f, 0.f, 0.f, 0.f};
;     bf16x8 At[4][2], B0[2][2], B1[2][2];
;     const char* cA = (const char*)g.A + (size_t)cur.pm * tstep; const char* cB = (const char*)g.Bt + (size_t)cur.pn * tstep;
;     S.a_ready(cur);
;     if constexpr (SP2) {
;         PG8_STAGE(PG8_SB(0, 0), cB, voffB); PG8_STAGE(PG8_SB(0, 1), cB + hstep, voffB); PG8_STAGE(PG8_SA(0, 0), cA, voffA); PG8_STAGE(PG8_SA(0, 1), cA + hstep, voffA);
.LBB0_548:
	s_and_b64 vcc, exec, s[0:1]
	s_cbranch_vccz .LBB0_300
	s_and_b64 s[0:1], s[44:45], exec
	s_cselect_b32 s0, 13, 17
	s_lshl_b32 s86, s0, 7
	v_mov_b32_e32 v0, v182
	s_cmp_ge_i32 s2, s86
	v_readfirstlane_b32 s5, v0
	s_cbranch_scc1 .LBB0_575
	v_lshlrev_b32_e32 v2, 4, v0
	v_add_u32_e32 v3, 0x2000, v2
	v_ashrrev_i32_e32 v4, 31, v3
	v_lshrrev_b32_e32 v4, 22, v4
	v_add_u32_e32 v4, v3, v4
	v_ashrrev_i32_e32 v10, 10, v4
	v_mul_i32_i24_e32 v4, 0x400, v10
	v_sub_u32_e32 v3, v3, v4
	v_lshrrev_b32_e32 v4, 4, v3
	v_bitop3_b32 v3, v4, v3, 32 bitop3:0x6c
	v_ashrrev_i32_e32 v4, 31, v3
	v_lshrrev_b32_e32 v4, 26, v4
	v_add_u32_e32 v4, v3, v4
	v_lshlrev_b32_e32 v5, 3, v10
	s_and_b64 s[6:7], s[44:45], exec
	s_mov_b32 s1, 0x6a00000
	v_ashrrev_i32_e32 v11, 6, v4
	v_and_b32_e32 v5, -16, v5
	s_cselect_b32 s1, s1, 0x7300000
	v_add_u32_e32 v5, v11, v5
	s_add_u32 s28, s76, s1
	v_and_b32_e32 v6, 3, v11
	s_mov_b32 s1, 0x1fffe0
	v_lshrrev_b32_e32 v7, 2, v5
	v_lshlrev_b32_e32 v8, 1, v5
	v_and_b32_e32 v4, 0xc0, v4
	v_and_or_b32 v6, v5, s1, v6
	v_and_b32_e32 v7, 4, v7
	v_and_b32_e32 v8, 24, v8
	v_sub_u32_e32 v3, v3, v4
	v_or3_b32 v6, v6, v7, v8
	v_lshlrev_b32_e32 v7, 5, v10
	v_ashrrev_i16_sdwa v3, v184, sext(v3) dst_sel:DWORD dst_unused:UNUSED_PAD src0_sel:DWORD src1_sel:BYTE_0
	v_and_b32_e32 v7, 32, v7
	v_bfe_i32 v12, v3, 0, 16
	v_add_lshl_u32 v3, v7, v12, 1
	v_lshl_add_u32 v154, v6, 11, v3
	v_lshl_add_u32 v156, v5, 11, v3
	v_bfe_i32 v3, v0, 27, 1
	v_lshrrev_b32_e32 v3, 22, v3
	v_add_u32_e32 v3, v2, v3
	v_and_b32_e32 v3, 0xfffffc00, v3
	v_sub_u32_e32 v2, v2, v3
	v_lshrrev_b32_e32 v3, 4, v2
	v_ashrrev_i32_e32 v4, 31, v0
	v_bitop3_b32 v2, v3, v2, 32 bitop3:0x6c
	v_lshrrev_b32_e32 v4, 26, v4
	v_ashrrev_i32_e32 v3, 31, v2
	v_add_u32_e32 v4, v0, v4
	v_lshrrev_b32_e32 v3, 26, v3
	v_ashrrev_i32_e32 v14, 6, v4
	s_addc_u32 s29, s77, 0
	s_ashr_i32 s7, s5, 6
	v_add_u32_e32 v3, v2, v3
	v_lshlrev_b32_e32 v4, 3, v14
	s_lshl_b32 s31, s0, 4
	v_readlane_b32 s8, v253, 58
	s_ashr_i32 s6, s5, 8
	s_lshl_b32 s30, s7, 10
	v_ashrrev_i32_e32 v13, 6, v3
	v_and_b32_e32 v4, -16, v4
	s_or_b32 s33, s31, 1
	v_readlane_b32 s9, v253, 59
	v_add_u32_e32 v4, v13, v4
	v_and_b32_e32 v5, 3, v13
	s_and_b64 s[8:9], s[8:9], exec
	v_and_or_b32 v5, v4, s1, v5
	s_cselect_b32 s1, s33, s31
	s_lshl_b32 s46, s0, 3
	v_lshrrev_b32_e32 v6, 2, v4
	v_lshlrev_b32_e32 v7, 1, v4
	v_and_b32_e32 v3, 0xc0, v3
	s_abs_i32 s47, s46
	v_and_b32_e32 v6, 4, v6
	v_and_b32_e32 v7, 24, v7
	v_sub_u32_e32 v2, v2, v3
	v_cvt_f32_u32_e32 v3, s47
	v_or3_b32 v5, v5, v6, v7
	v_lshlrev_b32_e32 v6, 5, v14
	v_ashrrev_i16_sdwa v2, v184, sext(v2) dst_sel:DWORD dst_unused:UNUSED_PAD src0_sel:DWORD src1_sel:BYTE_0
	v_and_b32_e32 v6, 32, v6
	v_bfe_i32 v15, v2, 0, 16
	v_add_lshl_u32 v2, v6, v15, 1
	v_lshl_add_u32 v158, v5, 11, v2
	v_lshl_add_u32 v160, v4, 11, v2
	v_rcp_iflag_f32_e32 v2, v3
	v_readlane_b32 s4, v253, 60
	s_mul_i32 s1, s1, s4
	v_readlane_b32 s4, v254, 6
	v_mul_f32_e32 v2, 0x4f7ffffe, v2
	v_cvt_u32_f32_e32 v2, v2
	s_sub_i32 s8, 0, s47
	s_add_i32 s1, s1, s4
	s_ashr_i32 s4, s1, 31
	v_readfirstlane_b32 s49, v2
	s_mul_i32 s8, s8, s49
	s_bfe_i32 s48, s0, 0x1001c
	s_mul_hi_u32 s8, s49, s8
	s_xor_b32 s0, s4, s48
	s_abs_i32 s4, s1
	s_add_i32 s49, s49, s8
	s_mul_hi_u32 s8, s4, s49
	s_mul_i32 s9, s8, s47
	s_sub_i32 s4, s4, s9
	s_add_i32 s9, s8, 1
	s_sub_i32 s10, s4, s47
	s_cmp_ge_u32 s4, s47
	s_cselect_b32 s8, s9, s8
	s_cselect_b32 s4, s10, s4
	s_add_i32 s9, s8, 1
	s_cmp_ge_u32 s4, s47
	s_cselect_b32 s4, s9, s8
	s_xor_b32 s4, s4, s0
	s_sub_i32 s0, s4, s0
	s_lshl_b32 s8, s0, 3
	s_sub_i32 s4, 0x80, s8
	s_min_i32 s9, s4, 8
	s_sext_i32_i16 s4, s9
	v_cvt_f32_i32_e32 v2, s4
	s_mul_i32 s0, s0, s46
	s_sub_i32 s10, s1, s0
	v_cvt_f32_i32_e32 v3, s10
	v_rcp_iflag_f32_e32 v4, v2
	s_xor_b32 s0, s10, s4
	s_ashr_i32 s0, s0, 30
	s_or_b32 s4, s0, 1
	v_mul_f32_e32 v4, v3, v4
	v_trunc_f32_e32 v4, v4
	v_fma_f32 v3, -v4, v2, v3
	v_cvt_i32_f32_e32 v4, v4
	v_cmp_ge_f32_e64 s[0:1], |v3|, |v2|
	s_and_b64 s[0:1], s[0:1], exec
	s_cselect_b32 s0, s4, 0
	v_readfirstlane_b32 s1, v4
	s_add_i32 s4, s1, s0
	s_mul_i32 s0, s4, s9
	s_sub_i32 s0, s10, s0
	s_sext_i32_i16 s0, s0
	s_add_i32 s20, s8, s0
	s_ashr_i32 s21, s20, 31
	s_bfe_i64 s[8:9], s[4:5], 0x100000
	s_lshl_b64 s[0:1], s[20:21], 19
	s_lshl_b64 s[8:9], s[8:9], 19
	s_add_u32 s24, s28, s8
	s_addc_u32 s25, s29, s9
	s_add_i32 s50, s30, 0
	s_add_i32 m0, s50, 0x10000
	v_mov_b32_e32 v159, v1
	global_load_lds_dwordx4 v158, s[24:25]
	s_add_i32 m0, s50, 0x12000
	s_add_u32 s8, s24, 0x40000
	global_load_lds_dwordx4 v154, s[24:25]
	s_addc_u32 s9, s25, 0
	s_add_i32 m0, s50, 0x14000
	v_mov_b32_e32 v155, v1
	global_load_lds_dwordx4 v158, s[8:9]
	s_add_i32 m0, s50, 0x16000
	s_add_u32 s22, s90, s0
	s_addc_u32 s23, s91, s1
	s_add_i32 s51, s50, 0x2000
	global_load_lds_dwordx4 v154, s[8:9]
	s_mov_b32 m0, s50
	s_add_u32 s0, s22, 0x40000
	global_load_lds_dwordx4 v160, s[22:23]
	s_mov_b32 m0, s51
	s_addc_u32 s1, s23, 0
	s_add_i32 s52, s50, 0x4000
	global_load_lds_dwordx4 v156, s[22:23]
	s_mov_b32 m0, s52
	s_add_i32 s53, s50, 0x6000
	global_load_lds_dwordx4 v160, s[0:1]
	s_mov_b32 m0, s53
	v_mov_b32_e32 v161, v1
	global_load_lds_dwordx4 v156, s[0:1]
	v_mov_b32_e32 v157, v1
	s_cmp_eq_u32 s6, 1
	v_lshl_add_u64 v[8:9], s[24:25], 0, v[158:159]
	v_lshl_add_u64 v[6:7], s[24:25], 0, v[154:155]
	v_lshl_add_u64 v[2:3], s[22:23], 0, v[160:161]
	s_cselect_b64 s[0:1], -1, 0
	s_cmp_lg_u32 s6, 1
	v_lshl_add_u64 v[4:5], s[22:23], 0, v[156:157]
	s_cbranch_scc1 .LBB0_552
; #define PG8_STAGE(bufoff, gbase, voff) do { _Pragma("unroll") for (int _i = 0; _i < 2; ++_i) \
;         __builtin_amdgcn_global_load_lds((const unsigned*)((const char*)(gbase) + (voff)[_i]), (PG8_LAS unsigned*)(lds + (bufoff) + ldsw + _i * 8192), 16, 0, 0); } while (0)
; #define PG8_WAIT_V(n) asm volatile("s_waitcnt vmcnt(" #n ")" ::: "memory")
; #define PG8_BAR __builtin_amdgcn_s_barrier()
; template <class Epi, class Sched, bool ALIGN_EPI = false, bool SP2 = false>
; __device__ __forceinline__ void gemm_phase(PG8_LAS unsigned char* lds, const Gemm g, const Sched& S, const Epi& E) {
;     ...
;         PG8_STAGE(PG8_SB(0, 0), cB, voffB); PG8_STAGE(PG8_SB(0, 1), cB + hstep, voffB); PG8_STAGE(PG8_SA(0, 0), cA, voffA); PG8_STAGE(PG8_SA(0, 1), cA + hstep, voffA);
;         if (wr == 1) PG8_BAR;
;         PG8_WAIT_V(2); PG8_BAR;
;         PG8_STAGE(PG8_SB(1, 0), cB + kstep, voffB); PG8_STAGE(PG8_SA(1, 0), cA + kstep, voffA); PG8_STAGE(PG8_SB(1, 1), cB + hstep + kstep, voffB);
;         PG8_WAIT_V(6); PG8_BAR;
.LBB0_552:
	s_and_b64 s[8:9], s[44:45], exec
	s_movk_i32 s8, 0xc00
	s_cselect_b32 s44, s8, 0x1000
	s_cselect_b32 s45, 12, 16
	s_cselect_b32 s54, 0, 8
	s_and_b32 s7, s7, 3
	s_add_i32 m0, s50, 0x18000
	v_lshl_add_u64 v[8:9], v[8:9], 0, s[38:39]
	s_lshl_b32 s10, s6, 13
	s_lshl_b32 s11, s7, 12
	s_waitcnt vmcnt(2)
	s_barrier
	global_load_lds_dwordx4 v[8:9], off
	v_lshl_add_u64 v[6:7], v[6:7], 0, s[38:39]
	s_add_i32 m0, s50, 0x1a000
	s_add_i32 s55, s50, 0x8000
	s_add_i32 s56, s50, 0xa000
	global_load_lds_dwordx4 v[6:7], off
	v_lshl_add_u64 v[2:3], v[2:3], 0, s[38:39]
	s_mov_b32 m0, s55
	s_add_u32 s8, s24, 0x40080
	global_load_lds_dwordx4 v[2:3], off
	v_lshl_add_u64 v[2:3], v[4:5], 0, s[38:39]
	s_mov_b32 m0, s56
	s_addc_u32 s9, s25, 0
	global_load_lds_dwordx4 v[2:3], off
	s_add_i32 m0, s50, 0x1c000
	v_lshl_add_u64 v[2:3], s[8:9], 0, v[158:159]
	global_load_lds_dwordx4 v[2:3], off
	v_lshl_add_u64 v[2:3], s[8:9], 0, v[154:155]
	s_add_i32 m0, s50, 0x1e000
	v_bfe_u32 v4, v0, 4, 2
	global_load_lds_dwordx4 v[2:3], off
	v_and_b32_e32 v3, 15, v0
	v_lshlrev_b32_e32 v5, 4, v4
	v_lshlrev_b32_e32 v0, 2, v0
	v_lshl_or_b32 v174, s6, 6, v3
	v_lshl_or_b32 v3, v3, 6, v5
	v_and_b32_e32 v0, 32, v0
	v_bitop3_b32 v5, v3, s10, v0 bitop3:0xde
	v_bitop3_b32 v175, v3, s11, v0 bitop3:0xde
	v_lshlrev_b32_e32 v3, 14, v14
	v_and_b32_e32 v3, 0xffff8000, v3
	s_sext_i32_i16 s59, s4
	v_lshlrev_b32_e32 v2, 3, v4
	s_cmpk_lt_u32 s5, 0x100
	v_cmp_lt_u32_e64 s[4:5], 1, v4
	v_lshlrev_b32_e32 v0, 5, v4
	v_lshl_add_u32 v3, v13, 11, v3
	v_and_b32_e32 v4, 1, v14
	v_lshl_or_b32 v3, v4, 6, v3
	v_lshl_add_u32 v164, v15, 1, v3
	v_lshlrev_b32_e32 v3, 14, v10
	v_readlane_b32 s12, v253, 40
	v_and_b32_e32 v3, 0xffff8000, v3
	s_waitcnt vmcnt(6)
	v_readlane_b32 s13, v253, 41
	v_lshl_add_u32 v3, v11, 11, v3
	v_and_b32_e32 v4, 1, v10
	s_cselect_b64 s[8:9], -1, 0
	s_cmp_lg_u32 s7, 0
	v_lshl_add_u64 v[162:163], s[12:13], 0, v[0:1]
	v_lshl_or_b32 v0, s7, 5, v2
	v_lshl_or_b32 v3, v4, 6, v3
	s_mov_b32 s57, 0
	s_cselect_b64 s[10:11], -1, 0
	s_lshr_b32 s58, s54, 1
	v_lshl_or_b32 v176, s7, 6, v2
	v_mov_b32_e32 v165, v1
	v_lshl_add_u32 v166, v12, 1, v3
	v_mov_b32_e32 v167, v1
	v_add_u32_e32 v177, 0, v5
	v_lshlrev_b32_e32 v178, 1, v0
	v_lshlrev_b32_e32 v179, 2, v2
	s_barrier
	s_branch .LBB0_555

; #define PG8_STAGE(bufoff, gbase, voff) do { _Pragma("unroll") for (int _i = 0; _i < 2; ++_i) \
;         __builtin_amdgcn_global_load_lds((const unsigned*)((const char*)(gbase) + (voff)[_i]), (PG8_LAS unsigned*)(lds + (bufoff) + ldsw + _i * 8192), 16, 0, 0); } while (0)
; #define PG8_LDA(dst, b, h) do { _Pragma("unroll") for (int m = 0; m < 4; ++m) _Pragma("unroll") for (int k = 0; k < 2; ++k) dst[m][k] = *(const PG8_LAS bf16x8*)(lds + PG8_SA(b, h) + aoff + m * 2048 + k * 1024); } while (0)
; #define PG8_LDB(dst, b, h) do { _Pragma("unroll") for (int n = 0; n < 2; ++n) _Pragma("unroll") for (int k = 0; k < 2; ++k) dst[n][k] = *(const PG8_LAS bf16x8*)(lds + PG8_SB(b, h) + boff + n * 2048 + k * 1024); } while (0)
; #define PG8_WAIT_V(n) asm volatile("s_waitcnt vmcnt(" #n ")" ::: "memory")
; #define PG8_WAIT_L(n) asm volatile("s_waitcnt lgkmcnt(" #n ")" ::: "memory")
; #define PG8_BAR __builtin_amdgcn_s_barrier()
; #define PG8_SCHED __builtin_amdgcn_sched_barrier(0)
; template <class Epi, class Sched, bool ALIGN_EPI = false, bool SP2 = false>
; __device__ __forceinline__ void gemm_phase(PG8_LAS unsigned char* lds, const Gemm g, const Sched& S, const Epi& E) {
;     ...
;         const bool has_next = S.next(ui + 1, nxt);
;         const char* nA = has_next ? (const char*)g.A + (size_t)nxt.pm * tstep : cA; const char* nB = has_next ? (const char*)g.Bt + (size_t)nxt.pn * tstep : cB;
;         for (int t = 0; t < nt; t += 2) {
;             const bool last = (t == nt - 2);
;             const char* a1 = cA + (size_t)(t + 1) * kstep;
;             const char* a2 = last ? nA : cA + (size_t)(t + 2) * kstep; const char* b2 = last ? nB : cB + (size_t)(t + 2) * kstep;
;             const char* a3 = a2 + kstep; const char* b3 = b2 + kstep;
;             if (last && has_next) S.a_ready(nxt);
;             if constexpr (SP2) {
;             PG8_LDB(B0, 0, 0); PG8_LDB(B1, 0, 1); PG8_SCHED; PG8_LDA(At, 0, 0); PG8_STAGE(PG8_SA(1, 1), a1 + hstep, voffA);
;             PG8_WAIT_V(8); PG8_WAIT_L(0); PG8_BAR; PG8_MMA(0, 0, At, B0); PG8_MMA(0, 1, At, B1); PG8_BAR; PG8_SCHED;
;             PG8_LDA(At, 0, 1); PG8_STAGE(PG8_SB(0, 0), b2, voffB); PG8_STAGE(PG8_SB(0, 1), b2 + hstep, voffB); PG8_STAGE(PG8_SA(0, 0), a2, voffA);
;             PG8_WAIT_V(8); PG8_WAIT_L(0); PG8_BAR; PG8_MMA(1, 0, At, B0); PG8_MMA(1, 1, At, B1); PG8_BAR; PG8_SCHED;
.LBB0_557:
	s_ashr_i32 s15, s14, 31
	s_lshl_b64 s[16:17], s[14:15], 19
	s_add_u32 s16, s90, s16
	s_addc_u32 s17, s91, s17
	s_and_b64 s[18:19], s[6:7], exec
	s_cselect_b32 s15, s17, s23
	s_cselect_b32 s21, s16, s22
	s_ashr_i32 s13, s12, 31
	s_lshl_b64 s[18:19], s[12:13], 19
	s_add_u32 s18, s28, s18
	s_addc_u32 s19, s29, s19
	s_and_b64 s[26:27], s[6:7], exec
	s_cselect_b32 s13, s19, s25
	s_cselect_b32 s60, s18, s24
	s_add_u32 s22, s22, 0x40080
	s_addc_u32 s23, s23, 0
	s_add_u32 s61, s24, 0x100
	s_addc_u32 s62, s25, 0
	s_mov_b32 s63, -2
	s_waitcnt vmcnt(0)
	s_add_u32 s24, s22, 0xfffc0080
	s_addc_u32 s25, s23, -1
	s_add_i32 s64, 0, 0x10000
	s_cmp_eq_u32 s63, 12
	s_cselect_b32 s27, s15, s25
	s_cselect_b32 s26, s21, s24
	v_add_u32_e32 v0, s64, v175
	s_cselect_b32 s25, s13, s62
	s_cselect_b32 s24, s60, s61
	s_add_i32 s66, 0, 0x14000
	ds_read_b128 v[130:133], v0
	ds_read_b128 v[134:137], v0 offset:1024
	ds_read_b128 v[138:141], v0 offset:2048
	ds_read_b128 v[142:145], v0 offset:3072
	v_add_u32_e32 v0, s66, v175
	ds_read_b128 v[168:171], v0
	ds_read_b128 v[200:203], v0 offset:1024
	ds_read_b128 v[204:207], v0 offset:2048
	ds_read_b128 v[208:211], v0 offset:3072
	v_lshl_add_u64 v[146:147], s[22:23], 0, v[164:165]
	s_add_i32 m0, s50, 0xc000
	ds_read_b128 v[212:215], v177
	ds_read_b128 v[216:219], v177 offset:1024
	ds_read_b128 v[220:223], v177 offset:2048
	ds_read_b128 v[224:227], v177 offset:3072
	ds_read_b128 v[228:231], v177 offset:4096
	ds_read_b128 v[232:235], v177 offset:5120
	ds_read_b128 v[236:239], v177 offset:6144
	ds_read_b128 v[240:243], v177 offset:7168
	global_load_lds_dwordx4 v[146:147], off
	v_lshl_add_u64 v[146:147], s[22:23], 0, v[166:167]
	s_add_i32 m0, s50, 0xe000
	s_nop 0
	global_load_lds_dwordx4 v[146:147], off
	s_waitcnt vmcnt(8)
	s_waitcnt lgkmcnt(0)
	s_and_b64 vcc, exec, s[8:9]
	s_cbranch_vccnz .Lpe_558
	s_barrier
.Lpe_558:
	s_setprio 1
	s_waitcnt lgkmcnt(0)
	v_mfma_f32_16x16x32_bf16 v[126:129], v[130:133], v[212:215], 0
	v_mfma_f32_16x16x32_bf16 v[122:125], v[138:141], v[212:215], 0
	v_mfma_f32_16x16x32_bf16 v[114:117], v[130:133], v[220:223], 0
	v_mfma_f32_16x16x32_bf16 v[106:109], v[138:141], v[220:223], 0
	v_mfma_f32_16x16x32_bf16 v[94:97], v[130:133], v[228:231], 0
	v_mfma_f32_16x16x32_bf16 v[90:93], v[138:141], v[228:231], 0
	v_mfma_f32_16x16x32_bf16 v[82:85], v[130:133], v[236:239], 0
	v_mfma_f32_16x16x32_bf16 v[74:77], v[138:141], v[236:239], 0
	v_mfma_f32_16x16x32_bf16 v[126:129], v[134:137], v[216:219], v[126:129]
	v_mfma_f32_16x16x32_bf16 v[122:125], v[142:145], v[216:219], v[122:125]
	v_mfma_f32_16x16x32_bf16 v[114:117], v[134:137], v[224:227], v[114:117]
	v_mfma_f32_16x16x32_bf16 v[106:109], v[142:145], v[224:227], v[106:109]
	v_mfma_f32_16x16x32_bf16 v[94:97], v[134:137], v[232:235], v[94:97]
	v_mfma_f32_16x16x32_bf16 v[90:93], v[142:145], v[232:235], v[90:93]
	v_mfma_f32_16x16x32_bf16 v[82:85], v[134:137], v[240:243], v[82:85]
	v_mfma_f32_16x16x32_bf16 v[74:77], v[142:145], v[240:243], v[74:77]
	s_setprio 0
	s_setprio 1
	v_mfma_f32_16x16x32_bf16 v[118:121], v[168:171], v[212:215], 0
	v_mfma_f32_16x16x32_bf16 v[110:113], v[204:207], v[212:215], 0
	v_mfma_f32_16x16x32_bf16 v[102:105], v[168:171], v[220:223], 0
	v_mfma_f32_16x16x32_bf16 v[98:101], v[204:207], v[220:223], 0
	v_mfma_f32_16x16x32_bf16 v[86:89], v[168:171], v[228:231], 0
	v_mfma_f32_16x16x32_bf16 v[78:81], v[204:207], v[228:231], 0
	v_mfma_f32_16x16x32_bf16 v[70:73], v[168:171], v[236:239], 0
	v_mfma_f32_16x16x32_bf16 v[66:69], v[204:207], v[236:239], 0
	v_mfma_f32_16x16x32_bf16 v[118:121], v[200:203], v[216:219], v[118:121]
	v_mfma_f32_16x16x32_bf16 v[110:113], v[208:211], v[216:219], v[110:113]
	v_mfma_f32_16x16x32_bf16 v[102:105], v[200:203], v[224:227], v[102:105]
	v_mfma_f32_16x16x32_bf16 v[98:101], v[208:211], v[224:227], v[98:101]
	v_mfma_f32_16x16x32_bf16 v[86:89], v[200:203], v[232:235], v[86:89]
	v_mfma_f32_16x16x32_bf16 v[78:81], v[208:211], v[232:235], v[78:81]
	v_mfma_f32_16x16x32_bf16 v[70:73], v[200:203], v[240:243], v[70:73]
	v_mfma_f32_16x16x32_bf16 v[66:69], v[208:211], v[240:243], v[66:69]
	s_setprio 0
	s_barrier
	s_add_i32 s64, s64, s30
	v_lshl_add_u64 v[146:147], s[24:25], 0, v[158:159]
	s_mov_b32 m0, s64
	ds_read_b128 v[212:215], v177 offset:16384
	ds_read_b128 v[216:219], v177 offset:17408
	ds_read_b128 v[220:223], v177 offset:18432
	ds_read_b128 v[224:227], v177 offset:19456
	ds_read_b128 v[228:231], v177 offset:20480
	ds_read_b128 v[232:235], v177 offset:21504
	ds_read_b128 v[236:239], v177 offset:22528
	ds_read_b128 v[240:243], v177 offset:23552
	global_load_lds_dwordx4 v[146:147], off
	s_add_i32 m0, s64, 0x2000
	s_add_u32 s64, s24, 0x40000
	v_lshl_add_u64 v[148:149], s[24:25], 0, v[154:155]
	s_addc_u32 s65, s25, 0
	s_add_i32 s66, s66, s30
	global_load_lds_dwordx4 v[148:149], off
	v_lshl_add_u64 v[172:173], s[64:65], 0, v[158:159]
	s_mov_b32 m0, s66
	v_lshl_add_u64 v[180:181], s[26:27], 0, v[156:157]
	global_load_lds_dwordx4 v[172:173], off
	v_lshl_add_u64 v[172:173], s[64:65], 0, v[154:155]
	s_add_i32 m0, s66, 0x2000
	s_nop 0
	global_load_lds_dwordx4 v[172:173], off
	v_lshl_add_u64 v[172:173], s[26:27], 0, v[160:161]
	s_mov_b32 m0, s50
	s_nop 0
	global_load_lds_dwordx4 v[172:173], off
	s_mov_b32 m0, s51
	s_nop 0
	global_load_lds_dwordx4 v[180:181], off
	s_waitcnt vmcnt(8)
	s_waitcnt lgkmcnt(0)
	s_barrier
; #define PG8_STAGE(bufoff, gbase, voff) do { _Pragma("unroll") for (int _i = 0; _i < 2; ++_i) \
;         __builtin_amdgcn_global_load_lds((const unsigned*)((const char*)(gbase) + (voff)[_i]), (PG8_LAS unsigned*)(lds + (bufoff) + ldsw + _i * 8192), 16, 0, 0); } while (0)
; #define PG8_LDA(dst, b, h) do { _Pragma("unroll") for (int m = 0; m < 4; ++m) _Pragma("unroll") for (int k = 0; k < 2; ++k) dst[m][k] = *(const PG8_LAS bf16x8*)(lds + PG8_SA(b, h) + aoff + m * 2048 + k * 1024); } while (0)
; #define PG8_LDB(dst, b, h) do { _Pragma("unroll") for (int n = 0; n < 2; ++n) _Pragma("unroll") for (int k = 0; k < 2; ++k) dst[n][k] = *(const PG8_LAS bf16x8*)(lds + PG8_SB(b, h) + boff + n * 2048 + k * 1024); } while (0)
; #define PG8_MMA(ai, bj, At, Bt) do { __builtin_amdgcn_s_setprio(1); _Pragma("unroll") for (int m = 0; m < 4; ++m) _Pragma("unroll") for (int n = 0; n < 2; ++n) _Pragma("unroll") for (int k = 0; k < 2; ++k) \
;         acc[ai][bj][m][n] = __builtin_amdgcn_mfma_f32_16x16x32_bf16(Bt[n][k], At[m][k], acc[ai][bj][m][n], 0, 0, 0); __builtin_amdgcn_s_setprio(0); } while (0)
; #define PG8_WAIT_V(n) asm volatile("s_waitcnt vmcnt(" #n ")" ::: "memory")
; #define PG8_WAIT_L(n) asm volatile("s_waitcnt lgkmcnt(" #n ")" ::: "memory")
; #define PG8_BAR __builtin_amdgcn_s_barrier()
; #define PG8_SCHED __builtin_amdgcn_sched_barrier(0)
; template <class Epi, class Sched, bool ALIGN_EPI = false, bool SP2 = false>
; __device__ __forceinline__ void gemm_phase(PG8_LAS unsigned char* lds, const Gemm g, const Sched& S, const Epi& E) {
;     ...
;             PG8_WAIT_V(8); PG8_WAIT_L(0); PG8_BAR; PG8_MMA(1, 0, At, B0); PG8_MMA(1, 1, At, B1); PG8_BAR; PG8_SCHED;
;             PG8_LDB(B0, 1, 0); PG8_LDB(B1, 1, 1); PG8_SCHED; PG8_LDA(At, 1, 0); PG8_STAGE(PG8_SA(0, 1), a2 + hstep, voffA);
;             PG8_WAIT_V(8); PG8_WAIT_L(0); PG8_BAR; PG8_MMA(0, 0, At, B0); PG8_MMA(0, 1, At, B1); PG8_BAR; PG8_SCHED;
	s_setprio 1
	s_waitcnt lgkmcnt(0)
	v_mfma_f32_16x16x32_bf16 v[62:65], v[130:133], v[212:215], 0
	v_mfma_f32_16x16x32_bf16 v[58:61], v[138:141], v[212:215], 0
	v_mfma_f32_16x16x32_bf16 v[50:53], v[130:133], v[220:223], 0
	v_mfma_f32_16x16x32_bf16 v[42:45], v[138:141], v[220:223], 0
	v_mfma_f32_16x16x32_bf16 v[30:33], v[130:133], v[228:231], 0
	v_mfma_f32_16x16x32_bf16 v[26:29], v[138:141], v[228:231], 0
	v_mfma_f32_16x16x32_bf16 v[18:21], v[130:133], v[236:239], 0
	v_mfma_f32_16x16x32_bf16 v[10:13], v[138:141], v[236:239], 0
	v_mfma_f32_16x16x32_bf16 v[62:65], v[134:137], v[216:219], v[62:65]
	v_mfma_f32_16x16x32_bf16 v[58:61], v[142:145], v[216:219], v[58:61]
	v_mfma_f32_16x16x32_bf16 v[50:53], v[134:137], v[224:227], v[50:53]
	v_mfma_f32_16x16x32_bf16 v[42:45], v[142:145], v[224:227], v[42:45]
	v_mfma_f32_16x16x32_bf16 v[30:33], v[134:137], v[232:235], v[30:33]
	v_mfma_f32_16x16x32_bf16 v[26:29], v[142:145], v[232:235], v[26:29]
	v_mfma_f32_16x16x32_bf16 v[18:21], v[134:137], v[240:243], v[18:21]
	v_mfma_f32_16x16x32_bf16 v[10:13], v[142:145], v[240:243], v[10:13]
	s_setprio 0
	s_setprio 1
	v_mfma_f32_16x16x32_bf16 v[54:57], v[168:171], v[212:215], 0
	v_mfma_f32_16x16x32_bf16 v[46:49], v[204:207], v[212:215], 0
	v_mfma_f32_16x16x32_bf16 v[38:41], v[168:171], v[220:223], 0
	v_mfma_f32_16x16x32_bf16 v[34:37], v[204:207], v[220:223], 0
	v_mfma_f32_16x16x32_bf16 v[22:25], v[168:171], v[228:231], 0
	v_mfma_f32_16x16x32_bf16 v[14:17], v[204:207], v[228:231], 0
	v_mfma_f32_16x16x32_bf16 v[6:9], v[168:171], v[236:239], 0
	v_mfma_f32_16x16x32_bf16 v[2:5], v[204:207], v[236:239], 0
	v_mfma_f32_16x16x32_bf16 v[54:57], v[200:203], v[216:219], v[54:57]
	v_mfma_f32_16x16x32_bf16 v[46:49], v[208:211], v[216:219], v[46:49]
	v_mfma_f32_16x16x32_bf16 v[38:41], v[200:203], v[224:227], v[38:41]
	v_mfma_f32_16x16x32_bf16 v[34:37], v[208:211], v[224:227], v[34:37]
	v_mfma_f32_16x16x32_bf16 v[22:25], v[200:203], v[232:235], v[22:25]
	v_mfma_f32_16x16x32_bf16 v[14:17], v[208:211], v[232:235], v[14:17]
	v_mfma_f32_16x16x32_bf16 v[6:9], v[200:203], v[240:243], v[6:9]
	v_mfma_f32_16x16x32_bf16 v[2:5], v[208:211], v[240:243], v[2:5]
	s_setprio 0
	s_barrier
	s_add_i32 s64, 0, 0x18000
	v_add_u32_e32 v0, s64, v175
	s_add_i32 s65, 0, 0x1c000
	ds_read_b128 v[130:133], v0
	ds_read_b128 v[134:137], v0 offset:1024
	ds_read_b128 v[138:141], v0 offset:2048
	ds_read_b128 v[142:145], v0 offset:3072
	v_add_u32_e32 v0, s65, v175
	ds_read_b128 v[168:171], v0
	ds_read_b128 v[200:203], v0 offset:1024
	ds_read_b128 v[204:207], v0 offset:2048
	ds_read_b128 v[208:211], v0 offset:3072
	s_add_u32 s26, s26, 0x40000
	s_addc_u32 s27, s27, 0
	s_mov_b32 m0, s52
	v_lshl_add_u64 v[244:245], s[26:27], 0, v[160:161]
	ds_read_b128 v[212:215], v177 offset:32768
	ds_read_b128 v[216:219], v177 offset:33792
	ds_read_b128 v[220:223], v177 offset:34816
	ds_read_b128 v[224:227], v177 offset:35840
	ds_read_b128 v[228:231], v177 offset:36864
	ds_read_b128 v[232:235], v177 offset:37888
	ds_read_b128 v[236:239], v177 offset:38912
	ds_read_b128 v[240:243], v177 offset:39936
	global_load_lds_dwordx4 v[244:245], off
	v_lshl_add_u64 v[244:245], s[26:27], 0, v[156:157]
	s_mov_b32 m0, s53
	s_nop 0
	global_load_lds_dwordx4 v[244:245], off
	s_waitcnt vmcnt(8)
	s_waitcnt lgkmcnt(0)
	s_barrier
	s_setprio 1
	s_waitcnt lgkmcnt(0)
	v_mfma_f32_16x16x32_bf16 v[126:129], v[130:133], v[212:215], v[126:129]
	v_mfma_f32_16x16x32_bf16 v[122:125], v[138:141], v[212:215], v[122:125]
	v_mfma_f32_16x16x32_bf16 v[114:117], v[130:133], v[220:223], v[114:117]
	v_mfma_f32_16x16x32_bf16 v[106:109], v[138:141], v[220:223], v[106:109]
	v_mfma_f32_16x16x32_bf16 v[94:97], v[130:133], v[228:231], v[94:97]
	v_mfma_f32_16x16x32_bf16 v[90:93], v[138:141], v[228:231], v[90:93]
	v_mfma_f32_16x16x32_bf16 v[82:85], v[130:133], v[236:239], v[82:85]
	v_mfma_f32_16x16x32_bf16 v[74:77], v[138:141], v[236:239], v[74:77]
	v_mfma_f32_16x16x32_bf16 v[126:129], v[134:137], v[216:219], v[126:129]
	v_mfma_f32_16x16x32_bf16 v[122:125], v[142:145], v[216:219], v[122:125]
	v_mfma_f32_16x16x32_bf16 v[114:117], v[134:137], v[224:227], v[114:117]
	v_mfma_f32_16x16x32_bf16 v[106:109], v[142:145], v[224:227], v[106:109]
	v_mfma_f32_16x16x32_bf16 v[94:97], v[134:137], v[232:235], v[94:97]
	v_mfma_f32_16x16x32_bf16 v[90:93], v[142:145], v[232:235], v[90:93]
	v_mfma_f32_16x16x32_bf16 v[82:85], v[134:137], v[240:243], v[82:85]
	v_mfma_f32_16x16x32_bf16 v[74:77], v[142:145], v[240:243], v[74:77]
	s_setprio 0
	s_setprio 1
	v_mfma_f32_16x16x32_bf16 v[118:121], v[168:171], v[212:215], v[118:121]
	v_mfma_f32_16x16x32_bf16 v[110:113], v[204:207], v[212:215], v[110:113]
	v_mfma_f32_16x16x32_bf16 v[102:105], v[168:171], v[220:223], v[102:105]
	v_mfma_f32_16x16x32_bf16 v[98:101], v[204:207], v[220:223], v[98:101]
	v_mfma_f32_16x16x32_bf16 v[86:89], v[168:171], v[228:231], v[86:89]
	v_mfma_f32_16x16x32_bf16 v[78:81], v[204:207], v[228:231], v[78:81]
	v_mfma_f32_16x16x32_bf16 v[70:73], v[168:171], v[236:239], v[70:73]
	v_mfma_f32_16x16x32_bf16 v[66:69], v[204:207], v[236:239], v[66:69]
	v_mfma_f32_16x16x32_bf16 v[118:121], v[200:203], v[216:219], v[118:121]
	v_mfma_f32_16x16x32_bf16 v[110:113], v[208:211], v[216:219], v[110:113]
	v_mfma_f32_16x16x32_bf16 v[102:105], v[200:203], v[224:227], v[102:105]
	v_mfma_f32_16x16x32_bf16 v[98:101], v[208:211], v[224:227], v[98:101]
	v_mfma_f32_16x16x32_bf16 v[86:89], v[200:203], v[232:235], v[86:89]
	v_mfma_f32_16x16x32_bf16 v[78:81], v[208:211], v[232:235], v[78:81]
	v_mfma_f32_16x16x32_bf16 v[70:73], v[200:203], v[240:243], v[70:73]
	v_mfma_f32_16x16x32_bf16 v[66:69], v[208:211], v[240:243], v[66:69]
	s_setprio 0
	s_barrier
; #define PG8_STAGE(bufoff, gbase, voff) do { _Pragma("unroll") for (int _i = 0; _i < 2; ++_i) \
;         __builtin_amdgcn_global_load_lds((const unsigned*)((const char*)(gbase) + (voff)[_i]), (PG8_LAS unsigned*)(lds + (bufoff) + ldsw + _i * 8192), 16, 0, 0); } while (0)
; #define PG8_LDA(dst, b, h) do { _Pragma("unroll") for (int m = 0; m < 4; ++m) _Pragma("unroll") for (int k = 0; k < 2; ++k) dst[m][k] = *(const PG8_LAS bf16x8*)(lds + PG8_SA(b, h) + aoff + m * 2048 + k * 1024); } while (0)
; #define PG8_LDB(dst, b, h) do { _Pragma("unroll") for (int n = 0; n < 2; ++n) _Pragma("unroll") for (int k = 0; k < 2; ++k) dst[n][k] = *(const PG8_LAS bf16x8*)(lds + PG8_SB(b, h) + boff + n * 2048 + k * 1024); } while (0)
; #define PG8_MMA(ai, bj, At, Bt) do { __builtin_amdgcn_s_setprio(1); _Pragma("unroll") for (int m = 0; m < 4; ++m) _Pragma("unroll") for (int n = 0; n < 2; ++n) _Pragma("unroll") for (int k = 0; k < 2; ++k) \
;         acc[ai][bj][m][n] = __builtin_amdgcn_mfma_f32_16x16x32_bf16(Bt[n][k], At[m][k], acc[ai][bj][m][n], 0, 0, 0); __builtin_amdgcn_s_setprio(0); } while (0)
; #define PG8_WAIT_V(n) asm volatile("s_waitcnt vmcnt(" #n ")" ::: "memory")
; template <class Epi, class Sched, bool ALIGN_EPI = false, bool SP2 = false>
; __device__ __forceinline__ void gemm_phase(PG8_LAS unsigned char* lds, const Gemm g, const Sched& S, const Epi& E) {
;     ...
;             PG8_LDB(B0, 0, 0); PG8_LDB(B1, 0, 1); PG8_SCHED; PG8_LDA(At, 0, 0); PG8_STAGE(PG8_SA(1, 1), a1 + hstep, voffA);
;             PG8_WAIT_V(8); PG8_WAIT_L(0); PG8_BAR; PG8_MMA(0, 0, At, B0); PG8_MMA(0, 1, At, B1); PG8_BAR; PG8_SCHED;
;             PG8_LDA(At, 0, 1); PG8_STAGE(PG8_SB(0, 0), b2, voffB); PG8_STAGE(PG8_SB(0, 1), b2 + hstep, voffB); PG8_STAGE(PG8_SA(0, 0), a2, voffA);
;             PG8_WAIT_V(8); PG8_WAIT_L(0); PG8_BAR; PG8_MMA(1, 0, At, B0); PG8_MMA(1, 1, At, B1); PG8_BAR; PG8_SCHED;
;             PG8_LDB(B0, 1, 0); PG8_LDB(B1, 1, 1); PG8_SCHED; PG8_LDA(At, 1, 0); PG8_STAGE(PG8_SA(0, 1), a2 + hstep, voffA);
;             PG8_WAIT_V(8); PG8_WAIT_L(0); PG8_BAR; PG8_MMA(0, 0, At, B0); PG8_MMA(0, 1, At, B1); PG8_BAR; PG8_SCHED;
;             PG8_LDA(At, 1, 1); PG8_STAGE(PG8_SB(1, 0), b3, voffB); PG8_STAGE(PG8_SB(1, 1), b3 + hstep, voffB); PG8_STAGE(PG8_SA(1, 0), a3, voffA);
;             PG8_WAIT_V(8); PG8_WAIT_L(0); PG8_BAR; PG8_MMA(1, 0, At, B0); PG8_MMA(1, 1, At, B1); PG8_BAR; PG8_SCHED;
	s_add_i32 s26, s64, s30
	v_lshl_add_u64 v[146:147], v[146:147], 0, s[38:39]
	s_mov_b32 m0, s26
	ds_read_b128 v[212:215], v177 offset:49152
	ds_read_b128 v[216:219], v177 offset:50176
	ds_read_b128 v[220:223], v177 offset:51200
	ds_read_b128 v[224:227], v177 offset:52224
	ds_read_b128 v[228:231], v177 offset:53248
	ds_read_b128 v[232:235], v177 offset:54272
	ds_read_b128 v[236:239], v177 offset:55296
	ds_read_b128 v[240:243], v177 offset:56320
	global_load_lds_dwordx4 v[146:147], off
	s_add_i32 m0, s26, 0x2000
	s_add_u32 s24, s24, 0x40080
	v_lshl_add_u64 v[146:147], v[148:149], 0, s[38:39]
	s_addc_u32 s25, s25, 0
	s_add_i32 s26, s65, s30
	global_load_lds_dwordx4 v[146:147], off
	v_lshl_add_u64 v[146:147], s[24:25], 0, v[158:159]
	s_mov_b32 m0, s26
	s_nop 0
	global_load_lds_dwordx4 v[146:147], off
	v_lshl_add_u64 v[146:147], s[24:25], 0, v[154:155]
	s_add_i32 m0, s26, 0x2000
	s_nop 0
	global_load_lds_dwordx4 v[146:147], off
	v_lshl_add_u64 v[146:147], v[172:173], 0, s[38:39]
	s_mov_b32 m0, s55
	s_nop 0
	global_load_lds_dwordx4 v[146:147], off
	v_lshl_add_u64 v[146:147], v[180:181], 0, s[38:39]
	s_mov_b32 m0, s56
	s_nop 0
	global_load_lds_dwordx4 v[146:147], off
	s_waitcnt vmcnt(8)
	s_waitcnt lgkmcnt(0)
	s_barrier
	s_setprio 1
	s_waitcnt lgkmcnt(0)
	v_mfma_f32_16x16x32_bf16 v[62:65], v[130:133], v[212:215], v[62:65]
	v_mfma_f32_16x16x32_bf16 v[58:61], v[138:141], v[212:215], v[58:61]
	v_mfma_f32_16x16x32_bf16 v[50:53], v[130:133], v[220:223], v[50:53]
	v_mfma_f32_16x16x32_bf16 v[42:45], v[138:141], v[220:223], v[42:45]
	v_mfma_f32_16x16x32_bf16 v[30:33], v[130:133], v[228:231], v[30:33]
	v_mfma_f32_16x16x32_bf16 v[26:29], v[138:141], v[228:231], v[26:29]
	v_mfma_f32_16x16x32_bf16 v[18:21], v[130:133], v[236:239], v[18:21]
	v_mfma_f32_16x16x32_bf16 v[10:13], v[138:141], v[236:239], v[10:13]
	v_mfma_f32_16x16x32_bf16 v[62:65], v[134:137], v[216:219], v[62:65]
	v_mfma_f32_16x16x32_bf16 v[58:61], v[142:145], v[216:219], v[58:61]
	v_mfma_f32_16x16x32_bf16 v[50:53], v[134:137], v[224:227], v[50:53]
	v_mfma_f32_16x16x32_bf16 v[42:45], v[142:145], v[224:227], v[42:45]
	v_mfma_f32_16x16x32_bf16 v[30:33], v[134:137], v[232:235], v[30:33]
	v_mfma_f32_16x16x32_bf16 v[26:29], v[142:145], v[232:235], v[26:29]
	v_mfma_f32_16x16x32_bf16 v[18:21], v[134:137], v[240:243], v[18:21]
	v_mfma_f32_16x16x32_bf16 v[10:13], v[142:145], v[240:243], v[10:13]
	s_setprio 0
	s_setprio 1
	v_mfma_f32_16x16x32_bf16 v[54:57], v[168:171], v[212:215], v[54:57]
	v_mfma_f32_16x16x32_bf16 v[46:49], v[204:207], v[212:215], v[46:49]
	v_mfma_f32_16x16x32_bf16 v[38:41], v[168:171], v[220:223], v[38:41]
	v_mfma_f32_16x16x32_bf16 v[34:37], v[204:207], v[220:223], v[34:37]
	v_mfma_f32_16x16x32_bf16 v[22:25], v[168:171], v[228:231], v[22:25]
	v_mfma_f32_16x16x32_bf16 v[14:17], v[204:207], v[228:231], v[14:17]
	v_mfma_f32_16x16x32_bf16 v[6:9], v[168:171], v[236:239], v[6:9]
	v_mfma_f32_16x16x32_bf16 v[2:5], v[204:207], v[236:239], v[2:5]
	v_mfma_f32_16x16x32_bf16 v[54:57], v[200:203], v[216:219], v[54:57]
	v_mfma_f32_16x16x32_bf16 v[46:49], v[208:211], v[216:219], v[46:49]
	v_mfma_f32_16x16x32_bf16 v[38:41], v[200:203], v[224:227], v[38:41]
	v_mfma_f32_16x16x32_bf16 v[34:37], v[208:211], v[224:227], v[34:37]
	v_mfma_f32_16x16x32_bf16 v[22:25], v[200:203], v[232:235], v[22:25]
	v_mfma_f32_16x16x32_bf16 v[14:17], v[208:211], v[232:235], v[14:17]
	v_mfma_f32_16x16x32_bf16 v[6:9], v[200:203], v[240:243], v[6:9]
	v_mfma_f32_16x16x32_bf16 v[2:5], v[208:211], v[240:243], v[2:5]
	s_setprio 0
	s_barrier
	s_add_i32 s63, s63, 2
	s_add_u32 s22, s22, 0x100
	s_addc_u32 s23, s23, 0
	s_add_u32 s61, s61, 0x100
	s_addc_u32 s62, s62, 0
.LBB0_558:
	s_add_u32 s24, s22, 0xfffc0080
	s_addc_u32 s25, s23, -1
	s_add_i32 s64, 0, 0x10000
	s_cmp_eq_u32 s63, 12
	s_cselect_b32 s27, s15, s25
	s_cselect_b32 s26, s21, s24
	v_add_u32_e32 v0, s64, v175
	s_cselect_b32 s25, s13, s62
	s_cselect_b32 s24, s60, s61
	s_add_i32 s66, 0, 0x14000
	ds_read_b128 v[130:133], v0
	ds_read_b128 v[134:137], v0 offset:1024
	ds_read_b128 v[138:141], v0 offset:2048
	ds_read_b128 v[142:145], v0 offset:3072
	v_add_u32_e32 v0, s66, v175
	ds_read_b128 v[168:171], v0
	ds_read_b128 v[200:203], v0 offset:1024
	ds_read_b128 v[204:207], v0 offset:2048
	ds_read_b128 v[208:211], v0 offset:3072
	v_lshl_add_u64 v[146:147], s[22:23], 0, v[164:165]
	s_add_i32 m0, s50, 0xc000
	ds_read_b128 v[212:215], v177
	ds_read_b128 v[216:219], v177 offset:1024
	ds_read_b128 v[220:223], v177 offset:2048
	ds_read_b128 v[224:227], v177 offset:3072
	ds_read_b128 v[228:231], v177 offset:4096
	ds_read_b128 v[232:235], v177 offset:5120
	ds_read_b128 v[236:239], v177 offset:6144
	ds_read_b128 v[240:243], v177 offset:7168
	global_load_lds_dwordx4 v[146:147], off
	v_lshl_add_u64 v[146:147], s[22:23], 0, v[166:167]
	s_add_i32 m0, s50, 0xe000
	s_nop 0
	global_load_lds_dwordx4 v[146:147], off
	s_waitcnt vmcnt(8)
	s_waitcnt lgkmcnt(0)
	s_barrier
; #define PG8_STAGE(bufoff, gbase, voff) do { _Pragma("unroll") for (int _i = 0; _i < 2; ++_i) \
;         __builtin_amdgcn_global_load_lds((const unsigned*)((const char*)(gbase) + (voff)[_i]), (PG8_LAS unsigned*)(lds + (bufoff) + ldsw + _i * 8192), 16, 0, 0); } while (0)
; #define PG8_LDA(dst, b, h) do { _Pragma("unroll") for (int m = 0; m < 4; ++m) _Pragma("unroll") for (int k = 0; k < 2; ++k) dst[m][k] = *(const PG8_LAS bf16x8*)(lds + PG8_SA(b, h) + aoff + m * 2048 + k * 1024); } while (0)
; #define PG8_MMA(ai, bj, At, Bt) do { __builtin_amdgcn_s_setprio(1); _Pragma("unroll") for (int m = 0; m < 4; ++m) _Pragma("unroll") for (int n = 0; n < 2; ++n) _Pragma("unroll") for (int k = 0; k < 2; ++k) \
;         acc[ai][bj][m][n] = __builtin_amdgcn_mfma_f32_16x16x32_bf16(Bt[n][k], At[m][k], acc[ai][bj][m][n], 0, 0, 0); __builtin_amdgcn_s_setprio(0); } while (0)
; #define PG8_WAIT_V(n) asm volatile("s_waitcnt vmcnt(" #n ")" ::: "memory")
; #define PG8_WAIT_L(n) asm volatile("s_waitcnt lgkmcnt(" #n ")" ::: "memory")
; #define PG8_BAR __builtin_amdgcn_s_barrier()
; #define PG8_SCHED __builtin_amdgcn_sched_barrier(0)
; template <class Epi, class Sched, bool ALIGN_EPI = false, bool SP2 = false>
; __device__ __forceinline__ void gemm_phase(PG8_LAS unsigned char* lds, const Gemm g, const Sched& S, const Epi& E) {
;     ...
;             PG8_WAIT_V(8); PG8_WAIT_L(0); PG8_BAR; PG8_MMA(0, 0, At, B0); PG8_MMA(0, 1, At, B1); PG8_BAR; PG8_SCHED;
;             PG8_LDA(At, 0, 1); PG8_STAGE(PG8_SB(0, 0), b2, voffB); PG8_STAGE(PG8_SB(0, 1), b2 + hstep, voffB); PG8_STAGE(PG8_SA(0, 0), a2, voffA);
;             PG8_WAIT_V(8); PG8_WAIT_L(0); PG8_BAR; PG8_MMA(1, 0, At, B0); PG8_MMA(1, 1, At, B1); PG8_BAR; PG8_SCHED;
	s_setprio 1
	s_waitcnt lgkmcnt(0)
	v_mfma_f32_16x16x32_bf16 v[126:129], v[130:133], v[212:215], v[126:129]
	v_mfma_f32_16x16x32_bf16 v[122:125], v[138:141], v[212:215], v[122:125]
	v_mfma_f32_16x16x32_bf16 v[114:117], v[130:133], v[220:223], v[114:117]
	v_mfma_f32_16x16x32_bf16 v[106:109], v[138:141], v[220:223], v[106:109]
	v_mfma_f32_16x16x32_bf16 v[94:97], v[130:133], v[228:231], v[94:97]
	v_mfma_f32_16x16x32_bf16 v[90:93], v[138:141], v[228:231], v[90:93]
	v_mfma_f32_16x16x32_bf16 v[82:85], v[130:133], v[236:239], v[82:85]
	v_mfma_f32_16x16x32_bf16 v[74:77], v[138:141], v[236:239], v[74:77]
	v_mfma_f32_16x16x32_bf16 v[126:129], v[134:137], v[216:219], v[126:129]
	v_mfma_f32_16x16x32_bf16 v[122:125], v[142:145], v[216:219], v[122:125]
	v_mfma_f32_16x16x32_bf16 v[114:117], v[134:137], v[224:227], v[114:117]
	v_mfma_f32_16x16x32_bf16 v[106:109], v[142:145], v[224:227], v[106:109]
	v_mfma_f32_16x16x32_bf16 v[94:97], v[134:137], v[232:235], v[94:97]
	v_mfma_f32_16x16x32_bf16 v[90:93], v[142:145], v[232:235], v[90:93]
	v_mfma_f32_16x16x32_bf16 v[82:85], v[134:137], v[240:243], v[82:85]
	v_mfma_f32_16x16x32_bf16 v[74:77], v[142:145], v[240:243], v[74:77]
	s_setprio 0
	s_setprio 1
	v_mfma_f32_16x16x32_bf16 v[118:121], v[168:171], v[212:215], v[118:121]
	v_mfma_f32_16x16x32_bf16 v[110:113], v[204:207], v[212:215], v[110:113]
	v_mfma_f32_16x16x32_bf16 v[102:105], v[168:171], v[220:223], v[102:105]
	v_mfma_f32_16x16x32_bf16 v[98:101], v[204:207], v[220:223], v[98:101]
	v_mfma_f32_16x16x32_bf16 v[86:89], v[168:171], v[228:231], v[86:89]
	v_mfma_f32_16x16x32_bf16 v[78:81], v[204:207], v[228:231], v[78:81]
	v_mfma_f32_16x16x32_bf16 v[70:73], v[168:171], v[236:239], v[70:73]
	v_mfma_f32_16x16x32_bf16 v[66:69], v[204:207], v[236:239], v[66:69]
	v_mfma_f32_16x16x32_bf16 v[118:121], v[200:203], v[216:219], v[118:121]
	v_mfma_f32_16x16x32_bf16 v[110:113], v[208:211], v[216:219], v[110:113]
	v_mfma_f32_16x16x32_bf16 v[102:105], v[200:203], v[224:227], v[102:105]
	v_mfma_f32_16x16x32_bf16 v[98:101], v[208:211], v[224:227], v[98:101]
	v_mfma_f32_16x16x32_bf16 v[86:89], v[200:203], v[232:235], v[86:89]
	v_mfma_f32_16x16x32_bf16 v[78:81], v[208:211], v[232:235], v[78:81]
	v_mfma_f32_16x16x32_bf16 v[70:73], v[200:203], v[240:243], v[70:73]
	v_mfma_f32_16x16x32_bf16 v[66:69], v[208:211], v[240:243], v[66:69]
	s_setprio 0
	s_barrier
	s_add_i32 s64, s64, s30
	v_lshl_add_u64 v[146:147], s[24:25], 0, v[158:159]
	s_mov_b32 m0, s64
	ds_read_b128 v[212:215], v177 offset:16384
	ds_read_b128 v[216:219], v177 offset:17408
	ds_read_b128 v[220:223], v177 offset:18432
	ds_read_b128 v[224:227], v177 offset:19456
	ds_read_b128 v[228:231], v177 offset:20480
	ds_read_b128 v[232:235], v177 offset:21504
	ds_read_b128 v[236:239], v177 offset:22528
	ds_read_b128 v[240:243], v177 offset:23552
	global_load_lds_dwordx4 v[146:147], off
	s_add_i32 m0, s64, 0x2000
	s_add_u32 s64, s24, 0x40000
	v_lshl_add_u64 v[148:149], s[24:25], 0, v[154:155]
	s_addc_u32 s65, s25, 0
	s_add_i32 s66, s66, s30
	global_load_lds_dwordx4 v[148:149], off
	v_lshl_add_u64 v[172:173], s[64:65], 0, v[158:159]
	s_mov_b32 m0, s66
	v_lshl_add_u64 v[180:181], s[26:27], 0, v[156:157]
	global_load_lds_dwordx4 v[172:173], off
	v_lshl_add_u64 v[172:173], s[64:65], 0, v[154:155]
	s_add_i32 m0, s66, 0x2000
	s_nop 0
	global_load_lds_dwordx4 v[172:173], off
	v_lshl_add_u64 v[172:173], s[26:27], 0, v[160:161]
	s_mov_b32 m0, s50
	s_nop 0
	global_load_lds_dwordx4 v[172:173], off
	s_mov_b32 m0, s51
	s_nop 0
	global_load_lds_dwordx4 v[180:181], off
	s_waitcnt vmcnt(8)
	s_waitcnt lgkmcnt(0)
	s_barrier
	s_setprio 1
	s_waitcnt lgkmcnt(0)
	v_mfma_f32_16x16x32_bf16 v[62:65], v[130:133], v[212:215], v[62:65]
	v_mfma_f32_16x16x32_bf16 v[58:61], v[138:141], v[212:215], v[58:61]
	v_mfma_f32_16x16x32_bf16 v[50:53], v[130:133], v[220:223], v[50:53]
	v_mfma_f32_16x16x32_bf16 v[42:45], v[138:141], v[220:223], v[42:45]
	v_mfma_f32_16x16x32_bf16 v[30:33], v[130:133], v[228:231], v[30:33]
	v_mfma_f32_16x16x32_bf16 v[26:29], v[138:141], v[228:231], v[26:29]
	v_mfma_f32_16x16x32_bf16 v[18:21], v[130:133], v[236:239], v[18:21]
	v_mfma_f32_16x16x32_bf16 v[10:13], v[138:141], v[236:239], v[10:13]
	v_mfma_f32_16x16x32_bf16 v[62:65], v[134:137], v[216:219], v[62:65]
	v_mfma_f32_16x16x32_bf16 v[58:61], v[142:145], v[216:219], v[58:61]
	v_mfma_f32_16x16x32_bf16 v[50:53], v[134:137], v[224:227], v[50:53]
	v_mfma_f32_16x16x32_bf16 v[42:45], v[142:145], v[224:227], v[42:45]
	v_mfma_f32_16x16x32_bf16 v[30:33], v[134:137], v[232:235], v[30:33]
	v_mfma_f32_16x16x32_bf16 v[26:29], v[142:145], v[232:235], v[26:29]
	v_mfma_f32_16x16x32_bf16 v[18:21], v[134:137], v[240:243], v[18:21]
	v_mfma_f32_16x16x32_bf16 v[10:13], v[142:145], v[240:243], v[10:13]
	s_setprio 0
	s_setprio 1
	v_mfma_f32_16x16x32_bf16 v[54:57], v[168:171], v[212:215], v[54:57]
	v_mfma_f32_16x16x32_bf16 v[46:49], v[204:207], v[212:215], v[46:49]
	v_mfma_f32_16x16x32_bf16 v[38:41], v[168:171], v[220:223], v[38:41]
	v_mfma_f32_16x16x32_bf16 v[34:37], v[204:207], v[220:223], v[34:37]
	v_mfma_f32_16x16x32_bf16 v[22:25], v[168:171], v[228:231], v[22:25]
	v_mfma_f32_16x16x32_bf16 v[14:17], v[204:207], v[228:231], v[14:17]
	v_mfma_f32_16x16x32_bf16 v[6:9], v[168:171], v[236:239], v[6:9]
	v_mfma_f32_16x16x32_bf16 v[2:5], v[204:207], v[236:239], v[2:5]
	v_mfma_f32_16x16x32_bf16 v[54:57], v[200:203], v[216:219], v[54:57]
	v_mfma_f32_16x16x32_bf16 v[46:49], v[208:211], v[216:219], v[46:49]
	v_mfma_f32_16x16x32_bf16 v[38:41], v[200:203], v[224:227], v[38:41]
	v_mfma_f32_16x16x32_bf16 v[34:37], v[208:211], v[224:227], v[34:37]
	v_mfma_f32_16x16x32_bf16 v[22:25], v[200:203], v[232:235], v[22:25]
	v_mfma_f32_16x16x32_bf16 v[14:17], v[208:211], v[232:235], v[14:17]
	v_mfma_f32_16x16x32_bf16 v[6:9], v[200:203], v[240:243], v[6:9]
	v_mfma_f32_16x16x32_bf16 v[2:5], v[208:211], v[240:243], v[2:5]
	s_setprio 0
	s_barrier
; #define PG8_STAGE(bufoff, gbase, voff) do { _Pragma("unroll") for (int _i = 0; _i < 2; ++_i) \
;         __builtin_amdgcn_global_load_lds((const unsigned*)((const char*)(gbase) + (voff)[_i]), (PG8_LAS unsigned*)(lds + (bufoff) + ldsw + _i * 8192), 16, 0, 0); } while (0)
; #define PG8_LDA(dst, b, h) do { _Pragma("unroll") for (int m = 0; m < 4; ++m) _Pragma("unroll") for (int k = 0; k < 2; ++k) dst[m][k] = *(const PG8_LAS bf16x8*)(lds + PG8_SA(b, h) + aoff + m * 2048 + k * 1024); } while (0)
; #define PG8_LDB(dst, b, h) do { _Pragma("unroll") for (int n = 0; n < 2; ++n) _Pragma("unroll") for (int k = 0; k < 2; ++k) dst[n][k] = *(const PG8_LAS bf16x8*)(lds + PG8_SB(b, h) + boff + n * 2048 + k * 1024); } while (0)
; #define PG8_MMA(ai, bj, At, Bt) do { __builtin_amdgcn_s_setprio(1); _Pragma("unroll") for (int m = 0; m < 4; ++m) _Pragma("unroll") for (int n = 0; n < 2; ++n) _Pragma("unroll") for (int k = 0; k < 2; ++k) \
;         acc[ai][bj][m][n] = __builtin_amdgcn_mfma_f32_16x16x32_bf16(Bt[n][k], At[m][k], acc[ai][bj][m][n], 0, 0, 0); __builtin_amdgcn_s_setprio(0); } while (0)
; #define PG8_WAIT_V(n) asm volatile("s_waitcnt vmcnt(" #n ")" ::: "memory")
; #define PG8_WAIT_L(n) asm volatile("s_waitcnt lgkmcnt(" #n ")" ::: "memory")
; #define PG8_BAR __builtin_amdgcn_s_barrier()
; #define PG8_SCHED __builtin_amdgcn_sched_barrier(0)
; template <class Epi, class Sched, bool ALIGN_EPI = false, bool SP2 = false>
; __device__ __forceinline__ void gemm_phase(PG8_LAS unsigned char* lds, const Gemm g, const Sched& S, const Epi& E) {
;     ...
;             PG8_LDB(B0, 1, 0); PG8_LDB(B1, 1, 1); PG8_SCHED; PG8_LDA(At, 1, 0); PG8_STAGE(PG8_SA(0, 1), a2 + hstep, voffA);
;             PG8_WAIT_V(8); PG8_WAIT_L(0); PG8_BAR; PG8_MMA(0, 0, At, B0); PG8_MMA(0, 1, At, B1); PG8_BAR; PG8_SCHED;
	s_add_i32 s64, 0, 0x18000
	v_add_u32_e32 v0, s64, v175
	s_add_i32 s65, 0, 0x1c000
	ds_read_b128 v[130:133], v0
	ds_read_b128 v[134:137], v0 offset:1024
	ds_read_b128 v[138:141], v0 offset:2048
	ds_read_b128 v[142:145], v0 offset:3072
	v_add_u32_e32 v0, s65, v175
	ds_read_b128 v[168:171], v0
	ds_read_b128 v[200:203], v0 offset:1024
	ds_read_b128 v[204:207], v0 offset:2048
	ds_read_b128 v[208:211], v0 offset:3072
	s_add_u32 s26, s26, 0x40000
	s_addc_u32 s27, s27, 0
	s_mov_b32 m0, s52
	v_lshl_add_u64 v[244:245], s[26:27], 0, v[160:161]
	ds_read_b128 v[212:215], v177 offset:32768
	ds_read_b128 v[216:219], v177 offset:33792
	ds_read_b128 v[220:223], v177 offset:34816
	ds_read_b128 v[224:227], v177 offset:35840
	ds_read_b128 v[228:231], v177 offset:36864
	ds_read_b128 v[232:235], v177 offset:37888
	ds_read_b128 v[236:239], v177 offset:38912
	ds_read_b128 v[240:243], v177 offset:39936
	global_load_lds_dwordx4 v[244:245], off
	v_lshl_add_u64 v[244:245], s[26:27], 0, v[156:157]
	s_mov_b32 m0, s53
	s_nop 0
	global_load_lds_dwordx4 v[244:245], off
	s_waitcnt vmcnt(8)
	s_waitcnt lgkmcnt(0)
	s_barrier
	s_setprio 1
	s_waitcnt lgkmcnt(0)
	v_mfma_f32_16x16x32_bf16 v[126:129], v[130:133], v[212:215], v[126:129]
	v_mfma_f32_16x16x32_bf16 v[122:125], v[138:141], v[212:215], v[122:125]
	v_mfma_f32_16x16x32_bf16 v[114:117], v[130:133], v[220:223], v[114:117]
	v_mfma_f32_16x16x32_bf16 v[106:109], v[138:141], v[220:223], v[106:109]
	v_mfma_f32_16x16x32_bf16 v[94:97], v[130:133], v[228:231], v[94:97]
	v_mfma_f32_16x16x32_bf16 v[90:93], v[138:141], v[228:231], v[90:93]
	v_mfma_f32_16x16x32_bf16 v[82:85], v[130:133], v[236:239], v[82:85]
	v_mfma_f32_16x16x32_bf16 v[74:77], v[138:141], v[236:239], v[74:77]
	v_mfma_f32_16x16x32_bf16 v[126:129], v[134:137], v[216:219], v[126:129]
	v_mfma_f32_16x16x32_bf16 v[122:125], v[142:145], v[216:219], v[122:125]
	v_mfma_f32_16x16x32_bf16 v[114:117], v[134:137], v[224:227], v[114:117]
	v_mfma_f32_16x16x32_bf16 v[106:109], v[142:145], v[224:227], v[106:109]
	v_mfma_f32_16x16x32_bf16 v[94:97], v[134:137], v[232:235], v[94:97]
	v_mfma_f32_16x16x32_bf16 v[90:93], v[142:145], v[232:235], v[90:93]
	v_mfma_f32_16x16x32_bf16 v[82:85], v[134:137], v[240:243], v[82:85]
	v_mfma_f32_16x16x32_bf16 v[74:77], v[142:145], v[240:243], v[74:77]
	s_setprio 0
	s_setprio 1
	v_mfma_f32_16x16x32_bf16 v[118:121], v[168:171], v[212:215], v[118:121]
	v_mfma_f32_16x16x32_bf16 v[110:113], v[204:207], v[212:215], v[110:113]
	v_mfma_f32_16x16x32_bf16 v[102:105], v[168:171], v[220:223], v[102:105]
	v_mfma_f32_16x16x32_bf16 v[98:101], v[204:207], v[220:223], v[98:101]
	v_mfma_f32_16x16x32_bf16 v[86:89], v[168:171], v[228:231], v[86:89]
	v_mfma_f32_16x16x32_bf16 v[78:81], v[204:207], v[228:231], v[78:81]
	v_mfma_f32_16x16x32_bf16 v[70:73], v[168:171], v[236:239], v[70:73]
	v_mfma_f32_16x16x32_bf16 v[66:69], v[204:207], v[236:239], v[66:69]
	v_mfma_f32_16x16x32_bf16 v[118:121], v[200:203], v[216:219], v[118:121]
	v_mfma_f32_16x16x32_bf16 v[110:113], v[208:211], v[216:219], v[110:113]
	v_mfma_f32_16x16x32_bf16 v[102:105], v[200:203], v[224:227], v[102:105]
	v_mfma_f32_16x16x32_bf16 v[98:101], v[208:211], v[224:227], v[98:101]
	v_mfma_f32_16x16x32_bf16 v[86:89], v[200:203], v[232:235], v[86:89]
	v_mfma_f32_16x16x32_bf16 v[78:81], v[208:211], v[232:235], v[78:81]
	v_mfma_f32_16x16x32_bf16 v[70:73], v[200:203], v[240:243], v[70:73]
	v_mfma_f32_16x16x32_bf16 v[66:69], v[208:211], v[240:243], v[66:69]
	s_setprio 0
	s_barrier
; #define PG8_STAGE(bufoff, gbase, voff) do { _Pragma("unroll") for (int _i = 0; _i < 2; ++_i) \
;         __builtin_amdgcn_global_load_lds((const unsigned*)((const char*)(gbase) + (voff)[_i]), (PG8_LAS unsigned*)(lds + (bufoff) + ldsw + _i * 8192), 16, 0, 0); } while (0)
; #define PG8_LDA(dst, b, h) do { _Pragma("unroll") for (int m = 0; m < 4; ++m) _Pragma("unroll") for (int k = 0; k < 2; ++k) dst[m][k] = *(const PG8_LAS bf16x8*)(lds + PG8_SA(b, h) + aoff + m * 2048 + k * 1024); } while (0)
; #define PG8_MMA(ai, bj, At, Bt) do { __builtin_amdgcn_s_setprio(1); _Pragma("unroll") for (int m = 0; m < 4; ++m) _Pragma("unroll") for (int n = 0; n < 2; ++n) _Pragma("unroll") for (int k = 0; k < 2; ++k) \
;         acc[ai][bj][m][n] = __builtin_amdgcn_mfma_f32_16x16x32_bf16(Bt[n][k], At[m][k], acc[ai][bj][m][n], 0, 0, 0); __builtin_amdgcn_s_setprio(0); } while (0)
; #define PG8_WAIT_V(n) asm volatile("s_waitcnt vmcnt(" #n ")" ::: "memory")
; #define PG8_WAIT_L(n) asm volatile("s_waitcnt lgkmcnt(" #n ")" ::: "memory")
; #define PG8_BAR __builtin_amdgcn_s_barrier()
; #define PG8_SCHED __builtin_amdgcn_sched_barrier(0)
; template <class Epi, class Sched, bool ALIGN_EPI = false, bool SP2 = false>
; __device__ __forceinline__ void gemm_phase(PG8_LAS unsigned char* lds, const Gemm g, const Sched& S, const Epi& E) {
;     ...
;             PG8_LDA(At, 1, 1); PG8_STAGE(PG8_SB(1, 0), b3, voffB); PG8_STAGE(PG8_SB(1, 1), b3 + hstep, voffB); PG8_STAGE(PG8_SA(1, 0), a3, voffA);
;             PG8_WAIT_V(8); PG8_WAIT_L(0); PG8_BAR; PG8_MMA(1, 0, At, B0); PG8_MMA(1, 1, At, B1); PG8_BAR; PG8_SCHED;
	s_add_i32 s26, s64, s30
	v_lshl_add_u64 v[146:147], v[146:147], 0, s[38:39]
	s_mov_b32 m0, s26
	ds_read_b128 v[212:215], v177 offset:49152
	ds_read_b128 v[216:219], v177 offset:50176
	ds_read_b128 v[220:223], v177 offset:51200
	ds_read_b128 v[224:227], v177 offset:52224
	ds_read_b128 v[228:231], v177 offset:53248
	ds_read_b128 v[232:235], v177 offset:54272
	ds_read_b128 v[236:239], v177 offset:55296
	ds_read_b128 v[240:243], v177 offset:56320
	global_load_lds_dwordx4 v[146:147], off
	s_add_i32 m0, s26, 0x2000
	s_add_u32 s24, s24, 0x40080
	v_lshl_add_u64 v[146:147], v[148:149], 0, s[38:39]
	s_addc_u32 s25, s25, 0
	s_add_i32 s26, s65, s30
	global_load_lds_dwordx4 v[146:147], off
	v_lshl_add_u64 v[146:147], s[24:25], 0, v[158:159]
	s_mov_b32 m0, s26
	s_nop 0
	global_load_lds_dwordx4 v[146:147], off
	v_lshl_add_u64 v[146:147], s[24:25], 0, v[154:155]
	s_add_i32 m0, s26, 0x2000
	s_nop 0
	global_load_lds_dwordx4 v[146:147], off
	v_lshl_add_u64 v[146:147], v[172:173], 0, s[38:39]
	s_mov_b32 m0, s55
	s_nop 0
	global_load_lds_dwordx4 v[146:147], off
	v_lshl_add_u64 v[146:147], v[180:181], 0, s[38:39]
	s_mov_b32 m0, s56
	s_nop 0
	global_load_lds_dwordx4 v[146:147], off
	s_waitcnt vmcnt(8)
	s_waitcnt lgkmcnt(0)
	s_barrier
	s_setprio 1
	s_waitcnt lgkmcnt(0)
	v_mfma_f32_16x16x32_bf16 v[62:65], v[130:133], v[212:215], v[62:65]
	v_mfma_f32_16x16x32_bf16 v[58:61], v[138:141], v[212:215], v[58:61]
	v_mfma_f32_16x16x32_bf16 v[50:53], v[130:133], v[220:223], v[50:53]
	v_mfma_f32_16x16x32_bf16 v[42:45], v[138:141], v[220:223], v[42:45]
	v_mfma_f32_16x16x32_bf16 v[30:33], v[130:133], v[228:231], v[30:33]
	v_mfma_f32_16x16x32_bf16 v[26:29], v[138:141], v[228:231], v[26:29]
	v_mfma_f32_16x16x32_bf16 v[18:21], v[130:133], v[236:239], v[18:21]
	v_mfma_f32_16x16x32_bf16 v[10:13], v[138:141], v[236:239], v[10:13]
	v_mfma_f32_16x16x32_bf16 v[62:65], v[134:137], v[216:219], v[62:65]
	v_mfma_f32_16x16x32_bf16 v[58:61], v[142:145], v[216:219], v[58:61]
	v_mfma_f32_16x16x32_bf16 v[50:53], v[134:137], v[224:227], v[50:53]
	v_mfma_f32_16x16x32_bf16 v[42:45], v[142:145], v[224:227], v[42:45]
	v_mfma_f32_16x16x32_bf16 v[30:33], v[134:137], v[232:235], v[30:33]
	v_mfma_f32_16x16x32_bf16 v[26:29], v[142:145], v[232:235], v[26:29]
	v_mfma_f32_16x16x32_bf16 v[18:21], v[134:137], v[240:243], v[18:21]
	v_mfma_f32_16x16x32_bf16 v[10:13], v[142:145], v[240:243], v[10:13]
	s_setprio 0
	s_setprio 1
	v_mfma_f32_16x16x32_bf16 v[54:57], v[168:171], v[212:215], v[54:57]
	v_mfma_f32_16x16x32_bf16 v[46:49], v[204:207], v[212:215], v[46:49]
	v_mfma_f32_16x16x32_bf16 v[38:41], v[168:171], v[220:223], v[38:41]
	v_mfma_f32_16x16x32_bf16 v[34:37], v[204:207], v[220:223], v[34:37]
	v_mfma_f32_16x16x32_bf16 v[22:25], v[168:171], v[228:231], v[22:25]
	v_mfma_f32_16x16x32_bf16 v[14:17], v[204:207], v[228:231], v[14:17]
	v_mfma_f32_16x16x32_bf16 v[6:9], v[168:171], v[236:239], v[6:9]
	v_mfma_f32_16x16x32_bf16 v[2:5], v[204:207], v[236:239], v[2:5]
	v_mfma_f32_16x16x32_bf16 v[54:57], v[200:203], v[216:219], v[54:57]
	v_mfma_f32_16x16x32_bf16 v[46:49], v[208:211], v[216:219], v[46:49]
	v_mfma_f32_16x16x32_bf16 v[38:41], v[200:203], v[224:227], v[38:41]
	v_mfma_f32_16x16x32_bf16 v[34:37], v[208:211], v[224:227], v[34:37]
	v_mfma_f32_16x16x32_bf16 v[22:25], v[200:203], v[232:235], v[22:25]
	v_mfma_f32_16x16x32_bf16 v[14:17], v[208:211], v[232:235], v[14:17]
	v_mfma_f32_16x16x32_bf16 v[6:9], v[200:203], v[240:243], v[6:9]
	v_mfma_f32_16x16x32_bf16 v[2:5], v[208:211], v[240:243], v[2:5]
	s_setprio 0
	s_cmp_lg_u32 s63, 12
	s_cbranch_scc1 .Llb_558
	s_and_b64 vcc, exec, s[8:9]
	s_cbranch_vccz .Lnb_558

; #define PG8_BAR __builtin_amdgcn_s_barrier()
;     __device__ __forceinline__ void operator()(const f32x4 (&acc)[2][2][4][2], const Unit& u, int wr, int wc, int fr, int fq) const {
;         const int row0 = u.pm * BM + wr * 64 + fr;
;         if (u.pn < nqk) {
; template <class Epi, class Sched, bool ALIGN_EPI = false, bool SP2 = false>
; __device__ __forceinline__ void gemm_phase(PG8_LAS unsigned char* lds, const Gemm g, const Sched& S, const Epi& E) {
;     ...
;         if constexpr (ALIGN_EPI) { if (wr == 0) PG8_BAR; }
;         if constexpr (!Epi::AFTER_DRAIN) { E(acc, cur, wr, wc, fr, fq); S.done(cur); }
.Lnb_558:
	s_add_i32 s63, s63, 2
	s_add_u32 s22, s22, 0x100
	s_addc_u32 s23, s23, 0
	s_add_u32 s61, s61, 0x100
	s_addc_u32 s62, s62, 0
	s_cmp_gt_u32 s63, 13
	s_cbranch_scc0 .LBB0_558
	s_and_b64 vcc, exec, s[8:9]
	s_cbranch_vccnz .LBB0_563
	v_lshl_add_u32 v168, s20, 8, v174
	s_cmp_ge_i32 s59, s54
	s_mov_b64 s[20:21], -1
	s_cbranch_scc1 .LBB0_564

;     __device__ __forceinline__ void operator()(const f32x4 (&acc)[2][2][4][2], const Unit& u, int wr, int wc, int fr, int fq) const {
;         const int row0 = u.pm * BM + wr * 64 + fr;
;         if (u.pn < nqk) {
.LBB0_563:
	v_lshl_add_u32 v168, s20, 8, v174
	s_cmp_ge_i32 s59, s54
	s_mov_b64 s[20:21], -1
	s_cbranch_scc0 .LBB0_561

; #define PG8_BAR __builtin_amdgcn_s_barrier()
; template <class Epi, class Sched, bool ALIGN_EPI = false, bool SP2 = false>
; __device__ __forceinline__ void gemm_phase(PG8_LAS unsigned char* lds, const Gemm g, const Sched& S, const Epi& E) {
;     ...
;         if (!has_next) break;
; #pragma unroll
;         for (int a = 0; a < 2; ++a)
; #pragma unroll
;             for (int b = 0; b < 2; ++b)
; #pragma unroll
;                 for (int m = 0; m < 4; ++m)
; #pragma unroll
;                     for (int n = 0; n < 2; ++n) acc[a][b][m][n] = (f32x4){0.f, 0.f, 0.f, 0.f};
;         cur = nxt; cA = nA; cB = nB; ++ui;
;         if constexpr (ALIGN_EPI) { if (wr == 1) PG8_BAR; }
.LBB0_572:
	s_andn2_b64 vcc, exec, s[0:1]
	s_cbranch_vccnz .LBB0_553
	s_branch .LBB0_553

; #define PG8_STAGE(bufoff, gbase, voff) do { _Pragma("unroll") for (int _i = 0; _i < 2; ++_i) \
;         __builtin_amdgcn_global_load_lds((const unsigned*)((const char*)(gbase) + (voff)[_i]), (PG8_LAS unsigned*)(lds + (bufoff) + ldsw + _i * 8192), 16, 0, 0); } while (0)
; #define PG8_WAIT_V(n) asm volatile("s_waitcnt vmcnt(" #n ")" ::: "memory")
; #define PG8_BAR __builtin_amdgcn_s_barrier()
; template <class Epi, class Sched, bool ALIGN_EPI = false, bool SP2 = false>
; __device__ __forceinline__ void gemm_phase(PG8_LAS unsigned char* lds, const Gemm g, const Sched& S, const Epi& E) {
;     ...
;     const int tid = tid_, wid = __builtin_amdgcn_readfirstlane(tid >> 6), lane = tid & 63, wr = wid >> 2, wc = wid & 3, fr = lane & 15, fq = lane >> 4;
;     const int K = g.K, nt = K / BK;
;     unsigned voffA[2], voffB[2];
; #pragma unroll
;     for (int i = 0; i < 2; ++i) { int R, C; stage_rc(tid * 16 + i * 8192, R, C); const int Rb = Epi::PERM ? ((R & ~31) + perm32(R & 31)) : R;
;         voffA[i] = (unsigned)(R * K + C) * 2u; voffB[i] = (unsigned)(Rb * K + C) * 2u; }
;     const size_t kstep = (size_t)(BK * 2);
;     const size_t hstep = (size_t)HALF * K * 2;
;     const size_t tstep = 2 * hstep;
;     const unsigned ldsw = (unsigned)wid * 1024u;
;     const int aoff = lds_byte(wr * 64 + fr, fq * 8), boff = lds_byte(wc * 32 + fr, fq * 8);
;     ...
;     Unit cur, nxt; int ui = 0;
;     if (!S.next(0, cur)) return;
;     f32x4 acc[2][2][4][2];
; #pragma unroll
;     for (int a = 0; a < 2; ++a)
; #pragma unroll
;         for (int b = 0; b < 2; ++b)
; #pragma unroll
;             for (int m = 0; m < 4; ++m)
; #pragma unroll
;                 for (int n = 0; n < 2; ++n) acc[a][b][m][n] = (f32x4){0.f, 0.f, 0.f, 0.f};
;     bf16x8 At[4][2], B0[2][2], B1[2][2];
;     const char* cA = (const char*)g.A + (size_t)cur.pm * tstep; const char* cB = (const char*)g.Bt + (size_t)cur.pn * tstep;
;     S.a_ready(cur);
;     if constexpr (SP2) {
;         PG8_STAGE(PG8_SB(0, 0), cB, voffB); PG8_STAGE(PG8_SB(0, 1), cB + hstep, voffB); PG8_STAGE(PG8_SA(0, 0), cA, voffA); PG8_STAGE(PG8_SA(0, 1), cA + hstep, voffA);
;         if (wr == 1) PG8_BAR;
;         PG8_WAIT_V(2); PG8_BAR;
;         PG8_STAGE(PG8_SB(1, 0), cB + kstep, voffB); PG8_STAGE(PG8_SA(1, 0), cA + kstep, voffA); PG8_STAGE(PG8_SB(1, 1), cB + hstep + kstep, voffB);
;         PG8_WAIT_V(6); PG8_BAR;
.LBB0_1077:
	v_readlane_b32 s4, v255, 5
	v_mov_b32_e32 v12, v182
	v_readlane_b32 s5, v255, 6
	s_and_b64 vcc, exec, s[4:5]
	v_readfirstlane_b32 s4, v12
	s_cbranch_vccnz .LBB0_1097
	v_lshlrev_b32_e32 v0, 4, v12
	v_add_u32_e32 v2, 0x2000, v0
	v_ashrrev_i32_e32 v3, 31, v2
	v_lshrrev_b32_e32 v3, 22, v3
	v_add_u32_e32 v3, v2, v3
	v_ashrrev_i32_e32 v6, 10, v3
	v_mul_i32_i24_e32 v3, 0x400, v6
	v_sub_u32_e32 v2, v2, v3
	v_lshrrev_b32_e32 v3, 4, v2
	v_bitop3_b32 v2, v3, v2, 32 bitop3:0x6c
	v_ashrrev_i32_e32 v3, 31, v2
	v_lshrrev_b32_e32 v3, 26, v3
	v_add_u32_e32 v3, v2, v3
	v_lshlrev_b32_e32 v4, 3, v6
	v_ashrrev_i32_e32 v7, 6, v3
	v_and_b32_e32 v4, -16, v4
	v_add_u32_e32 v4, v7, v4
	s_add_u32 s22, s76, s0
	v_and_b32_e32 v5, 3, v7
	s_mov_b32 s0, 0x1fffe0
	v_lshrrev_b32_e32 v8, 2, v4
	v_lshlrev_b32_e32 v9, 1, v4
	v_and_b32_e32 v3, 0xc0, v3
	v_and_or_b32 v5, v4, s0, v5
	v_and_b32_e32 v8, 4, v8
	v_and_b32_e32 v9, 24, v9
	v_sub_u32_e32 v2, v2, v3
	v_or3_b32 v5, v5, v8, v9
	v_lshlrev_b32_e32 v8, 5, v6
	v_ashrrev_i16_sdwa v2, v184, sext(v2) dst_sel:DWORD dst_unused:UNUSED_PAD src0_sel:DWORD src1_sel:BYTE_0
	v_and_b32_e32 v9, 32, v8
	v_bfe_i32 v8, v2, 0, 16
	v_add_lshl_u32 v2, v9, v8, 1
	v_lshl_add_u32 v130, v5, 11, v2
	v_lshl_add_u32 v132, v4, 11, v2
	v_bfe_i32 v2, v12, 27, 1
	v_lshrrev_b32_e32 v2, 22, v2
	v_add_u32_e32 v2, v0, v2
	v_and_b32_e32 v2, 0xfffffc00, v2
	v_sub_u32_e32 v0, v0, v2
	v_lshrrev_b32_e32 v2, 4, v0
	v_ashrrev_i32_e32 v3, 31, v12
	v_bitop3_b32 v0, v2, v0, 32 bitop3:0x6c
	v_lshrrev_b32_e32 v3, 26, v3
	v_ashrrev_i32_e32 v2, 31, v0
	v_add_u32_e32 v3, v12, v3
	v_lshrrev_b32_e32 v2, 26, v2
	v_ashrrev_i32_e32 v10, 6, v3
	v_add_u32_e32 v2, v0, v2
	v_lshlrev_b32_e32 v3, 3, v10
	v_ashrrev_i32_e32 v9, 6, v2
	v_and_b32_e32 v3, -16, v3
	v_add_u32_e32 v3, v9, v3
	v_and_b32_e32 v4, 3, v9
	v_lshrrev_b32_e32 v5, 2, v3
	v_lshlrev_b32_e32 v11, 1, v3
	v_and_b32_e32 v2, 0xc0, v2
	s_addc_u32 s23, s77, s1
	s_ashr_i32 s5, s4, 6
	v_and_or_b32 v4, v3, s0, v4
	v_and_b32_e32 v5, 4, v5
	v_and_b32_e32 v11, 24, v11
	v_sub_u32_e32 v0, v0, v2
	s_ashr_i32 s6, s4, 8
	s_lshl_b32 s24, s5, 10
	v_or3_b32 v4, v4, v5, v11
	v_lshlrev_b32_e32 v5, 5, v10
	v_ashrrev_i16_sdwa v0, v184, sext(v0) dst_sel:DWORD dst_unused:UNUSED_PAD src0_sel:DWORD src1_sel:BYTE_0
	v_readlane_b32 s0, v254, 8
	v_and_b32_e32 v5, 32, v5
	v_bfe_i32 v11, v0, 0, 16
	v_readlane_b32 s1, v254, 9
	s_add_u32 s18, s22, s0
	v_add_lshl_u32 v2, v5, v11, 1
	s_addc_u32 s19, s23, s1
	s_add_i32 s25, s24, 0
	v_lshl_add_u32 v0, v4, 11, v2
	s_add_i32 m0, s25, 0x10000
	v_lshl_add_u32 v134, v3, 11, v2
	global_load_lds_dwordx4 v0, s[18:19]
	s_add_i32 m0, s25, 0x12000
	s_add_u32 s0, s18, 0x40000
	global_load_lds_dwordx4 v130, s[18:19]
	s_addc_u32 s1, s19, 0
	s_add_i32 m0, s25, 0x14000
	s_add_i32 s26, s25, 0x2000
	global_load_lds_dwordx4 v0, s[0:1]
	s_add_i32 m0, s25, 0x16000
	s_add_i32 s27, s25, 0x4000
	global_load_lds_dwordx4 v130, s[0:1]
	v_readlane_b32 s0, v254, 10
	s_mov_b32 m0, s25
	v_readlane_b32 s1, v254, 11
	s_add_i32 s28, s25, 0x6000
	v_mov_b32_e32 v131, v1
	s_cmp_eq_u32 s6, 1
	v_lshl_add_u64 v[2:3], s[18:19], 0, v[0:1]
	v_lshl_add_u64 v[4:5], s[18:19], 0, v[130:131]
	global_load_lds_dwordx4 v134, s[0:1]
	s_mov_b32 m0, s26
	s_nop 0
	global_load_lds_dwordx4 v132, s[0:1]
	v_readlane_b32 s0, v254, 12
	s_mov_b32 m0, s27
	v_readlane_b32 s1, v254, 13
	s_nop 4
	global_load_lds_dwordx4 v134, s[0:1]
	s_mov_b32 m0, s28
	s_nop 0
	global_load_lds_dwordx4 v132, s[0:1]
	s_cselect_b64 s[0:1], -1, 0
	s_cmp_lg_u32 s6, 1
	s_cbranch_scc1 .LBB0_1080
.LBB0_1080:
	v_readlane_b32 s7, v255, 2
	s_waitcnt vmcnt(0)
	v_lshrrev_b32_e32 v18, 1, v12
	s_add_u32 s29, s7, 0x5000
	v_readlane_b32 s7, v255, 3
	v_and_b32_e32 v18, 24, v18
	v_readlane_b32 s16, v254, 10
	s_addc_u32 s30, s7, 0
	v_and_b32_e32 v13, 15, v12
	v_lshlrev_b32_e32 v19, 1, v18
	v_lshlrev_b32_e32 v12, 2, v12
	s_lshl_b32 s5, s5, 5
	v_mov_b32_e32 v135, v1
	v_readlane_b32 s17, v254, 11
	v_lshl_or_b32 v166, s6, 6, v13
	v_lshl_or_b32 v13, v13, 6, v19
	s_lshl_b32 s6, s6, 13
	v_and_b32_e32 v12, 32, v12
	s_and_b32 s5, s5, 0x60
	s_add_i32 m0, s25, 0x18000
	v_lshl_add_u64 v[2:3], v[2:3], 0, s[38:39]
	v_lshl_add_u64 v[14:15], s[16:17], 0, v[134:135]
	v_mov_b32_e32 v133, v1
	v_bitop3_b32 v19, v13, s6, v12 bitop3:0xde
	s_lshl_b32 s6, s5, 7
	s_waitcnt vmcnt(2)
	s_barrier
	global_load_lds_dwordx4 v[2:3], off
	v_lshl_add_u64 v[2:3], v[4:5], 0, s[38:39]
	s_add_i32 m0, s25, 0x1a000
	s_add_i32 s31, s25, 0x8000
	s_add_i32 s33, s25, 0xa000
	v_lshl_add_u64 v[16:17], s[16:17], 0, v[132:133]
	v_bitop3_b32 v167, v13, s6, v12 bitop3:0xde
	global_load_lds_dwordx4 v[2:3], off
	v_lshl_add_u64 v[2:3], v[14:15], 0, s[38:39]
	s_mov_b32 m0, s31
	s_add_u32 s6, s18, 0x40080
	global_load_lds_dwordx4 v[2:3], off
	v_lshl_add_u64 v[2:3], v[16:17], 0, s[38:39]
	s_mov_b32 m0, s33
	s_addc_u32 s7, s19, 0
	global_load_lds_dwordx4 v[2:3], off
	s_add_i32 m0, s25, 0x1c000
	v_lshl_add_u64 v[2:3], s[6:7], 0, v[0:1]
	global_load_lds_dwordx4 v[2:3], off
	v_lshl_add_u64 v[2:3], s[6:7], 0, v[130:131]
	s_add_i32 m0, s25, 0x1e000
	s_cmpk_lt_u32 s4, 0x100
	global_load_lds_dwordx4 v[2:3], off
	v_lshlrev_b32_e32 v2, 14, v10
	v_and_b32_e32 v2, 0xffff8000, v2
	v_lshl_add_u32 v2, v9, 11, v2
	v_and_b32_e32 v3, 1, v10
	v_lshl_or_b32 v2, v3, 6, v2
	v_lshl_add_u32 v136, v11, 1, v2
	v_lshlrev_b32_e32 v2, 14, v6
	v_and_b32_e32 v2, 0xffff8000, v2
	s_waitcnt vmcnt(6)
	v_lshl_add_u32 v2, v7, 11, v2
	v_and_b32_e32 v3, 1, v6
	v_or_b32_e32 v168, s5, v18
	v_lshl_or_b32 v2, v3, 6, v2
	v_readlane_b32 s4, v254, 16
	s_cselect_b64 s[6:7], -1, 0
	v_mov_b32_e32 v137, v1
	v_lshl_add_u32 v138, v8, 1, v2
	v_mov_b32_e32 v139, v1
	s_mov_b32 s34, 0
	v_add_u32_e32 v169, 0, v19
	v_readlane_b32 s44, v254, 7
	s_mov_b32 s35, s4
	s_barrier
	v_readlane_b32 s5, v254, 17
	s_waitcnt vmcnt(0)
	s_branch .LBB0_1083

; #define PG8_STAGE(bufoff, gbase, voff) do { _Pragma("unroll") for (int _i = 0; _i < 2; ++_i) \
;         __builtin_amdgcn_global_load_lds((const unsigned*)((const char*)(gbase) + (voff)[_i]), (PG8_LAS unsigned*)(lds + (bufoff) + ldsw + _i * 8192), 16, 0, 0); } while (0)
; #define PG8_LDA(dst, b, h) do { _Pragma("unroll") for (int m = 0; m < 4; ++m) _Pragma("unroll") for (int k = 0; k < 2; ++k) dst[m][k] = *(const PG8_LAS bf16x8*)(lds + PG8_SA(b, h) + aoff + m * 2048 + k * 1024); } while (0)
; #define PG8_LDB(dst, b, h) do { _Pragma("unroll") for (int n = 0; n < 2; ++n) _Pragma("unroll") for (int k = 0; k < 2; ++k) dst[n][k] = *(const PG8_LAS bf16x8*)(lds + PG8_SB(b, h) + boff + n * 2048 + k * 1024); } while (0)
; #define PG8_WAIT_V(n) asm volatile("s_waitcnt vmcnt(" #n ")" ::: "memory")
; #define PG8_WAIT_L(n) asm volatile("s_waitcnt lgkmcnt(" #n ")" ::: "memory")
; #define PG8_BAR __builtin_amdgcn_s_barrier()
; #define PG8_SCHED __builtin_amdgcn_sched_barrier(0)
; template <class Epi, class Sched, bool ALIGN_EPI = false, bool SP2 = false>
; __device__ __forceinline__ void gemm_phase(PG8_LAS unsigned char* lds, const Gemm g, const Sched& S, const Epi& E) {
;     ...
;         const bool has_next = S.next(ui + 1, nxt);
;         const char* nA = has_next ? (const char*)g.A + (size_t)nxt.pm * tstep : cA; const char* nB = has_next ? (const char*)g.Bt + (size_t)nxt.pn * tstep : cB;
;         for (int t = 0; t < nt; t += 2) {
;             const bool last = (t == nt - 2);
;             const char* a1 = cA + (size_t)(t + 1) * kstep;
;             const char* a2 = last ? nA : cA + (size_t)(t + 2) * kstep; const char* b2 = last ? nB : cB + (size_t)(t + 2) * kstep;
;             const char* a3 = a2 + kstep; const char* b3 = b2 + kstep;
;             if (last && has_next) S.a_ready(nxt);
;             if constexpr (SP2) {
;             PG8_LDB(B0, 0, 0); PG8_LDB(B1, 0, 1); PG8_SCHED; PG8_LDA(At, 0, 0); PG8_STAGE(PG8_SA(1, 1), a1 + hstep, voffA);
;             PG8_WAIT_V(8); PG8_WAIT_L(0); PG8_BAR; PG8_MMA(0, 0, At, B0); PG8_MMA(0, 1, At, B1); PG8_BAR; PG8_SCHED;
;             PG8_LDA(At, 0, 1); PG8_STAGE(PG8_SB(0, 0), b2, voffB); PG8_STAGE(PG8_SB(0, 1), b2 + hstep, voffB); PG8_STAGE(PG8_SA(0, 0), a2, voffA);
;             PG8_WAIT_V(8); PG8_WAIT_L(0); PG8_BAR; PG8_MMA(1, 0, At, B0); PG8_MMA(1, 1, At, B1); PG8_BAR; PG8_SCHED;
.LBB0_1089:
	s_ashr_i32 s11, s10, 31
	s_lshl_b64 s[12:13], s[10:11], 19
	s_add_u32 s12, s90, s12
	s_addc_u32 s13, s91, s13
	s_and_b64 s[14:15], s[4:5], exec
	s_cselect_b32 s11, s13, s17
	s_cselect_b32 s45, s12, s16
	s_ashr_i32 s9, s8, 31
	s_lshl_b64 s[14:15], s[8:9], 19
	s_add_u32 s14, s22, s14
	s_addc_u32 s15, s23, s15
	s_and_b64 s[20:21], s[4:5], exec
	s_cselect_b32 s9, s15, s19
	s_cselect_b32 s46, s14, s18
	s_add_u32 s16, s16, 0x40080
	s_addc_u32 s17, s17, 0
	s_add_u32 s47, s18, 0x100
	s_addc_u32 s48, s19, 0
	s_mov_b32 s49, -2
	s_add_u32 s18, s16, 0xfffc0080
	s_addc_u32 s19, s17, -1
	s_add_i32 s50, 0, 0x10000
	s_cmp_eq_u32 s49, 12
	s_cselect_b32 s21, s11, s19
	s_cselect_b32 s20, s45, s18
	v_add_u32_e32 v148, s50, v167
	s_cselect_b32 s19, s9, s48
	s_cselect_b32 s18, s46, s47
	s_add_i32 s52, 0, 0x14000
	ds_read_b128 v[140:143], v148
	ds_read_b128 v[144:147], v148 offset:1024
	ds_read_b128 v[154:157], v148 offset:2048
	ds_read_b128 v[158:161], v148 offset:3072
	v_add_u32_e32 v148, s52, v167
	ds_read_b128 v[162:165], v148
	ds_read_b128 v[170:173], v148 offset:1024
	ds_read_b128 v[174:177], v148 offset:2048
	ds_read_b128 v[178:181], v148 offset:3072
	v_lshl_add_u64 v[148:149], s[16:17], 0, v[136:137]
	s_add_i32 m0, s25, 0xc000
	ds_read_b128 v[200:203], v169
	ds_read_b128 v[204:207], v169 offset:1024
	ds_read_b128 v[208:211], v169 offset:2048
	ds_read_b128 v[212:215], v169 offset:3072
	ds_read_b128 v[216:219], v169 offset:4096
	ds_read_b128 v[220:223], v169 offset:5120
	ds_read_b128 v[224:227], v169 offset:6144
	ds_read_b128 v[228:231], v169 offset:7168
	global_load_lds_dwordx4 v[148:149], off
	v_lshl_add_u64 v[148:149], s[16:17], 0, v[138:139]
	s_add_i32 m0, s25, 0xe000
	s_nop 0
	global_load_lds_dwordx4 v[148:149], off
	s_waitcnt vmcnt(20)
	s_waitcnt lgkmcnt(0)
	s_and_b64 vcc, exec, s[6:7]
	s_cbranch_vccnz .Lpe_1090
	s_barrier
.Lpe_1090:
	s_setprio 1
	s_waitcnt lgkmcnt(0)
	v_mfma_f32_16x16x32_bf16 v[126:129], v[140:143], v[200:203], 0
	v_mfma_f32_16x16x32_bf16 v[122:125], v[154:157], v[200:203], 0
	v_mfma_f32_16x16x32_bf16 v[118:121], v[140:143], v[208:211], 0
	v_mfma_f32_16x16x32_bf16 v[114:117], v[154:157], v[208:211], 0
	v_mfma_f32_16x16x32_bf16 v[110:113], v[140:143], v[216:219], 0
	v_mfma_f32_16x16x32_bf16 v[106:109], v[154:157], v[216:219], 0
	v_mfma_f32_16x16x32_bf16 v[102:105], v[140:143], v[224:227], 0
	v_mfma_f32_16x16x32_bf16 v[98:101], v[154:157], v[224:227], 0
	v_mfma_f32_16x16x32_bf16 v[126:129], v[144:147], v[204:207], v[126:129]
	v_mfma_f32_16x16x32_bf16 v[122:125], v[158:161], v[204:207], v[122:125]
	v_mfma_f32_16x16x32_bf16 v[118:121], v[144:147], v[212:215], v[118:121]
	v_mfma_f32_16x16x32_bf16 v[114:117], v[158:161], v[212:215], v[114:117]
	v_mfma_f32_16x16x32_bf16 v[110:113], v[144:147], v[220:223], v[110:113]
	v_mfma_f32_16x16x32_bf16 v[106:109], v[158:161], v[220:223], v[106:109]
	v_mfma_f32_16x16x32_bf16 v[102:105], v[144:147], v[228:231], v[102:105]
	v_mfma_f32_16x16x32_bf16 v[98:101], v[158:161], v[228:231], v[98:101]
	s_setprio 0
	s_setprio 1
	v_mfma_f32_16x16x32_bf16 v[62:65], v[162:165], v[200:203], 0
	v_mfma_f32_16x16x32_bf16 v[58:61], v[174:177], v[200:203], 0
	v_mfma_f32_16x16x32_bf16 v[54:57], v[162:165], v[208:211], 0
	v_mfma_f32_16x16x32_bf16 v[50:53], v[174:177], v[208:211], 0
	v_mfma_f32_16x16x32_bf16 v[46:49], v[162:165], v[216:219], 0
	v_mfma_f32_16x16x32_bf16 v[42:45], v[174:177], v[216:219], 0
	v_mfma_f32_16x16x32_bf16 v[38:41], v[162:165], v[224:227], 0
	v_mfma_f32_16x16x32_bf16 v[34:37], v[174:177], v[224:227], 0
	v_mfma_f32_16x16x32_bf16 v[62:65], v[170:173], v[204:207], v[62:65]
	v_mfma_f32_16x16x32_bf16 v[58:61], v[178:181], v[204:207], v[58:61]
	v_mfma_f32_16x16x32_bf16 v[54:57], v[170:173], v[212:215], v[54:57]
	v_mfma_f32_16x16x32_bf16 v[50:53], v[178:181], v[212:215], v[50:53]
	v_mfma_f32_16x16x32_bf16 v[46:49], v[170:173], v[220:223], v[46:49]
	v_mfma_f32_16x16x32_bf16 v[42:45], v[178:181], v[220:223], v[42:45]
	v_mfma_f32_16x16x32_bf16 v[38:41], v[170:173], v[228:231], v[38:41]
	v_mfma_f32_16x16x32_bf16 v[34:37], v[178:181], v[228:231], v[34:37]
	s_setprio 0
	s_barrier
	s_add_i32 s50, s50, s24
	v_lshl_add_u64 v[148:149], s[18:19], 0, v[0:1]
	s_mov_b32 m0, s50
	ds_read_b128 v[200:203], v169 offset:16384
	ds_read_b128 v[204:207], v169 offset:17408
	ds_read_b128 v[208:211], v169 offset:18432
	ds_read_b128 v[212:215], v169 offset:19456
	ds_read_b128 v[216:219], v169 offset:20480
	ds_read_b128 v[220:223], v169 offset:21504
	ds_read_b128 v[224:227], v169 offset:22528
	ds_read_b128 v[228:231], v169 offset:23552
	global_load_lds_dwordx4 v[148:149], off
	s_add_i32 m0, s50, 0x2000
	s_add_u32 s50, s18, 0x40000
	v_lshl_add_u64 v[232:233], s[18:19], 0, v[130:131]
	s_addc_u32 s51, s19, 0
	s_add_i32 s52, s52, s24
	global_load_lds_dwordx4 v[232:233], off
	v_lshl_add_u64 v[234:235], s[50:51], 0, v[0:1]
	s_mov_b32 m0, s52
	v_lshl_add_u64 v[236:237], s[20:21], 0, v[132:133]
	global_load_lds_dwordx4 v[234:235], off
	v_lshl_add_u64 v[234:235], s[50:51], 0, v[130:131]
	s_add_i32 m0, s52, 0x2000
	s_nop 0
	global_load_lds_dwordx4 v[234:235], off
	v_lshl_add_u64 v[234:235], s[20:21], 0, v[134:135]
	s_mov_b32 m0, s25
	s_nop 0
	global_load_lds_dwordx4 v[234:235], off
	s_mov_b32 m0, s26
	s_nop 0
	global_load_lds_dwordx4 v[236:237], off
	s_waitcnt vmcnt(20)
	s_waitcnt lgkmcnt(0)
	s_barrier
; #define PG8_STAGE(bufoff, gbase, voff) do { _Pragma("unroll") for (int _i = 0; _i < 2; ++_i) \
;         __builtin_amdgcn_global_load_lds((const unsigned*)((const char*)(gbase) + (voff)[_i]), (PG8_LAS unsigned*)(lds + (bufoff) + ldsw + _i * 8192), 16, 0, 0); } while (0)
; #define PG8_LDA(dst, b, h) do { _Pragma("unroll") for (int m = 0; m < 4; ++m) _Pragma("unroll") for (int k = 0; k < 2; ++k) dst[m][k] = *(const PG8_LAS bf16x8*)(lds + PG8_SA(b, h) + aoff + m * 2048 + k * 1024); } while (0)
; #define PG8_LDB(dst, b, h) do { _Pragma("unroll") for (int n = 0; n < 2; ++n) _Pragma("unroll") for (int k = 0; k < 2; ++k) dst[n][k] = *(const PG8_LAS bf16x8*)(lds + PG8_SB(b, h) + boff + n * 2048 + k * 1024); } while (0)
; #define PG8_MMA(ai, bj, At, Bt) do { __builtin_amdgcn_s_setprio(1); _Pragma("unroll") for (int m = 0; m < 4; ++m) _Pragma("unroll") for (int n = 0; n < 2; ++n) _Pragma("unroll") for (int k = 0; k < 2; ++k) \
;         acc[ai][bj][m][n] = __builtin_amdgcn_mfma_f32_16x16x32_bf16(Bt[n][k], At[m][k], acc[ai][bj][m][n], 0, 0, 0); __builtin_amdgcn_s_setprio(0); } while (0)
; #define PG8_WAIT_V(n) asm volatile("s_waitcnt vmcnt(" #n ")" ::: "memory")
; #define PG8_WAIT_L(n) asm volatile("s_waitcnt lgkmcnt(" #n ")" ::: "memory")
; #define PG8_BAR __builtin_amdgcn_s_barrier()
; #define PG8_SCHED __builtin_amdgcn_sched_barrier(0)
; template <class Epi, class Sched, bool ALIGN_EPI = false, bool SP2 = false>
; __device__ __forceinline__ void gemm_phase(PG8_LAS unsigned char* lds, const Gemm g, const Sched& S, const Epi& E) {
;     ...
;             PG8_WAIT_V(8); PG8_WAIT_L(0); PG8_BAR; PG8_MMA(1, 0, At, B0); PG8_MMA(1, 1, At, B1); PG8_BAR; PG8_SCHED;
;             PG8_LDB(B0, 1, 0); PG8_LDB(B1, 1, 1); PG8_SCHED; PG8_LDA(At, 1, 0); PG8_STAGE(PG8_SA(0, 1), a2 + hstep, voffA);
;             PG8_WAIT_V(8); PG8_WAIT_L(0); PG8_BAR; PG8_MMA(0, 0, At, B0); PG8_MMA(0, 1, At, B1); PG8_BAR; PG8_SCHED;
	s_setprio 1
	s_waitcnt lgkmcnt(0)
	v_mfma_f32_16x16x32_bf16 v[94:97], v[140:143], v[200:203], 0
	v_mfma_f32_16x16x32_bf16 v[90:93], v[154:157], v[200:203], 0
	v_mfma_f32_16x16x32_bf16 v[86:89], v[140:143], v[208:211], 0
	v_mfma_f32_16x16x32_bf16 v[82:85], v[154:157], v[208:211], 0
	v_mfma_f32_16x16x32_bf16 v[78:81], v[140:143], v[216:219], 0
	v_mfma_f32_16x16x32_bf16 v[74:77], v[154:157], v[216:219], 0
	v_mfma_f32_16x16x32_bf16 v[70:73], v[140:143], v[224:227], 0
	v_mfma_f32_16x16x32_bf16 v[66:69], v[154:157], v[224:227], 0
	v_mfma_f32_16x16x32_bf16 v[94:97], v[144:147], v[204:207], v[94:97]
	v_mfma_f32_16x16x32_bf16 v[90:93], v[158:161], v[204:207], v[90:93]
	v_mfma_f32_16x16x32_bf16 v[86:89], v[144:147], v[212:215], v[86:89]
	v_mfma_f32_16x16x32_bf16 v[82:85], v[158:161], v[212:215], v[82:85]
	v_mfma_f32_16x16x32_bf16 v[78:81], v[144:147], v[220:223], v[78:81]
	v_mfma_f32_16x16x32_bf16 v[74:77], v[158:161], v[220:223], v[74:77]
	v_mfma_f32_16x16x32_bf16 v[70:73], v[144:147], v[228:231], v[70:73]
	v_mfma_f32_16x16x32_bf16 v[66:69], v[158:161], v[228:231], v[66:69]
	s_setprio 0
	s_setprio 1
	v_mfma_f32_16x16x32_bf16 v[30:33], v[162:165], v[200:203], 0
	v_mfma_f32_16x16x32_bf16 v[26:29], v[174:177], v[200:203], 0
	v_mfma_f32_16x16x32_bf16 v[22:25], v[162:165], v[208:211], 0
	v_mfma_f32_16x16x32_bf16 v[18:21], v[174:177], v[208:211], 0
	v_mfma_f32_16x16x32_bf16 v[14:17], v[162:165], v[216:219], 0
	v_mfma_f32_16x16x32_bf16 v[10:13], v[174:177], v[216:219], 0
	v_mfma_f32_16x16x32_bf16 v[6:9], v[162:165], v[224:227], 0
	v_mfma_f32_16x16x32_bf16 v[2:5], v[174:177], v[224:227], 0
	v_mfma_f32_16x16x32_bf16 v[30:33], v[170:173], v[204:207], v[30:33]
	v_mfma_f32_16x16x32_bf16 v[26:29], v[178:181], v[204:207], v[26:29]
	v_mfma_f32_16x16x32_bf16 v[22:25], v[170:173], v[212:215], v[22:25]
	v_mfma_f32_16x16x32_bf16 v[18:21], v[178:181], v[212:215], v[18:21]
	v_mfma_f32_16x16x32_bf16 v[14:17], v[170:173], v[220:223], v[14:17]
	v_mfma_f32_16x16x32_bf16 v[10:13], v[178:181], v[220:223], v[10:13]
	v_mfma_f32_16x16x32_bf16 v[6:9], v[170:173], v[228:231], v[6:9]
	v_mfma_f32_16x16x32_bf16 v[2:5], v[178:181], v[228:231], v[2:5]
	s_setprio 0
	s_barrier
	s_add_i32 s50, 0, 0x18000
	s_add_i32 s51, 0, 0x1c000
	v_add_u32_e32 v158, s50, v167
	v_add_u32_e32 v178, s51, v167
	ds_read_b128 v[140:143], v158
	ds_read_b128 v[144:147], v158 offset:1024
	ds_read_b128 v[154:157], v158 offset:2048
	ds_read_b128 v[158:161], v158 offset:3072
	ds_read_b128 v[162:165], v178
	ds_read_b128 v[170:173], v178 offset:1024
	ds_read_b128 v[174:177], v178 offset:2048
	ds_read_b128 v[178:181], v178 offset:3072
	s_add_u32 s20, s20, 0x40000
	s_addc_u32 s21, s21, 0
	s_mov_b32 m0, s27
	v_lshl_add_u64 v[238:239], s[20:21], 0, v[134:135]
	ds_read_b128 v[200:203], v169 offset:32768
	ds_read_b128 v[204:207], v169 offset:33792
	ds_read_b128 v[208:211], v169 offset:34816
	ds_read_b128 v[212:215], v169 offset:35840
	ds_read_b128 v[216:219], v169 offset:36864
	ds_read_b128 v[220:223], v169 offset:37888
	ds_read_b128 v[224:227], v169 offset:38912
	ds_read_b128 v[228:231], v169 offset:39936
	global_load_lds_dwordx4 v[238:239], off
	v_lshl_add_u64 v[238:239], s[20:21], 0, v[132:133]
	s_mov_b32 m0, s28
	s_nop 0
	global_load_lds_dwordx4 v[238:239], off
	s_waitcnt vmcnt(8)
	s_waitcnt lgkmcnt(0)
	s_barrier
	s_setprio 1
	s_waitcnt lgkmcnt(0)
	v_mfma_f32_16x16x32_bf16 v[126:129], v[140:143], v[200:203], v[126:129]
	v_mfma_f32_16x16x32_bf16 v[122:125], v[154:157], v[200:203], v[122:125]
	v_mfma_f32_16x16x32_bf16 v[118:121], v[140:143], v[208:211], v[118:121]
	v_mfma_f32_16x16x32_bf16 v[114:117], v[154:157], v[208:211], v[114:117]
	v_mfma_f32_16x16x32_bf16 v[110:113], v[140:143], v[216:219], v[110:113]
	v_mfma_f32_16x16x32_bf16 v[106:109], v[154:157], v[216:219], v[106:109]
	v_mfma_f32_16x16x32_bf16 v[102:105], v[140:143], v[224:227], v[102:105]
	v_mfma_f32_16x16x32_bf16 v[98:101], v[154:157], v[224:227], v[98:101]
	v_mfma_f32_16x16x32_bf16 v[126:129], v[144:147], v[204:207], v[126:129]
	v_mfma_f32_16x16x32_bf16 v[122:125], v[158:161], v[204:207], v[122:125]
	v_mfma_f32_16x16x32_bf16 v[118:121], v[144:147], v[212:215], v[118:121]
	v_mfma_f32_16x16x32_bf16 v[114:117], v[158:161], v[212:215], v[114:117]
	v_mfma_f32_16x16x32_bf16 v[110:113], v[144:147], v[220:223], v[110:113]
	v_mfma_f32_16x16x32_bf16 v[106:109], v[158:161], v[220:223], v[106:109]
	v_mfma_f32_16x16x32_bf16 v[102:105], v[144:147], v[228:231], v[102:105]
	v_mfma_f32_16x16x32_bf16 v[98:101], v[158:161], v[228:231], v[98:101]
	s_setprio 0
	s_setprio 1
	v_mfma_f32_16x16x32_bf16 v[62:65], v[162:165], v[200:203], v[62:65]
	v_mfma_f32_16x16x32_bf16 v[58:61], v[174:177], v[200:203], v[58:61]
	v_mfma_f32_16x16x32_bf16 v[54:57], v[162:165], v[208:211], v[54:57]
	v_mfma_f32_16x16x32_bf16 v[50:53], v[174:177], v[208:211], v[50:53]
	v_mfma_f32_16x16x32_bf16 v[46:49], v[162:165], v[216:219], v[46:49]
	v_mfma_f32_16x16x32_bf16 v[42:45], v[174:177], v[216:219], v[42:45]
	v_mfma_f32_16x16x32_bf16 v[38:41], v[162:165], v[224:227], v[38:41]
	v_mfma_f32_16x16x32_bf16 v[34:37], v[174:177], v[224:227], v[34:37]
	v_mfma_f32_16x16x32_bf16 v[62:65], v[170:173], v[204:207], v[62:65]
	v_mfma_f32_16x16x32_bf16 v[58:61], v[178:181], v[204:207], v[58:61]
	v_mfma_f32_16x16x32_bf16 v[54:57], v[170:173], v[212:215], v[54:57]
	v_mfma_f32_16x16x32_bf16 v[50:53], v[178:181], v[212:215], v[50:53]
	v_mfma_f32_16x16x32_bf16 v[46:49], v[170:173], v[220:223], v[46:49]
	v_mfma_f32_16x16x32_bf16 v[42:45], v[178:181], v[220:223], v[42:45]
	v_mfma_f32_16x16x32_bf16 v[38:41], v[170:173], v[228:231], v[38:41]
	v_mfma_f32_16x16x32_bf16 v[34:37], v[178:181], v[228:231], v[34:37]
	s_setprio 0
	s_barrier
; #define PG8_STAGE(bufoff, gbase, voff) do { _Pragma("unroll") for (int _i = 0; _i < 2; ++_i) \
;         __builtin_amdgcn_global_load_lds((const unsigned*)((const char*)(gbase) + (voff)[_i]), (PG8_LAS unsigned*)(lds + (bufoff) + ldsw + _i * 8192), 16, 0, 0); } while (0)
; #define PG8_LDA(dst, b, h) do { _Pragma("unroll") for (int m = 0; m < 4; ++m) _Pragma("unroll") for (int k = 0; k < 2; ++k) dst[m][k] = *(const PG8_LAS bf16x8*)(lds + PG8_SA(b, h) + aoff + m * 2048 + k * 1024); } while (0)
; #define PG8_LDB(dst, b, h) do { _Pragma("unroll") for (int n = 0; n < 2; ++n) _Pragma("unroll") for (int k = 0; k < 2; ++k) dst[n][k] = *(const PG8_LAS bf16x8*)(lds + PG8_SB(b, h) + boff + n * 2048 + k * 1024); } while (0)
; #define PG8_MMA(ai, bj, At, Bt) do { __builtin_amdgcn_s_setprio(1); _Pragma("unroll") for (int m = 0; m < 4; ++m) _Pragma("unroll") for (int n = 0; n < 2; ++n) _Pragma("unroll") for (int k = 0; k < 2; ++k) \
;         acc[ai][bj][m][n] = __builtin_amdgcn_mfma_f32_16x16x32_bf16(Bt[n][k], At[m][k], acc[ai][bj][m][n], 0, 0, 0); __builtin_amdgcn_s_setprio(0); } while (0)
; #define PG8_WAIT_V(n) asm volatile("s_waitcnt vmcnt(" #n ")" ::: "memory")
; template <class Epi, class Sched, bool ALIGN_EPI = false, bool SP2 = false>
; __device__ __forceinline__ void gemm_phase(PG8_LAS unsigned char* lds, const Gemm g, const Sched& S, const Epi& E) {
;     ...
;             PG8_LDB(B0, 0, 0); PG8_LDB(B1, 0, 1); PG8_SCHED; PG8_LDA(At, 0, 0); PG8_STAGE(PG8_SA(1, 1), a1 + hstep, voffA);
;             PG8_WAIT_V(8); PG8_WAIT_L(0); PG8_BAR; PG8_MMA(0, 0, At, B0); PG8_MMA(0, 1, At, B1); PG8_BAR; PG8_SCHED;
;             PG8_LDA(At, 0, 1); PG8_STAGE(PG8_SB(0, 0), b2, voffB); PG8_STAGE(PG8_SB(0, 1), b2 + hstep, voffB); PG8_STAGE(PG8_SA(0, 0), a2, voffA);
;             PG8_WAIT_V(8); PG8_WAIT_L(0); PG8_BAR; PG8_MMA(1, 0, At, B0); PG8_MMA(1, 1, At, B1); PG8_BAR; PG8_SCHED;
;             PG8_LDB(B0, 1, 0); PG8_LDB(B1, 1, 1); PG8_SCHED; PG8_LDA(At, 1, 0); PG8_STAGE(PG8_SA(0, 1), a2 + hstep, voffA);
;             PG8_WAIT_V(8); PG8_WAIT_L(0); PG8_BAR; PG8_MMA(0, 0, At, B0); PG8_MMA(0, 1, At, B1); PG8_BAR; PG8_SCHED;
;             PG8_LDA(At, 1, 1); PG8_STAGE(PG8_SB(1, 0), b3, voffB); PG8_STAGE(PG8_SB(1, 1), b3 + hstep, voffB); PG8_STAGE(PG8_SA(1, 0), a3, voffA);
;             PG8_WAIT_V(8); PG8_WAIT_L(0); PG8_BAR; PG8_MMA(1, 0, At, B0); PG8_MMA(1, 1, At, B1); PG8_BAR; PG8_SCHED;
	s_add_i32 s20, s50, s24
	v_lshl_add_u64 v[148:149], v[148:149], 0, s[38:39]
	s_mov_b32 m0, s20
	ds_read_b128 v[200:203], v169 offset:49152
	ds_read_b128 v[204:207], v169 offset:50176
	ds_read_b128 v[208:211], v169 offset:51200
	ds_read_b128 v[212:215], v169 offset:52224
	ds_read_b128 v[216:219], v169 offset:53248
	ds_read_b128 v[220:223], v169 offset:54272
	ds_read_b128 v[224:227], v169 offset:55296
	ds_read_b128 v[228:231], v169 offset:56320
	global_load_lds_dwordx4 v[148:149], off
	s_add_i32 m0, s20, 0x2000
	s_add_u32 s18, s18, 0x40080
	v_lshl_add_u64 v[148:149], v[232:233], 0, s[38:39]
	s_addc_u32 s19, s19, 0
	s_add_i32 s20, s51, s24
	global_load_lds_dwordx4 v[148:149], off
	v_lshl_add_u64 v[148:149], s[18:19], 0, v[0:1]
	s_mov_b32 m0, s20
	s_nop 0
	global_load_lds_dwordx4 v[148:149], off
	v_lshl_add_u64 v[148:149], s[18:19], 0, v[130:131]
	s_add_i32 m0, s20, 0x2000
	s_nop 0
	global_load_lds_dwordx4 v[148:149], off
	v_lshl_add_u64 v[148:149], v[234:235], 0, s[38:39]
	s_mov_b32 m0, s31
	s_nop 0
	global_load_lds_dwordx4 v[148:149], off
	v_lshl_add_u64 v[148:149], v[236:237], 0, s[38:39]
	s_mov_b32 m0, s33
	s_nop 0
	global_load_lds_dwordx4 v[148:149], off
	s_waitcnt vmcnt(8)
	s_waitcnt lgkmcnt(0)
	s_barrier
	s_setprio 1
	s_waitcnt lgkmcnt(0)
	v_mfma_f32_16x16x32_bf16 v[94:97], v[140:143], v[200:203], v[94:97]
	v_mfma_f32_16x16x32_bf16 v[90:93], v[154:157], v[200:203], v[90:93]
	v_mfma_f32_16x16x32_bf16 v[86:89], v[140:143], v[208:211], v[86:89]
	v_mfma_f32_16x16x32_bf16 v[82:85], v[154:157], v[208:211], v[82:85]
	v_mfma_f32_16x16x32_bf16 v[78:81], v[140:143], v[216:219], v[78:81]
	v_mfma_f32_16x16x32_bf16 v[74:77], v[154:157], v[216:219], v[74:77]
	v_mfma_f32_16x16x32_bf16 v[70:73], v[140:143], v[224:227], v[70:73]
	v_mfma_f32_16x16x32_bf16 v[66:69], v[154:157], v[224:227], v[66:69]
	v_mfma_f32_16x16x32_bf16 v[94:97], v[144:147], v[204:207], v[94:97]
	v_mfma_f32_16x16x32_bf16 v[90:93], v[158:161], v[204:207], v[90:93]
	v_mfma_f32_16x16x32_bf16 v[86:89], v[144:147], v[212:215], v[86:89]
	v_mfma_f32_16x16x32_bf16 v[82:85], v[158:161], v[212:215], v[82:85]
	v_mfma_f32_16x16x32_bf16 v[78:81], v[144:147], v[220:223], v[78:81]
	v_mfma_f32_16x16x32_bf16 v[74:77], v[158:161], v[220:223], v[74:77]
	v_mfma_f32_16x16x32_bf16 v[70:73], v[144:147], v[228:231], v[70:73]
	v_mfma_f32_16x16x32_bf16 v[66:69], v[158:161], v[228:231], v[66:69]
	s_setprio 0
	s_setprio 1
	v_mfma_f32_16x16x32_bf16 v[30:33], v[162:165], v[200:203], v[30:33]
	v_mfma_f32_16x16x32_bf16 v[26:29], v[174:177], v[200:203], v[26:29]
	v_mfma_f32_16x16x32_bf16 v[22:25], v[162:165], v[208:211], v[22:25]
	v_mfma_f32_16x16x32_bf16 v[18:21], v[174:177], v[208:211], v[18:21]
	v_mfma_f32_16x16x32_bf16 v[14:17], v[162:165], v[216:219], v[14:17]
	v_mfma_f32_16x16x32_bf16 v[10:13], v[174:177], v[216:219], v[10:13]
	v_mfma_f32_16x16x32_bf16 v[6:9], v[162:165], v[224:227], v[6:9]
	v_mfma_f32_16x16x32_bf16 v[2:5], v[174:177], v[224:227], v[2:5]
	v_mfma_f32_16x16x32_bf16 v[30:33], v[170:173], v[204:207], v[30:33]
	v_mfma_f32_16x16x32_bf16 v[26:29], v[178:181], v[204:207], v[26:29]
	v_mfma_f32_16x16x32_bf16 v[22:25], v[170:173], v[212:215], v[22:25]
	v_mfma_f32_16x16x32_bf16 v[18:21], v[178:181], v[212:215], v[18:21]
	v_mfma_f32_16x16x32_bf16 v[14:17], v[170:173], v[220:223], v[14:17]
	v_mfma_f32_16x16x32_bf16 v[10:13], v[178:181], v[220:223], v[10:13]
	v_mfma_f32_16x16x32_bf16 v[6:9], v[170:173], v[228:231], v[6:9]
	v_mfma_f32_16x16x32_bf16 v[2:5], v[178:181], v[228:231], v[2:5]
	s_setprio 0
	s_barrier
	s_add_i32 s49, s49, 2
	s_add_u32 s16, s16, 0x100
	s_addc_u32 s17, s17, 0
	s_add_u32 s47, s47, 0x100
	s_addc_u32 s48, s48, 0
.LBB0_1090:
	s_add_u32 s18, s16, 0xfffc0080
	s_addc_u32 s19, s17, -1
	s_add_i32 s50, 0, 0x10000
	s_cmp_eq_u32 s49, 12
	s_cselect_b32 s21, s11, s19
	s_cselect_b32 s20, s45, s18
	v_add_u32_e32 v148, s50, v167
	s_cselect_b32 s19, s9, s48
	s_cselect_b32 s18, s46, s47
	s_add_i32 s52, 0, 0x14000
	ds_read_b128 v[140:143], v148
	ds_read_b128 v[144:147], v148 offset:1024
	ds_read_b128 v[154:157], v148 offset:2048
	ds_read_b128 v[158:161], v148 offset:3072
	v_add_u32_e32 v148, s52, v167
	ds_read_b128 v[162:165], v148
	ds_read_b128 v[170:173], v148 offset:1024
	ds_read_b128 v[174:177], v148 offset:2048
	ds_read_b128 v[178:181], v148 offset:3072
	v_lshl_add_u64 v[148:149], s[16:17], 0, v[136:137]
	s_add_i32 m0, s25, 0xc000
	ds_read_b128 v[200:203], v169
	ds_read_b128 v[204:207], v169 offset:1024
	ds_read_b128 v[208:211], v169 offset:2048
	ds_read_b128 v[212:215], v169 offset:3072
	ds_read_b128 v[216:219], v169 offset:4096
	ds_read_b128 v[220:223], v169 offset:5120
	ds_read_b128 v[224:227], v169 offset:6144
	ds_read_b128 v[228:231], v169 offset:7168
	global_load_lds_dwordx4 v[148:149], off
	v_lshl_add_u64 v[148:149], s[16:17], 0, v[138:139]
	s_add_i32 m0, s25, 0xe000
	s_nop 0
	global_load_lds_dwordx4 v[148:149], off
	s_waitcnt vmcnt(8)
	s_waitcnt lgkmcnt(0)
	s_barrier
; #define PG8_STAGE(bufoff, gbase, voff) do { _Pragma("unroll") for (int _i = 0; _i < 2; ++_i) \
;         __builtin_amdgcn_global_load_lds((const unsigned*)((const char*)(gbase) + (voff)[_i]), (PG8_LAS unsigned*)(lds + (bufoff) + ldsw + _i * 8192), 16, 0, 0); } while (0)
; #define PG8_LDA(dst, b, h) do { _Pragma("unroll") for (int m = 0; m < 4; ++m) _Pragma("unroll") for (int k = 0; k < 2; ++k) dst[m][k] = *(const PG8_LAS bf16x8*)(lds + PG8_SA(b, h) + aoff + m * 2048 + k * 1024); } while (0)
; #define PG8_MMA(ai, bj, At, Bt) do { __builtin_amdgcn_s_setprio(1); _Pragma("unroll") for (int m = 0; m < 4; ++m) _Pragma("unroll") for (int n = 0; n < 2; ++n) _Pragma("unroll") for (int k = 0; k < 2; ++k) \
;         acc[ai][bj][m][n] = __builtin_amdgcn_mfma_f32_16x16x32_bf16(Bt[n][k], At[m][k], acc[ai][bj][m][n], 0, 0, 0); __builtin_amdgcn_s_setprio(0); } while (0)
; #define PG8_WAIT_V(n) asm volatile("s_waitcnt vmcnt(" #n ")" ::: "memory")
; #define PG8_WAIT_L(n) asm volatile("s_waitcnt lgkmcnt(" #n ")" ::: "memory")
; #define PG8_BAR __builtin_amdgcn_s_barrier()
; #define PG8_SCHED __builtin_amdgcn_sched_barrier(0)
; template <class Epi, class Sched, bool ALIGN_EPI = false, bool SP2 = false>
; __device__ __forceinline__ void gemm_phase(PG8_LAS unsigned char* lds, const Gemm g, const Sched& S, const Epi& E) {
;     ...
;             PG8_WAIT_V(8); PG8_WAIT_L(0); PG8_BAR; PG8_MMA(0, 0, At, B0); PG8_MMA(0, 1, At, B1); PG8_BAR; PG8_SCHED;
;             PG8_LDA(At, 0, 1); PG8_STAGE(PG8_SB(0, 0), b2, voffB); PG8_STAGE(PG8_SB(0, 1), b2 + hstep, voffB); PG8_STAGE(PG8_SA(0, 0), a2, voffA);
;             PG8_WAIT_V(8); PG8_WAIT_L(0); PG8_BAR; PG8_MMA(1, 0, At, B0); PG8_MMA(1, 1, At, B1); PG8_BAR; PG8_SCHED;
	s_setprio 1
	s_waitcnt lgkmcnt(0)
	v_mfma_f32_16x16x32_bf16 v[126:129], v[140:143], v[200:203], v[126:129]
	v_mfma_f32_16x16x32_bf16 v[122:125], v[154:157], v[200:203], v[122:125]
	v_mfma_f32_16x16x32_bf16 v[118:121], v[140:143], v[208:211], v[118:121]
	v_mfma_f32_16x16x32_bf16 v[114:117], v[154:157], v[208:211], v[114:117]
	v_mfma_f32_16x16x32_bf16 v[110:113], v[140:143], v[216:219], v[110:113]
	v_mfma_f32_16x16x32_bf16 v[106:109], v[154:157], v[216:219], v[106:109]
	v_mfma_f32_16x16x32_bf16 v[102:105], v[140:143], v[224:227], v[102:105]
	v_mfma_f32_16x16x32_bf16 v[98:101], v[154:157], v[224:227], v[98:101]
	v_mfma_f32_16x16x32_bf16 v[126:129], v[144:147], v[204:207], v[126:129]
	v_mfma_f32_16x16x32_bf16 v[122:125], v[158:161], v[204:207], v[122:125]
	v_mfma_f32_16x16x32_bf16 v[118:121], v[144:147], v[212:215], v[118:121]
	v_mfma_f32_16x16x32_bf16 v[114:117], v[158:161], v[212:215], v[114:117]
	v_mfma_f32_16x16x32_bf16 v[110:113], v[144:147], v[220:223], v[110:113]
	v_mfma_f32_16x16x32_bf16 v[106:109], v[158:161], v[220:223], v[106:109]
	v_mfma_f32_16x16x32_bf16 v[102:105], v[144:147], v[228:231], v[102:105]
	v_mfma_f32_16x16x32_bf16 v[98:101], v[158:161], v[228:231], v[98:101]
	s_setprio 0
	s_setprio 1
	v_mfma_f32_16x16x32_bf16 v[62:65], v[162:165], v[200:203], v[62:65]
	v_mfma_f32_16x16x32_bf16 v[58:61], v[174:177], v[200:203], v[58:61]
	v_mfma_f32_16x16x32_bf16 v[54:57], v[162:165], v[208:211], v[54:57]
	v_mfma_f32_16x16x32_bf16 v[50:53], v[174:177], v[208:211], v[50:53]
	v_mfma_f32_16x16x32_bf16 v[46:49], v[162:165], v[216:219], v[46:49]
	v_mfma_f32_16x16x32_bf16 v[42:45], v[174:177], v[216:219], v[42:45]
	v_mfma_f32_16x16x32_bf16 v[38:41], v[162:165], v[224:227], v[38:41]
	v_mfma_f32_16x16x32_bf16 v[34:37], v[174:177], v[224:227], v[34:37]
	v_mfma_f32_16x16x32_bf16 v[62:65], v[170:173], v[204:207], v[62:65]
	v_mfma_f32_16x16x32_bf16 v[58:61], v[178:181], v[204:207], v[58:61]
	v_mfma_f32_16x16x32_bf16 v[54:57], v[170:173], v[212:215], v[54:57]
	v_mfma_f32_16x16x32_bf16 v[50:53], v[178:181], v[212:215], v[50:53]
	v_mfma_f32_16x16x32_bf16 v[46:49], v[170:173], v[220:223], v[46:49]
	v_mfma_f32_16x16x32_bf16 v[42:45], v[178:181], v[220:223], v[42:45]
	v_mfma_f32_16x16x32_bf16 v[38:41], v[170:173], v[228:231], v[38:41]
	v_mfma_f32_16x16x32_bf16 v[34:37], v[178:181], v[228:231], v[34:37]
	s_setprio 0
	s_barrier
	s_add_i32 s50, s50, s24
	v_lshl_add_u64 v[148:149], s[18:19], 0, v[0:1]
	s_mov_b32 m0, s50
	ds_read_b128 v[200:203], v169 offset:16384
	ds_read_b128 v[204:207], v169 offset:17408
	ds_read_b128 v[208:211], v169 offset:18432
	ds_read_b128 v[212:215], v169 offset:19456
	ds_read_b128 v[216:219], v169 offset:20480
	ds_read_b128 v[220:223], v169 offset:21504
	ds_read_b128 v[224:227], v169 offset:22528
	ds_read_b128 v[228:231], v169 offset:23552
	global_load_lds_dwordx4 v[148:149], off
	s_add_i32 m0, s50, 0x2000
	s_add_u32 s50, s18, 0x40000
	v_lshl_add_u64 v[232:233], s[18:19], 0, v[130:131]
	s_addc_u32 s51, s19, 0
	s_add_i32 s52, s52, s24
	global_load_lds_dwordx4 v[232:233], off
	v_lshl_add_u64 v[234:235], s[50:51], 0, v[0:1]
	s_mov_b32 m0, s52
	v_lshl_add_u64 v[236:237], s[20:21], 0, v[132:133]
	global_load_lds_dwordx4 v[234:235], off
	v_lshl_add_u64 v[234:235], s[50:51], 0, v[130:131]
	s_add_i32 m0, s52, 0x2000
	s_nop 0
	global_load_lds_dwordx4 v[234:235], off
	v_lshl_add_u64 v[234:235], s[20:21], 0, v[134:135]
	s_mov_b32 m0, s25
	s_nop 0
	global_load_lds_dwordx4 v[234:235], off
	s_mov_b32 m0, s26
	s_nop 0
	global_load_lds_dwordx4 v[236:237], off
	s_waitcnt vmcnt(8)
	s_waitcnt lgkmcnt(0)
	s_barrier
	s_setprio 1
	s_waitcnt lgkmcnt(0)
	v_mfma_f32_16x16x32_bf16 v[94:97], v[140:143], v[200:203], v[94:97]
	v_mfma_f32_16x16x32_bf16 v[90:93], v[154:157], v[200:203], v[90:93]
	v_mfma_f32_16x16x32_bf16 v[86:89], v[140:143], v[208:211], v[86:89]
	v_mfma_f32_16x16x32_bf16 v[82:85], v[154:157], v[208:211], v[82:85]
	v_mfma_f32_16x16x32_bf16 v[78:81], v[140:143], v[216:219], v[78:81]
	v_mfma_f32_16x16x32_bf16 v[74:77], v[154:157], v[216:219], v[74:77]
	v_mfma_f32_16x16x32_bf16 v[70:73], v[140:143], v[224:227], v[70:73]
	v_mfma_f32_16x16x32_bf16 v[66:69], v[154:157], v[224:227], v[66:69]
	v_mfma_f32_16x16x32_bf16 v[94:97], v[144:147], v[204:207], v[94:97]
	v_mfma_f32_16x16x32_bf16 v[90:93], v[158:161], v[204:207], v[90:93]
	v_mfma_f32_16x16x32_bf16 v[86:89], v[144:147], v[212:215], v[86:89]
	v_mfma_f32_16x16x32_bf16 v[82:85], v[158:161], v[212:215], v[82:85]
	v_mfma_f32_16x16x32_bf16 v[78:81], v[144:147], v[220:223], v[78:81]
	v_mfma_f32_16x16x32_bf16 v[74:77], v[158:161], v[220:223], v[74:77]
	v_mfma_f32_16x16x32_bf16 v[70:73], v[144:147], v[228:231], v[70:73]
	v_mfma_f32_16x16x32_bf16 v[66:69], v[158:161], v[228:231], v[66:69]
	s_setprio 0
	s_setprio 1
	v_mfma_f32_16x16x32_bf16 v[30:33], v[162:165], v[200:203], v[30:33]
	v_mfma_f32_16x16x32_bf16 v[26:29], v[174:177], v[200:203], v[26:29]
	v_mfma_f32_16x16x32_bf16 v[22:25], v[162:165], v[208:211], v[22:25]
	v_mfma_f32_16x16x32_bf16 v[18:21], v[174:177], v[208:211], v[18:21]
	v_mfma_f32_16x16x32_bf16 v[14:17], v[162:165], v[216:219], v[14:17]
	v_mfma_f32_16x16x32_bf16 v[10:13], v[174:177], v[216:219], v[10:13]
	v_mfma_f32_16x16x32_bf16 v[6:9], v[162:165], v[224:227], v[6:9]
	v_mfma_f32_16x16x32_bf16 v[2:5], v[174:177], v[224:227], v[2:5]
	v_mfma_f32_16x16x32_bf16 v[30:33], v[170:173], v[204:207], v[30:33]
	v_mfma_f32_16x16x32_bf16 v[26:29], v[178:181], v[204:207], v[26:29]
	v_mfma_f32_16x16x32_bf16 v[22:25], v[170:173], v[212:215], v[22:25]
	v_mfma_f32_16x16x32_bf16 v[18:21], v[178:181], v[212:215], v[18:21]
	v_mfma_f32_16x16x32_bf16 v[14:17], v[170:173], v[220:223], v[14:17]
	v_mfma_f32_16x16x32_bf16 v[10:13], v[178:181], v[220:223], v[10:13]
	v_mfma_f32_16x16x32_bf16 v[6:9], v[170:173], v[228:231], v[6:9]
	v_mfma_f32_16x16x32_bf16 v[2:5], v[178:181], v[228:231], v[2:5]
	s_setprio 0
	s_barrier
; #define PG8_STAGE(bufoff, gbase, voff) do { _Pragma("unroll") for (int _i = 0; _i < 2; ++_i) \
;         __builtin_amdgcn_global_load_lds((const unsigned*)((const char*)(gbase) + (voff)[_i]), (PG8_LAS unsigned*)(lds + (bufoff) + ldsw + _i * 8192), 16, 0, 0); } while (0)
; #define PG8_LDA(dst, b, h) do { _Pragma("unroll") for (int m = 0; m < 4; ++m) _Pragma("unroll") for (int k = 0; k < 2; ++k) dst[m][k] = *(const PG8_LAS bf16x8*)(lds + PG8_SA(b, h) + aoff + m * 2048 + k * 1024); } while (0)
; #define PG8_LDB(dst, b, h) do { _Pragma("unroll") for (int n = 0; n < 2; ++n) _Pragma("unroll") for (int k = 0; k < 2; ++k) dst[n][k] = *(const PG8_LAS bf16x8*)(lds + PG8_SB(b, h) + boff + n * 2048 + k * 1024); } while (0)
; #define PG8_MMA(ai, bj, At, Bt) do { __builtin_amdgcn_s_setprio(1); _Pragma("unroll") for (int m = 0; m < 4; ++m) _Pragma("unroll") for (int n = 0; n < 2; ++n) _Pragma("unroll") for (int k = 0; k < 2; ++k) \
;         acc[ai][bj][m][n] = __builtin_amdgcn_mfma_f32_16x16x32_bf16(Bt[n][k], At[m][k], acc[ai][bj][m][n], 0, 0, 0); __builtin_amdgcn_s_setprio(0); } while (0)
; #define PG8_WAIT_V(n) asm volatile("s_waitcnt vmcnt(" #n ")" ::: "memory")
; #define PG8_WAIT_L(n) asm volatile("s_waitcnt lgkmcnt(" #n ")" ::: "memory")
; #define PG8_BAR __builtin_amdgcn_s_barrier()
; #define PG8_SCHED __builtin_amdgcn_sched_barrier(0)
; template <class Epi, class Sched, bool ALIGN_EPI = false, bool SP2 = false>
; __device__ __forceinline__ void gemm_phase(PG8_LAS unsigned char* lds, const Gemm g, const Sched& S, const Epi& E) {
;     ...
;             PG8_LDB(B0, 1, 0); PG8_LDB(B1, 1, 1); PG8_SCHED; PG8_LDA(At, 1, 0); PG8_STAGE(PG8_SA(0, 1), a2 + hstep, voffA);
;             PG8_WAIT_V(8); PG8_WAIT_L(0); PG8_BAR; PG8_MMA(0, 0, At, B0); PG8_MMA(0, 1, At, B1); PG8_BAR; PG8_SCHED;
	s_add_i32 s50, 0, 0x18000
	s_add_i32 s51, 0, 0x1c000
	v_add_u32_e32 v158, s50, v167
	v_add_u32_e32 v178, s51, v167
	ds_read_b128 v[140:143], v158
	ds_read_b128 v[144:147], v158 offset:1024
	ds_read_b128 v[154:157], v158 offset:2048
	ds_read_b128 v[158:161], v158 offset:3072
	ds_read_b128 v[162:165], v178
	ds_read_b128 v[170:173], v178 offset:1024
	ds_read_b128 v[174:177], v178 offset:2048
	ds_read_b128 v[178:181], v178 offset:3072
	s_add_u32 s20, s20, 0x40000
	s_addc_u32 s21, s21, 0
	s_mov_b32 m0, s27
	v_lshl_add_u64 v[238:239], s[20:21], 0, v[134:135]
	ds_read_b128 v[200:203], v169 offset:32768
	ds_read_b128 v[204:207], v169 offset:33792
	ds_read_b128 v[208:211], v169 offset:34816
	ds_read_b128 v[212:215], v169 offset:35840
	ds_read_b128 v[216:219], v169 offset:36864
	ds_read_b128 v[220:223], v169 offset:37888
	ds_read_b128 v[224:227], v169 offset:38912
	ds_read_b128 v[228:231], v169 offset:39936
	global_load_lds_dwordx4 v[238:239], off
	v_lshl_add_u64 v[238:239], s[20:21], 0, v[132:133]
	s_mov_b32 m0, s28
	s_nop 0
	global_load_lds_dwordx4 v[238:239], off
	s_waitcnt vmcnt(8)
	s_waitcnt lgkmcnt(0)
	s_barrier
	s_setprio 1
	s_waitcnt lgkmcnt(0)
	v_mfma_f32_16x16x32_bf16 v[126:129], v[140:143], v[200:203], v[126:129]
	v_mfma_f32_16x16x32_bf16 v[122:125], v[154:157], v[200:203], v[122:125]
	v_mfma_f32_16x16x32_bf16 v[118:121], v[140:143], v[208:211], v[118:121]
	v_mfma_f32_16x16x32_bf16 v[114:117], v[154:157], v[208:211], v[114:117]
	v_mfma_f32_16x16x32_bf16 v[110:113], v[140:143], v[216:219], v[110:113]
	v_mfma_f32_16x16x32_bf16 v[106:109], v[154:157], v[216:219], v[106:109]
	v_mfma_f32_16x16x32_bf16 v[102:105], v[140:143], v[224:227], v[102:105]
	v_mfma_f32_16x16x32_bf16 v[98:101], v[154:157], v[224:227], v[98:101]
	v_mfma_f32_16x16x32_bf16 v[126:129], v[144:147], v[204:207], v[126:129]
	v_mfma_f32_16x16x32_bf16 v[122:125], v[158:161], v[204:207], v[122:125]
	v_mfma_f32_16x16x32_bf16 v[118:121], v[144:147], v[212:215], v[118:121]
	v_mfma_f32_16x16x32_bf16 v[114:117], v[158:161], v[212:215], v[114:117]
	v_mfma_f32_16x16x32_bf16 v[110:113], v[144:147], v[220:223], v[110:113]
	v_mfma_f32_16x16x32_bf16 v[106:109], v[158:161], v[220:223], v[106:109]
	v_mfma_f32_16x16x32_bf16 v[102:105], v[144:147], v[228:231], v[102:105]
	v_mfma_f32_16x16x32_bf16 v[98:101], v[158:161], v[228:231], v[98:101]
	s_setprio 0
	s_setprio 1
	v_mfma_f32_16x16x32_bf16 v[62:65], v[162:165], v[200:203], v[62:65]
	v_mfma_f32_16x16x32_bf16 v[58:61], v[174:177], v[200:203], v[58:61]
	v_mfma_f32_16x16x32_bf16 v[54:57], v[162:165], v[208:211], v[54:57]
	v_mfma_f32_16x16x32_bf16 v[50:53], v[174:177], v[208:211], v[50:53]
	v_mfma_f32_16x16x32_bf16 v[46:49], v[162:165], v[216:219], v[46:49]
	v_mfma_f32_16x16x32_bf16 v[42:45], v[174:177], v[216:219], v[42:45]
	v_mfma_f32_16x16x32_bf16 v[38:41], v[162:165], v[224:227], v[38:41]
	v_mfma_f32_16x16x32_bf16 v[34:37], v[174:177], v[224:227], v[34:37]
	v_mfma_f32_16x16x32_bf16 v[62:65], v[170:173], v[204:207], v[62:65]
	v_mfma_f32_16x16x32_bf16 v[58:61], v[178:181], v[204:207], v[58:61]
	v_mfma_f32_16x16x32_bf16 v[54:57], v[170:173], v[212:215], v[54:57]
	v_mfma_f32_16x16x32_bf16 v[50:53], v[178:181], v[212:215], v[50:53]
	v_mfma_f32_16x16x32_bf16 v[46:49], v[170:173], v[220:223], v[46:49]
	v_mfma_f32_16x16x32_bf16 v[42:45], v[178:181], v[220:223], v[42:45]
	v_mfma_f32_16x16x32_bf16 v[38:41], v[170:173], v[228:231], v[38:41]
	v_mfma_f32_16x16x32_bf16 v[34:37], v[178:181], v[228:231], v[34:37]
	s_setprio 0
	s_barrier
; #define PG8_STAGE(bufoff, gbase, voff) do { _Pragma("unroll") for (int _i = 0; _i < 2; ++_i) \
;         __builtin_amdgcn_global_load_lds((const unsigned*)((const char*)(gbase) + (voff)[_i]), (PG8_LAS unsigned*)(lds + (bufoff) + ldsw + _i * 8192), 16, 0, 0); } while (0)
; #define PG8_LDA(dst, b, h) do { _Pragma("unroll") for (int m = 0; m < 4; ++m) _Pragma("unroll") for (int k = 0; k < 2; ++k) dst[m][k] = *(const PG8_LAS bf16x8*)(lds + PG8_SA(b, h) + aoff + m * 2048 + k * 1024); } while (0)
; #define PG8_MMA(ai, bj, At, Bt) do { __builtin_amdgcn_s_setprio(1); _Pragma("unroll") for (int m = 0; m < 4; ++m) _Pragma("unroll") for (int n = 0; n < 2; ++n) _Pragma("unroll") for (int k = 0; k < 2; ++k) \
;         acc[ai][bj][m][n] = __builtin_amdgcn_mfma_f32_16x16x32_bf16(Bt[n][k], At[m][k], acc[ai][bj][m][n], 0, 0, 0); __builtin_amdgcn_s_setprio(0); } while (0)
; #define PG8_WAIT_V(n) asm volatile("s_waitcnt vmcnt(" #n ")" ::: "memory")
; #define PG8_WAIT_L(n) asm volatile("s_waitcnt lgkmcnt(" #n ")" ::: "memory")
; #define PG8_BAR __builtin_amdgcn_s_barrier()
; #define PG8_SCHED __builtin_amdgcn_sched_barrier(0)
; template <class Epi, class Sched, bool ALIGN_EPI = false, bool SP2 = false>
; __device__ __forceinline__ void gemm_phase(PG8_LAS unsigned char* lds, const Gemm g, const Sched& S, const Epi& E) {
;     ...
;             PG8_LDA(At, 1, 1); PG8_STAGE(PG8_SB(1, 0), b3, voffB); PG8_STAGE(PG8_SB(1, 1), b3 + hstep, voffB); PG8_STAGE(PG8_SA(1, 0), a3, voffA);
;             PG8_WAIT_V(8); PG8_WAIT_L(0); PG8_BAR; PG8_MMA(1, 0, At, B0); PG8_MMA(1, 1, At, B1); PG8_BAR; PG8_SCHED;
;     ...
;         if constexpr (ALIGN_EPI) { if (wr == 0) PG8_BAR; }
	s_add_i32 s20, s50, s24
	v_lshl_add_u64 v[148:149], v[148:149], 0, s[38:39]
	s_mov_b32 m0, s20
	ds_read_b128 v[200:203], v169 offset:49152
	ds_read_b128 v[204:207], v169 offset:50176
	ds_read_b128 v[208:211], v169 offset:51200
	ds_read_b128 v[212:215], v169 offset:52224
	ds_read_b128 v[216:219], v169 offset:53248
	ds_read_b128 v[220:223], v169 offset:54272
	ds_read_b128 v[224:227], v169 offset:55296
	ds_read_b128 v[228:231], v169 offset:56320
	global_load_lds_dwordx4 v[148:149], off
	s_add_i32 m0, s20, 0x2000
	s_add_u32 s18, s18, 0x40080
	v_lshl_add_u64 v[148:149], v[232:233], 0, s[38:39]
	s_addc_u32 s19, s19, 0
	s_add_i32 s20, s51, s24
	global_load_lds_dwordx4 v[148:149], off
	v_lshl_add_u64 v[148:149], s[18:19], 0, v[0:1]
	s_mov_b32 m0, s20
	s_nop 0
	global_load_lds_dwordx4 v[148:149], off
	v_lshl_add_u64 v[148:149], s[18:19], 0, v[130:131]
	s_add_i32 m0, s20, 0x2000
	s_nop 0
	global_load_lds_dwordx4 v[148:149], off
	v_lshl_add_u64 v[148:149], v[234:235], 0, s[38:39]
	s_mov_b32 m0, s31
	s_nop 0
	global_load_lds_dwordx4 v[148:149], off
	v_lshl_add_u64 v[148:149], v[236:237], 0, s[38:39]
	s_mov_b32 m0, s33
	s_nop 0
	global_load_lds_dwordx4 v[148:149], off
	s_waitcnt vmcnt(8)
	s_waitcnt lgkmcnt(0)
	s_barrier
	s_setprio 1
	s_waitcnt lgkmcnt(0)
	v_mfma_f32_16x16x32_bf16 v[94:97], v[140:143], v[200:203], v[94:97]
	v_mfma_f32_16x16x32_bf16 v[90:93], v[154:157], v[200:203], v[90:93]
	v_mfma_f32_16x16x32_bf16 v[86:89], v[140:143], v[208:211], v[86:89]
	v_mfma_f32_16x16x32_bf16 v[82:85], v[154:157], v[208:211], v[82:85]
	v_mfma_f32_16x16x32_bf16 v[78:81], v[140:143], v[216:219], v[78:81]
	v_mfma_f32_16x16x32_bf16 v[74:77], v[154:157], v[216:219], v[74:77]
	v_mfma_f32_16x16x32_bf16 v[70:73], v[140:143], v[224:227], v[70:73]
	v_mfma_f32_16x16x32_bf16 v[66:69], v[154:157], v[224:227], v[66:69]
	v_mfma_f32_16x16x32_bf16 v[94:97], v[144:147], v[204:207], v[94:97]
	v_mfma_f32_16x16x32_bf16 v[90:93], v[158:161], v[204:207], v[90:93]
	v_mfma_f32_16x16x32_bf16 v[86:89], v[144:147], v[212:215], v[86:89]
	v_mfma_f32_16x16x32_bf16 v[82:85], v[158:161], v[212:215], v[82:85]
	v_mfma_f32_16x16x32_bf16 v[78:81], v[144:147], v[220:223], v[78:81]
	v_mfma_f32_16x16x32_bf16 v[74:77], v[158:161], v[220:223], v[74:77]
	v_mfma_f32_16x16x32_bf16 v[70:73], v[144:147], v[228:231], v[70:73]
	v_mfma_f32_16x16x32_bf16 v[66:69], v[158:161], v[228:231], v[66:69]
	s_setprio 0
	s_setprio 1
	v_mfma_f32_16x16x32_bf16 v[30:33], v[162:165], v[200:203], v[30:33]
	v_mfma_f32_16x16x32_bf16 v[26:29], v[174:177], v[200:203], v[26:29]
	v_mfma_f32_16x16x32_bf16 v[22:25], v[162:165], v[208:211], v[22:25]
	v_mfma_f32_16x16x32_bf16 v[18:21], v[174:177], v[208:211], v[18:21]
	v_mfma_f32_16x16x32_bf16 v[14:17], v[162:165], v[216:219], v[14:17]
	v_mfma_f32_16x16x32_bf16 v[10:13], v[174:177], v[216:219], v[10:13]
	v_mfma_f32_16x16x32_bf16 v[6:9], v[162:165], v[224:227], v[6:9]
	v_mfma_f32_16x16x32_bf16 v[2:5], v[174:177], v[224:227], v[2:5]
	v_mfma_f32_16x16x32_bf16 v[30:33], v[170:173], v[204:207], v[30:33]
	v_mfma_f32_16x16x32_bf16 v[26:29], v[178:181], v[204:207], v[26:29]
	v_mfma_f32_16x16x32_bf16 v[22:25], v[170:173], v[212:215], v[22:25]
	v_mfma_f32_16x16x32_bf16 v[18:21], v[178:181], v[212:215], v[18:21]
	v_mfma_f32_16x16x32_bf16 v[14:17], v[170:173], v[220:223], v[14:17]
	v_mfma_f32_16x16x32_bf16 v[10:13], v[178:181], v[220:223], v[10:13]
	v_mfma_f32_16x16x32_bf16 v[6:9], v[170:173], v[228:231], v[6:9]
	v_mfma_f32_16x16x32_bf16 v[2:5], v[178:181], v[228:231], v[2:5]
	s_setprio 0
	s_cmp_lg_u32 s49, 12
	s_cbranch_scc1 .Llb_1090
	s_and_b64 vcc, exec, s[6:7]
	s_cbranch_vccz .Lnb_1090

; #define PG8_BAR __builtin_amdgcn_s_barrier()
; template <class Epi, class Sched, bool ALIGN_EPI = false, bool SP2 = false>
; __device__ __forceinline__ void gemm_phase(PG8_LAS unsigned char* lds, const Gemm g, const Sched& S, const Epi& E) {
;     ...
;         for (int t = 0; t < nt; t += 2) {
;     ...
;         if constexpr (ALIGN_EPI) { if (wr == 0) PG8_BAR; }
;         if constexpr (!Epi::AFTER_DRAIN) { E(acc, cur, wr, wc, fr, fq); S.done(cur); }
;         if (!has_next) break;
.Lnb_1090:
	s_add_i32 s49, s49, 2
	s_add_u32 s16, s16, 0x100
	s_addc_u32 s17, s17, 0
	s_add_u32 s47, s47, 0x100
	s_addc_u32 s48, s48, 0
	s_cmp_gt_u32 s49, 13
	s_cbranch_scc0 .LBB0_1090
	s_and_b64 vcc, exec, s[6:7]
	s_cbranch_vccz .LBB0_1093

; #define PG8_BAR __builtin_amdgcn_s_barrier()
; template <class Epi, class Sched, bool ALIGN_EPI = false, bool SP2 = false>
; __device__ __forceinline__ void gemm_phase(PG8_LAS unsigned char* lds, const Gemm g, const Sched& S, const Epi& E) {
;     ...
;         if (!has_next) break;
;     ...
;         if constexpr (ALIGN_EPI) { if (wr == 1) PG8_BAR; }
.Lres_b_tail:
	s_cbranch_vccnz .LBB0_1082
	s_andn2_b64 vcc, exec, s[0:1]
	s_cbranch_vccnz .LBB0_1081
	s_branch .LBB0_1081
